# scan: the y flush (round + global store) of chunk n is deferred behind the LDS prologue reads of chunk n+1; only the barrier and the LDS read stay at the chunk boundary
# baseline (speedup 1.0000x reference)
; #define SC_GLOAD(ci_) { rg0 = SC_G1(ci_, 0); rg1 = SC_G1(ci_, 1); rg2 = SC_G1(ci_, 2); }
; #define SC_LSTORE(st_) { SC_S1(st_, 0, rg0) SC_S1(st_, 1, rg1) SC_S1(st_, 2, rg2) }
; __device__ __forceinline__ void rwkv_scan_unit(const Params& p, int unit, char* smem) {
;     ...
;     __syncthreads();
;     SC_GLOAD(0)
;     SC_LSTORE(0)
;     __syncthreads();
;     for (int ci = 0; ci < NCH; ++ci) {
;         const int st = (ci & 1) * STG;
;         if (ci + 1 < NCH) { SC_GLOAD(ci + 1) }
.LBB0_380:
	global_load_dword v39, v[152:153], off
	v_add_u32_e32 v87, 16, v87
	v_add_u32_e32 v85, 16, v85
	v_add_u32_e32 v83, 16, v83
	v_add_u32_e32 v88, -16, v88
	v_add_u32_e32 v86, -16, v86
	v_add_u32_e32 v84, -16, v84
	v_add_u32_e32 v142, s55, v87
	v_cmp_lt_i32_e32 vcc, s2, v142
	s_nop 1
	v_cndmask_b32_e32 v143, v196, v197, vcc
	v_add_u32_e32 v143, v143, v88
	v_cndmask_b32_e64 v142, v143, v142, s[44:45]
	v_ashrrev_i32_e32 v143, 31, v142
	v_lshl_add_u64 v[142:143], v[142:143], 0, s[88:89]
	v_lshlrev_b64 v[142:143], 9, v[142:143]
	v_lshl_add_u64 v[140:141], v[152:153], 0, v[142:143]
	global_load_dwordx4 v[140:143], v[140:141], off
	v_add_u32_e32 v146, s55, v85
	v_cmp_lt_i32_e32 vcc, s2, v146
	s_nop 1
	v_cndmask_b32_e32 v147, v196, v197, vcc
	v_add_u32_e32 v147, v147, v86
	v_cndmask_b32_e64 v146, v147, v146, s[44:45]
	v_ashrrev_i32_e32 v147, 31, v146
	v_lshl_add_u64 v[146:147], v[146:147], 0, s[88:89]
	v_lshlrev_b64 v[146:147], 9, v[146:147]
	v_lshl_add_u64 v[144:145], v[154:155], 0, v[146:147]
	global_load_dwordx4 v[144:147], v[144:145], off
	v_add_u32_e32 v150, s55, v83
	v_cmp_lt_i32_e32 vcc, s2, v150
	s_nop 1
	v_cndmask_b32_e32 v151, v196, v197, vcc
	v_add_u32_e32 v151, v151, v84
	v_cndmask_b32_e64 v150, v151, v150, s[44:45]
	v_ashrrev_i32_e32 v151, 31, v150
	v_lshl_add_u64 v[150:151], v[150:151], 0, s[88:89]
	v_lshlrev_b64 v[150:151], 9, v[150:151]
	v_lshl_add_u64 v[148:149], v[156:157], 0, v[150:151]
	global_load_dwordx4 v[148:151], v[148:149], off
	global_load_dword v39, v[152:153], off
	v_add_u32_e32 v87, 16, v87
	v_add_u32_e32 v85, 16, v85
	v_add_u32_e32 v83, 16, v83
	v_add_u32_e32 v88, -16, v88
	v_add_u32_e32 v86, -16, v86
	v_add_u32_e32 v84, -16, v84
	v_add_u32_e32 v126, s55, v87
	v_cmp_lt_i32_e32 vcc, s2, v126
	s_nop 1
	v_cndmask_b32_e32 v127, v196, v197, vcc
	v_add_u32_e32 v127, v127, v88
	v_cndmask_b32_e64 v126, v127, v126, s[44:45]
	v_ashrrev_i32_e32 v127, 31, v126
	v_lshl_add_u64 v[126:127], v[126:127], 0, s[88:89]
	v_lshlrev_b64 v[126:127], 9, v[126:127]
	v_lshl_add_u64 v[124:125], v[152:153], 0, v[126:127]
	global_load_dwordx4 v[124:127], v[124:125], off
	v_add_u32_e32 v130, s55, v85
	v_cmp_lt_i32_e32 vcc, s2, v130
	s_nop 1
	v_cndmask_b32_e32 v131, v196, v197, vcc
	v_add_u32_e32 v131, v131, v86
	v_cndmask_b32_e64 v130, v131, v130, s[44:45]
	v_ashrrev_i32_e32 v131, 31, v130
	v_lshl_add_u64 v[130:131], v[130:131], 0, s[88:89]
	v_lshlrev_b64 v[130:131], 9, v[130:131]
	v_lshl_add_u64 v[128:129], v[154:155], 0, v[130:131]
	global_load_dwordx4 v[128:131], v[128:129], off
	v_add_u32_e32 v134, s55, v83
	v_cmp_lt_i32_e32 vcc, s2, v134
	s_nop 1
	v_cndmask_b32_e32 v135, v196, v197, vcc
	v_add_u32_e32 v135, v135, v84
	v_cndmask_b32_e64 v134, v135, v134, s[44:45]
	v_ashrrev_i32_e32 v135, 31, v134
	v_lshl_add_u64 v[134:135], v[134:135], 0, s[88:89]
	v_lshlrev_b64 v[134:135], 9, v[134:135]
	v_lshl_add_u64 v[132:133], v[156:157], 0, v[134:135]
	global_load_dwordx4 v[132:135], v[132:133], off
	global_load_dword v39, v[152:153], off
	v_add_u32_e32 v87, 16, v87
	v_add_u32_e32 v85, 16, v85
	v_add_u32_e32 v83, 16, v83
	v_add_u32_e32 v88, -16, v88
	v_add_u32_e32 v86, -16, v86
	v_add_u32_e32 v84, -16, v84
	v_add_u32_e32 v230, s55, v88
	v_cndmask_b32_e64 v230, v230, v87, s[44:45]
	v_ashrrev_i32_e32 v231, 31, v230
	v_lshl_add_u64 v[230:231], v[230:231], 0, s[88:89]
	v_lshlrev_b64 v[230:231], 9, v[230:231]
	v_lshl_add_u64 v[224:225], v[152:153], 0, v[230:231]
	v_add_u32_e32 v230, s55, v86
	v_cndmask_b32_e64 v230, v230, v85, s[44:45]
	v_ashrrev_i32_e32 v231, 31, v230
	v_lshl_add_u64 v[230:231], v[230:231], 0, s[88:89]
	v_lshlrev_b64 v[230:231], 9, v[230:231]
	v_lshl_add_u64 v[226:227], v[154:155], 0, v[230:231]
	v_add_u32_e32 v230, s55, v84
	v_cndmask_b32_e64 v230, v230, v83, s[44:45]
	v_ashrrev_i32_e32 v231, 31, v230
	v_lshl_add_u64 v[230:231], v[230:231], 0, s[88:89]
	v_lshlrev_b64 v[230:231], 9, v[230:231]
	v_lshl_add_u64 v[228:229], v[156:157], 0, v[230:231]
	s_mov_b32 s100, 0

; __device__ __forceinline__ void rwkv_scan_unit(const Params& p, int unit, char* smem) {
;     ...
;         const char* lb = smem + st + ks * 16;
;         const char* vb = smem + st + 1280 + rl * 4;
;         float* yl = (float*)(smem + YOFF + (ci & 1) * 1024) + rl;
;         f32x4 e4 = *(const f32x4*)(lb), kd4 = *(const f32x4*)(lb + 256), ka4 = *(const f32x4*)(lb + 512), r4 = *(const f32x4*)(lb + 768), kk4 = *(const f32x4*)(lb + 1024);
;         float vv = *(const float*)vb;
;         f32x2 sA = {s0, s1}, sB = {s2, s3};
;         float c;
;         { const f32x2 cv = sA * (f32x2){kk4[0], kk4[1]} + sB * (f32x2){kk4[2], kk4[3]}; c = red16(cv[0] + cv[1]); }
; #pragma unroll
;         for (int u = 0; u < SCH; ++u) {
;             f32x4 ne = e4, nkd = kd4, nka = ka4, nr = r4, nkk = kk4; float nv = vv;
;             if (u + 1 < SCH) { const char* q = lb + (u + 1) * STEPB;
;                 ne = *(const f32x4*)(q); nkd = *(const f32x4*)(q + 256); nka = *(const f32x4*)(q + 512); nr = *(const f32x4*)(q + 768); nkk = *(const f32x4*)(q + 1024);
;                 nv = *(const float*)(vb + (u + 1) * STEPB); }
;             const f32x2 v2 = {vv, vv}, c2 = {c, c};
;             const f32x2 tA = __builtin_elementwise_fma(v2, (f32x2){kd4[0], kd4[1]}, __builtin_elementwise_fma(-sA, (f32x2){e4[0], e4[1]}, sA));
;             const f32x2 tB = __builtin_elementwise_fma(v2, (f32x2){kd4[2], kd4[3]}, __builtin_elementwise_fma(-sB, (f32x2){e4[2], e4[3]}, sB));
;             sA = __builtin_elementwise_fma(-c2, (f32x2){ka4[0], ka4[1]}, tA);
;             sB = __builtin_elementwise_fma(-c2, (f32x2){ka4[2], ka4[3]}, tB);
;             const f32x2 yv = __builtin_elementwise_fma(sB, (f32x2){r4[2], r4[3]}, sA * (f32x2){r4[0], r4[1]});
;             float y = yv[0] + yv[1];
;             if (u + 1 < SCH) {
;                 const f32x2 cv = __builtin_elementwise_fma(sB, (f32x2){nkk[2], nkk[3]}, sA * (f32x2){nkk[0], nkk[1]});
;                 float cn = cv[0] + cv[1];
;                 cn = DPP_ADD(cn, 0xB1);  y = DPP_ADD(y, 0xB1);
;                 cn = DPP_ADD(cn, 0x4E);  y = DPP_ADD(y, 0x4E);
;                 cn = DPP_ADD(cn, 0x141); y = DPP_ADD(y, 0x141);
;                 cn = DPP_ADD(cn, 0x140); y = DPP_ADD(y, 0x140);
;                 c = cn;
;             } else y = red16(y);
;             if (ks == 0) yl[u * 16] = y;
.Lsc_p0_body:
	s_add_i32 s30, s64, -1
	s_and_b32 s30, s30, 1
	s_mul_i32 s52, s30, 0x5400
	v_or_b32_e32 v91, s52, v80
	v_add_u32_e32 v92, s52, v81
	ds_read_b128 v[32:35], v91 offset:1024
	ds_read_b128 v[12:15], v91 offset:0
	ds_read_b128 v[16:19], v91 offset:256
	ds_read_b32 v36, v92 offset:1280
	ds_read_b128 v[24:27], v91 offset:512
	ds_read_b128 v[28:31], v91 offset:768
	ds_read_b128 v[40:43], v91 offset:1344
	ds_read_b128 v[60:63], v91 offset:1856
	ds_read_b128 v[44:47], v91 offset:1600
	ds_read_b128 v[94:97], v91 offset:2368
	ds_read_b32 v38, v92 offset:2624
	ds_read_b128 v[64:67], v91 offset:2112
	s_cmp_eq_u32 s100, 0
	s_cbranch_scc1 .Lsc_p0_nodefer
	s_waitcnt lgkmcnt(12)
	v_bfe_u32 v247, v246, 16, 1
	s_movk_i32 s0, 0x7fff
	v_add3_u32 v247, v246, v247, s0
	global_store_short_d16_hi v[244:245], v247, off
	s_branch .Lsc_p0_dd

; #define DPP_ADD(v, ctrl) ((v) + __builtin_bit_cast(float, __builtin_amdgcn_update_dpp(0, __builtin_bit_cast(int, (v)), (ctrl), 0xf, 0xf, true)))
; __device__ __forceinline__ void rwkv_scan_unit(const Params& p, int unit, char* smem) {
;     ...
;         for (int u = 0; u < SCH; ++u) {
;             f32x4 ne = e4, nkd = kd4, nka = ka4, nr = r4, nkk = kk4; float nv = vv;
;             if (u + 1 < SCH) { const char* q = lb + (u + 1) * STEPB;
;                 ne = *(const f32x4*)(q); nkd = *(const f32x4*)(q + 256); nka = *(const f32x4*)(q + 512); nr = *(const f32x4*)(q + 768); nkk = *(const f32x4*)(q + 1024);
;                 nv = *(const float*)(vb + (u + 1) * STEPB); }
;             const f32x2 v2 = {vv, vv}, c2 = {c, c};
;             const f32x2 tA = __builtin_elementwise_fma(v2, (f32x2){kd4[0], kd4[1]}, __builtin_elementwise_fma(-sA, (f32x2){e4[0], e4[1]}, sA));
;             const f32x2 tB = __builtin_elementwise_fma(v2, (f32x2){kd4[2], kd4[3]}, __builtin_elementwise_fma(-sB, (f32x2){e4[2], e4[3]}, sB));
;             sA = __builtin_elementwise_fma(-c2, (f32x2){ka4[0], ka4[1]}, tA);
;             sB = __builtin_elementwise_fma(-c2, (f32x2){ka4[2], ka4[3]}, tB);
;             const f32x2 yv = __builtin_elementwise_fma(sB, (f32x2){r4[2], r4[3]}, sA * (f32x2){r4[0], r4[1]});
;             float y = yv[0] + yv[1];
;             if (u + 1 < SCH) {
;                 const f32x2 cv = __builtin_elementwise_fma(sB, (f32x2){nkk[2], nkk[3]}, sA * (f32x2){nkk[0], nkk[1]});
;                 float cn = cv[0] + cv[1];
;                 cn = DPP_ADD(cn, 0xB1);  y = DPP_ADD(y, 0xB1);
;                 cn = DPP_ADD(cn, 0x4E);  y = DPP_ADD(y, 0x4E);
;                 cn = DPP_ADD(cn, 0x141); y = DPP_ADD(y, 0x141);
;                 cn = DPP_ADD(cn, 0x140); y = DPP_ADD(y, 0x140);
;                 c = cn;
;             } else y = red16(y);
;             if (ks == 0) yl[u * 16] = y;
;             e4 = ne; kd4 = nkd; ka4 = nka; r4 = nr; kk4 = nkk; vv = nv;
;         }
.Lsc_p0_dd:
	s_lshl_b32 s52, s30, 10
	v_lshl_add_u32 v37, v72, 2, s52
	v_lshlrev_b32_e32 v90, 2, v109
	v_add_u32_e32 v90, 0x800, v90
	v_cndmask_b32_e64 v37, v90, v37, s[50:51]
	s_waitcnt lgkmcnt(11)
	v_pk_mul_f32 v[32:33], v[20:21], v[32:33]
	s_waitcnt lgkmcnt(10)
	v_pk_fma_f32 v[12:13], v[20:21], v[12:13], v[20:21] neg_lo:[1,0,0] neg_hi:[1,0,0]
	v_pk_fma_f32 v[32:33], v[22:23], v[34:35], v[32:33]
	v_pk_fma_f32 v[14:15], v[22:23], v[14:15], v[22:23] neg_lo:[1,0,0] neg_hi:[1,0,0]
	v_add_f32_e32 v34, v32, v33
	s_waitcnt lgkmcnt(8)
	v_pk_fma_f32 v[12:13], v[36:37], v[16:17], v[12:13] op_sel_hi:[0,1,1]
	v_pk_fma_f32 v[14:15], v[36:37], v[18:19], v[14:15] op_sel_hi:[0,1,1]
	v_add_f32_dpp v35, v34, v34 quad_perm:[1,0,3,2] row_mask:0xf bank_mask:0xf bound_ctrl:1
	s_nop 1
	v_add_f32_dpp v34, v35, v35 quad_perm:[2,3,0,1] row_mask:0xf bank_mask:0xf bound_ctrl:1
	s_nop 1
	v_add_f32_dpp v35, v34, v34 row_half_mirror row_mask:0xf bank_mask:0xf bound_ctrl:1
	s_nop 1
	v_add_f32_dpp v90, v35, v35 row_mirror row_mask:0xf bank_mask:0xf bound_ctrl:1
	ds_read_b128 v[16:19], v91 offset:2944
	ds_read_b128 v[32:35], v91 offset:3712
	ds_read_b32 v36, v92 offset:3968
	s_waitcnt lgkmcnt(10)
	v_pk_fma_f32 v[20:21], v[90:91], v[24:25], v[12:13] op_sel_hi:[0,1,1] neg_lo:[1,0,0] neg_hi:[1,0,0]
	v_pk_fma_f32 v[22:23], v[90:91], v[26:27], v[14:15] op_sel_hi:[0,1,1] neg_lo:[1,0,0] neg_hi:[1,0,0]
	ds_read_b128 v[12:15], v91 offset:2688
	ds_read_b128 v[24:27], v91 offset:3200
	s_waitcnt lgkmcnt(7)
	v_pk_mul_f32 v[94:95], v[20:21], v[94:95]
	v_pk_mul_f32 v[28:29], v[20:21], v[28:29]
	v_pk_fma_f32 v[94:95], v[22:23], v[96:97], v[94:95]
	v_pk_fma_f32 v[28:29], v[22:23], v[30:31], v[28:29]
	v_add_f32_e32 v96, v94, v95
	v_add_f32_e32 v30, v28, v29
	v_pk_fma_f32 v[40:41], v[20:21], v[40:41], v[20:21] neg_lo:[1,0,0] neg_hi:[1,0,0]
	v_add_f32_dpp v97, v96, v96 quad_perm:[1,0,3,2] row_mask:0xf bank_mask:0xf bound_ctrl:1
	v_add_f32_dpp v31, v30, v30 quad_perm:[1,0,3,2] row_mask:0xf bank_mask:0xf bound_ctrl:1
	v_pk_fma_f32 v[42:43], v[22:23], v[42:43], v[22:23] neg_lo:[1,0,0] neg_hi:[1,0,0]
	v_add_f32_dpp v96, v97, v97 quad_perm:[2,3,0,1] row_mask:0xf bank_mask:0xf bound_ctrl:1
	v_add_f32_dpp v30, v31, v31 quad_perm:[2,3,0,1] row_mask:0xf bank_mask:0xf bound_ctrl:1
	s_waitcnt lgkmcnt(6)
	v_pk_fma_f32 v[40:41], v[38:39], v[44:45], v[40:41] op_sel_hi:[0,1,1]
	v_add_f32_dpp v97, v96, v96 row_half_mirror row_mask:0xf bank_mask:0xf bound_ctrl:1
	v_add_f32_dpp v31, v30, v30 row_half_mirror row_mask:0xf bank_mask:0xf bound_ctrl:1
	v_pk_fma_f32 v[42:43], v[38:39], v[46:47], v[42:43] op_sel_hi:[0,1,1]
	v_add_f32_dpp v90, v97, v97 row_mirror row_mask:0xf bank_mask:0xf bound_ctrl:1
	v_add_f32_dpp v30, v31, v31 row_mirror row_mask:0xf bank_mask:0xf bound_ctrl:1
	ds_write_b32 v37, v30 offset:43008
	ds_read_b128 v[28:31], v91 offset:3456
	v_pk_fma_f32 v[20:21], v[90:91], v[60:61], v[40:41] op_sel_hi:[0,1,1] neg_lo:[1,0,0] neg_hi:[1,0,0]
	v_pk_fma_f32 v[22:23], v[90:91], v[62:63], v[42:43] op_sel_hi:[0,1,1] neg_lo:[1,0,0] neg_hi:[1,0,0]
	ds_read_b128 v[40:43], v91 offset:4032
	ds_read_b128 v[60:63], v91 offset:4544
	ds_read_b128 v[44:47], v91 offset:4288
	ds_read_b128 v[94:97], v91 offset:5056
	ds_read_b32 v38, v92 offset:5312
	s_waitcnt lgkmcnt(8)
	v_pk_mul_f32 v[32:33], v[20:21], v[32:33]
	v_pk_mul_f32 v[64:65], v[20:21], v[64:65]
	v_pk_fma_f32 v[32:33], v[22:23], v[34:35], v[32:33]
	v_pk_fma_f32 v[64:65], v[22:23], v[66:67], v[64:65]
	v_add_f32_e32 v34, v32, v33
	v_add_f32_e32 v66, v64, v65
	v_pk_fma_f32 v[12:13], v[20:21], v[12:13], v[20:21] neg_lo:[1,0,0] neg_hi:[1,0,0]
	v_add_f32_dpp v35, v34, v34 quad_perm:[1,0,3,2] row_mask:0xf bank_mask:0xf bound_ctrl:1
	v_add_f32_dpp v67, v66, v66 quad_perm:[1,0,3,2] row_mask:0xf bank_mask:0xf bound_ctrl:1
	v_pk_fma_f32 v[14:15], v[22:23], v[14:15], v[22:23] neg_lo:[1,0,0] neg_hi:[1,0,0]
	v_add_f32_dpp v34, v35, v35 quad_perm:[2,3,0,1] row_mask:0xf bank_mask:0xf bound_ctrl:1
	v_add_f32_dpp v66, v67, v67 quad_perm:[2,3,0,1] row_mask:0xf bank_mask:0xf bound_ctrl:1
	v_pk_fma_f32 v[12:13], v[36:37], v[16:17], v[12:13] op_sel_hi:[0,1,1]
	v_add_f32_dpp v35, v34, v34 row_half_mirror row_mask:0xf bank_mask:0xf bound_ctrl:1
	v_add_f32_dpp v67, v66, v66 row_half_mirror row_mask:0xf bank_mask:0xf bound_ctrl:1
	v_pk_fma_f32 v[14:15], v[36:37], v[18:19], v[14:15] op_sel_hi:[0,1,1]
	v_add_f32_dpp v90, v35, v35 row_mirror row_mask:0xf bank_mask:0xf bound_ctrl:1
	v_add_f32_dpp v66, v67, v67 row_mirror row_mask:0xf bank_mask:0xf bound_ctrl:1
	ds_write_b32 v37, v66 offset:43072
	ds_read_b128 v[64:67], v91 offset:4800
	s_waitcnt lgkmcnt(9)
	v_pk_fma_f32 v[20:21], v[90:91], v[24:25], v[12:13] op_sel_hi:[0,1,1] neg_lo:[1,0,0] neg_hi:[1,0,0]
	v_pk_fma_f32 v[22:23], v[90:91], v[26:27], v[14:15] op_sel_hi:[0,1,1] neg_lo:[1,0,0] neg_hi:[1,0,0]
	ds_read_b128 v[12:15], v91 offset:5376
	ds_read_b128 v[24:27], v91 offset:5888
	ds_read_b128 v[16:19], v91 offset:5632
	ds_read_b128 v[32:35], v91 offset:6400
	ds_read_b32 v36, v92 offset:6656
	s_waitcnt lgkmcnt(7)
; #define DPP_ADD(v, ctrl) ((v) + __builtin_bit_cast(float, __builtin_amdgcn_update_dpp(0, __builtin_bit_cast(int, (v)), (ctrl), 0xf, 0xf, true)))
; __device__ __forceinline__ void rwkv_scan_unit(const Params& p, int unit, char* smem) {
;     ...
;         for (int u = 0; u < SCH; ++u) {
;             f32x4 ne = e4, nkd = kd4, nka = ka4, nr = r4, nkk = kk4; float nv = vv;
;             if (u + 1 < SCH) { const char* q = lb + (u + 1) * STEPB;
;                 ne = *(const f32x4*)(q); nkd = *(const f32x4*)(q + 256); nka = *(const f32x4*)(q + 512); nr = *(const f32x4*)(q + 768); nkk = *(const f32x4*)(q + 1024);
;                 nv = *(const float*)(vb + (u + 1) * STEPB); }
;             const f32x2 v2 = {vv, vv}, c2 = {c, c};
;             const f32x2 tA = __builtin_elementwise_fma(v2, (f32x2){kd4[0], kd4[1]}, __builtin_elementwise_fma(-sA, (f32x2){e4[0], e4[1]}, sA));
;             const f32x2 tB = __builtin_elementwise_fma(v2, (f32x2){kd4[2], kd4[3]}, __builtin_elementwise_fma(-sB, (f32x2){e4[2], e4[3]}, sB));
;             sA = __builtin_elementwise_fma(-c2, (f32x2){ka4[0], ka4[1]}, tA);
;             sB = __builtin_elementwise_fma(-c2, (f32x2){ka4[2], ka4[3]}, tB);
;             const f32x2 yv = __builtin_elementwise_fma(sB, (f32x2){r4[2], r4[3]}, sA * (f32x2){r4[0], r4[1]});
;             float y = yv[0] + yv[1];
;             if (u + 1 < SCH) {
;                 const f32x2 cv = __builtin_elementwise_fma(sB, (f32x2){nkk[2], nkk[3]}, sA * (f32x2){nkk[0], nkk[1]});
;                 float cn = cv[0] + cv[1];
;                 cn = DPP_ADD(cn, 0xB1);  y = DPP_ADD(y, 0xB1);
;                 cn = DPP_ADD(cn, 0x4E);  y = DPP_ADD(y, 0x4E);
;                 cn = DPP_ADD(cn, 0x141); y = DPP_ADD(y, 0x141);
;                 cn = DPP_ADD(cn, 0x140); y = DPP_ADD(y, 0x140);
;                 c = cn;
;             } else y = red16(y);
;             if (ks == 0) yl[u * 16] = y;
;             e4 = ne; kd4 = nkd; ka4 = nka; r4 = nr; kk4 = nkk; vv = nv;
;         }
	v_pk_mul_f32 v[94:95], v[20:21], v[94:95]
	v_pk_mul_f32 v[28:29], v[20:21], v[28:29]
	v_pk_fma_f32 v[94:95], v[22:23], v[96:97], v[94:95]
	v_pk_fma_f32 v[28:29], v[22:23], v[30:31], v[28:29]
	v_add_f32_e32 v96, v94, v95
	v_add_f32_e32 v30, v28, v29
	v_pk_fma_f32 v[40:41], v[20:21], v[40:41], v[20:21] neg_lo:[1,0,0] neg_hi:[1,0,0]
	v_add_f32_dpp v97, v96, v96 quad_perm:[1,0,3,2] row_mask:0xf bank_mask:0xf bound_ctrl:1
	v_add_f32_dpp v31, v30, v30 quad_perm:[1,0,3,2] row_mask:0xf bank_mask:0xf bound_ctrl:1
	v_pk_fma_f32 v[42:43], v[22:23], v[42:43], v[22:23] neg_lo:[1,0,0] neg_hi:[1,0,0]
	v_add_f32_dpp v96, v97, v97 quad_perm:[2,3,0,1] row_mask:0xf bank_mask:0xf bound_ctrl:1
	v_add_f32_dpp v30, v31, v31 quad_perm:[2,3,0,1] row_mask:0xf bank_mask:0xf bound_ctrl:1
	v_pk_fma_f32 v[40:41], v[38:39], v[44:45], v[40:41] op_sel_hi:[0,1,1]
	v_add_f32_dpp v97, v96, v96 row_half_mirror row_mask:0xf bank_mask:0xf bound_ctrl:1
	v_add_f32_dpp v31, v30, v30 row_half_mirror row_mask:0xf bank_mask:0xf bound_ctrl:1
	v_pk_fma_f32 v[42:43], v[38:39], v[46:47], v[42:43] op_sel_hi:[0,1,1]
	v_add_f32_dpp v90, v97, v97 row_mirror row_mask:0xf bank_mask:0xf bound_ctrl:1
	v_add_f32_dpp v30, v31, v31 row_mirror row_mask:0xf bank_mask:0xf bound_ctrl:1
	ds_write_b32 v37, v30 offset:43136
	ds_read_b128 v[28:31], v91 offset:6144
	v_pk_fma_f32 v[20:21], v[90:91], v[60:61], v[40:41] op_sel_hi:[0,1,1] neg_lo:[1,0,0] neg_hi:[1,0,0]
	v_pk_fma_f32 v[22:23], v[90:91], v[62:63], v[42:43] op_sel_hi:[0,1,1] neg_lo:[1,0,0] neg_hi:[1,0,0]
	ds_read_b128 v[40:43], v91 offset:6720
	ds_read_b128 v[60:63], v91 offset:7232
	ds_read_b128 v[44:47], v91 offset:6976
	ds_read_b128 v[94:97], v91 offset:7744
	ds_read_b32 v38, v92 offset:8000
	s_waitcnt lgkmcnt(7)
	v_pk_mul_f32 v[32:33], v[20:21], v[32:33]
	v_pk_mul_f32 v[64:65], v[20:21], v[64:65]
	v_pk_fma_f32 v[32:33], v[22:23], v[34:35], v[32:33]
	v_pk_fma_f32 v[64:65], v[22:23], v[66:67], v[64:65]
	v_add_f32_e32 v34, v32, v33
	v_add_f32_e32 v66, v64, v65
	v_pk_fma_f32 v[12:13], v[20:21], v[12:13], v[20:21] neg_lo:[1,0,0] neg_hi:[1,0,0]
	v_add_f32_dpp v35, v34, v34 quad_perm:[1,0,3,2] row_mask:0xf bank_mask:0xf bound_ctrl:1
	v_add_f32_dpp v67, v66, v66 quad_perm:[1,0,3,2] row_mask:0xf bank_mask:0xf bound_ctrl:1
	v_pk_fma_f32 v[14:15], v[22:23], v[14:15], v[22:23] neg_lo:[1,0,0] neg_hi:[1,0,0]
	v_add_f32_dpp v34, v35, v35 quad_perm:[2,3,0,1] row_mask:0xf bank_mask:0xf bound_ctrl:1
	v_add_f32_dpp v66, v67, v67 quad_perm:[2,3,0,1] row_mask:0xf bank_mask:0xf bound_ctrl:1
	v_pk_fma_f32 v[12:13], v[36:37], v[16:17], v[12:13] op_sel_hi:[0,1,1]
	v_add_f32_dpp v35, v34, v34 row_half_mirror row_mask:0xf bank_mask:0xf bound_ctrl:1
	v_add_f32_dpp v67, v66, v66 row_half_mirror row_mask:0xf bank_mask:0xf bound_ctrl:1
	v_pk_fma_f32 v[14:15], v[36:37], v[18:19], v[14:15] op_sel_hi:[0,1,1]
	v_add_f32_dpp v90, v35, v35 row_mirror row_mask:0xf bank_mask:0xf bound_ctrl:1
	v_add_f32_dpp v66, v67, v67 row_mirror row_mask:0xf bank_mask:0xf bound_ctrl:1
	ds_write_b32 v37, v66 offset:43200
	ds_read_b128 v[64:67], v91 offset:7488
	v_pk_fma_f32 v[20:21], v[90:91], v[24:25], v[12:13] op_sel_hi:[0,1,1] neg_lo:[1,0,0] neg_hi:[1,0,0]
	v_pk_fma_f32 v[22:23], v[90:91], v[26:27], v[14:15] op_sel_hi:[0,1,1] neg_lo:[1,0,0] neg_hi:[1,0,0]
	ds_read_b128 v[12:15], v91 offset:8064
	ds_read_b128 v[24:27], v91 offset:8576
	ds_read_b128 v[16:19], v91 offset:8320
	ds_read_b128 v[32:35], v91 offset:9088
	ds_read_b32 v36, v92 offset:9344
	s_waitcnt lgkmcnt(7)
	v_pk_mul_f32 v[94:95], v[20:21], v[94:95]
	v_pk_mul_f32 v[28:29], v[20:21], v[28:29]
	v_pk_fma_f32 v[94:95], v[22:23], v[96:97], v[94:95]
	v_pk_fma_f32 v[28:29], v[22:23], v[30:31], v[28:29]
	v_add_f32_e32 v96, v94, v95
	v_add_f32_e32 v30, v28, v29
	v_pk_fma_f32 v[40:41], v[20:21], v[40:41], v[20:21] neg_lo:[1,0,0] neg_hi:[1,0,0]
	v_add_f32_dpp v97, v96, v96 quad_perm:[1,0,3,2] row_mask:0xf bank_mask:0xf bound_ctrl:1
	v_add_f32_dpp v31, v30, v30 quad_perm:[1,0,3,2] row_mask:0xf bank_mask:0xf bound_ctrl:1
	v_pk_fma_f32 v[42:43], v[22:23], v[42:43], v[22:23] neg_lo:[1,0,0] neg_hi:[1,0,0]
	v_add_f32_dpp v96, v97, v97 quad_perm:[2,3,0,1] row_mask:0xf bank_mask:0xf bound_ctrl:1
	v_add_f32_dpp v30, v31, v31 quad_perm:[2,3,0,1] row_mask:0xf bank_mask:0xf bound_ctrl:1
	v_pk_fma_f32 v[40:41], v[38:39], v[44:45], v[40:41] op_sel_hi:[0,1,1]
	v_add_f32_dpp v97, v96, v96 row_half_mirror row_mask:0xf bank_mask:0xf bound_ctrl:1
	v_add_f32_dpp v31, v30, v30 row_half_mirror row_mask:0xf bank_mask:0xf bound_ctrl:1
	v_pk_fma_f32 v[42:43], v[38:39], v[46:47], v[42:43] op_sel_hi:[0,1,1]
	v_add_f32_dpp v90, v97, v97 row_mirror row_mask:0xf bank_mask:0xf bound_ctrl:1
	v_add_f32_dpp v30, v31, v31 row_mirror row_mask:0xf bank_mask:0xf bound_ctrl:1
	ds_write_b32 v37, v30 offset:43264
	ds_read_b128 v[28:31], v91 offset:8832
	v_pk_fma_f32 v[20:21], v[90:91], v[60:61], v[40:41] op_sel_hi:[0,1,1] neg_lo:[1,0,0] neg_hi:[1,0,0]
	v_pk_fma_f32 v[22:23], v[90:91], v[62:63], v[42:43] op_sel_hi:[0,1,1] neg_lo:[1,0,0] neg_hi:[1,0,0]
	ds_read_b128 v[40:43], v91 offset:9408
	ds_read_b128 v[60:63], v91 offset:9920
	ds_read_b128 v[44:47], v91 offset:9664
	ds_read_b128 v[94:97], v91 offset:10432
	ds_read_b32 v38, v92 offset:10688
	s_waitcnt lgkmcnt(7)
; #define DPP_ADD(v, ctrl) ((v) + __builtin_bit_cast(float, __builtin_amdgcn_update_dpp(0, __builtin_bit_cast(int, (v)), (ctrl), 0xf, 0xf, true)))
; __device__ __forceinline__ void rwkv_scan_unit(const Params& p, int unit, char* smem) {
;     ...
;         for (int u = 0; u < SCH; ++u) {
;             f32x4 ne = e4, nkd = kd4, nka = ka4, nr = r4, nkk = kk4; float nv = vv;
;             if (u + 1 < SCH) { const char* q = lb + (u + 1) * STEPB;
;                 ne = *(const f32x4*)(q); nkd = *(const f32x4*)(q + 256); nka = *(const f32x4*)(q + 512); nr = *(const f32x4*)(q + 768); nkk = *(const f32x4*)(q + 1024);
;                 nv = *(const float*)(vb + (u + 1) * STEPB); }
;             const f32x2 v2 = {vv, vv}, c2 = {c, c};
;             const f32x2 tA = __builtin_elementwise_fma(v2, (f32x2){kd4[0], kd4[1]}, __builtin_elementwise_fma(-sA, (f32x2){e4[0], e4[1]}, sA));
;             const f32x2 tB = __builtin_elementwise_fma(v2, (f32x2){kd4[2], kd4[3]}, __builtin_elementwise_fma(-sB, (f32x2){e4[2], e4[3]}, sB));
;             sA = __builtin_elementwise_fma(-c2, (f32x2){ka4[0], ka4[1]}, tA);
;             sB = __builtin_elementwise_fma(-c2, (f32x2){ka4[2], ka4[3]}, tB);
;             const f32x2 yv = __builtin_elementwise_fma(sB, (f32x2){r4[2], r4[3]}, sA * (f32x2){r4[0], r4[1]});
;             float y = yv[0] + yv[1];
;             if (u + 1 < SCH) {
;                 const f32x2 cv = __builtin_elementwise_fma(sB, (f32x2){nkk[2], nkk[3]}, sA * (f32x2){nkk[0], nkk[1]});
;                 float cn = cv[0] + cv[1];
;                 cn = DPP_ADD(cn, 0xB1);  y = DPP_ADD(y, 0xB1);
;                 cn = DPP_ADD(cn, 0x4E);  y = DPP_ADD(y, 0x4E);
;                 cn = DPP_ADD(cn, 0x141); y = DPP_ADD(y, 0x141);
;                 cn = DPP_ADD(cn, 0x140); y = DPP_ADD(y, 0x140);
;                 c = cn;
;             } else y = red16(y);
;             if (ks == 0) yl[u * 16] = y;
;             e4 = ne; kd4 = nkd; ka4 = nka; r4 = nr; kk4 = nkk; vv = nv;
;         }
	v_pk_mul_f32 v[32:33], v[20:21], v[32:33]
	v_pk_mul_f32 v[64:65], v[20:21], v[64:65]
	v_pk_fma_f32 v[32:33], v[22:23], v[34:35], v[32:33]
	v_pk_fma_f32 v[64:65], v[22:23], v[66:67], v[64:65]
	v_add_f32_e32 v34, v32, v33
	v_add_f32_e32 v66, v64, v65
	v_pk_fma_f32 v[12:13], v[20:21], v[12:13], v[20:21] neg_lo:[1,0,0] neg_hi:[1,0,0]
	v_add_f32_dpp v35, v34, v34 quad_perm:[1,0,3,2] row_mask:0xf bank_mask:0xf bound_ctrl:1
	v_add_f32_dpp v67, v66, v66 quad_perm:[1,0,3,2] row_mask:0xf bank_mask:0xf bound_ctrl:1
	v_pk_fma_f32 v[14:15], v[22:23], v[14:15], v[22:23] neg_lo:[1,0,0] neg_hi:[1,0,0]
	v_add_f32_dpp v34, v35, v35 quad_perm:[2,3,0,1] row_mask:0xf bank_mask:0xf bound_ctrl:1
	v_add_f32_dpp v66, v67, v67 quad_perm:[2,3,0,1] row_mask:0xf bank_mask:0xf bound_ctrl:1
	v_pk_fma_f32 v[12:13], v[36:37], v[16:17], v[12:13] op_sel_hi:[0,1,1]
	v_add_f32_dpp v35, v34, v34 row_half_mirror row_mask:0xf bank_mask:0xf bound_ctrl:1
	v_add_f32_dpp v67, v66, v66 row_half_mirror row_mask:0xf bank_mask:0xf bound_ctrl:1
	v_pk_fma_f32 v[14:15], v[36:37], v[18:19], v[14:15] op_sel_hi:[0,1,1]
	v_add_f32_dpp v90, v35, v35 row_mirror row_mask:0xf bank_mask:0xf bound_ctrl:1
	v_add_f32_dpp v66, v67, v67 row_mirror row_mask:0xf bank_mask:0xf bound_ctrl:1
	ds_write_b32 v37, v66 offset:43328
	ds_read_b128 v[64:67], v91 offset:10176
	v_pk_fma_f32 v[20:21], v[90:91], v[24:25], v[12:13] op_sel_hi:[0,1,1] neg_lo:[1,0,0] neg_hi:[1,0,0]
	v_pk_fma_f32 v[22:23], v[90:91], v[26:27], v[14:15] op_sel_hi:[0,1,1] neg_lo:[1,0,0] neg_hi:[1,0,0]
	ds_read_b128 v[12:15], v91 offset:10752
	ds_read_b128 v[24:27], v91 offset:11264
	ds_read_b128 v[16:19], v91 offset:11008
	ds_read_b128 v[32:35], v91 offset:11776
	ds_read_b32 v36, v92 offset:12032
	s_waitcnt lgkmcnt(7)
	v_pk_mul_f32 v[94:95], v[20:21], v[94:95]
	v_pk_mul_f32 v[28:29], v[20:21], v[28:29]
	v_pk_fma_f32 v[94:95], v[22:23], v[96:97], v[94:95]
	v_pk_fma_f32 v[28:29], v[22:23], v[30:31], v[28:29]
	v_add_f32_e32 v96, v94, v95
	v_add_f32_e32 v30, v28, v29
	v_pk_fma_f32 v[40:41], v[20:21], v[40:41], v[20:21] neg_lo:[1,0,0] neg_hi:[1,0,0]
	v_add_f32_dpp v97, v96, v96 quad_perm:[1,0,3,2] row_mask:0xf bank_mask:0xf bound_ctrl:1
	v_add_f32_dpp v31, v30, v30 quad_perm:[1,0,3,2] row_mask:0xf bank_mask:0xf bound_ctrl:1
	v_pk_fma_f32 v[42:43], v[22:23], v[42:43], v[22:23] neg_lo:[1,0,0] neg_hi:[1,0,0]
	v_add_f32_dpp v96, v97, v97 quad_perm:[2,3,0,1] row_mask:0xf bank_mask:0xf bound_ctrl:1
	v_add_f32_dpp v30, v31, v31 quad_perm:[2,3,0,1] row_mask:0xf bank_mask:0xf bound_ctrl:1
	v_pk_fma_f32 v[40:41], v[38:39], v[44:45], v[40:41] op_sel_hi:[0,1,1]
	v_add_f32_dpp v97, v96, v96 row_half_mirror row_mask:0xf bank_mask:0xf bound_ctrl:1
	v_add_f32_dpp v31, v30, v30 row_half_mirror row_mask:0xf bank_mask:0xf bound_ctrl:1
	v_pk_fma_f32 v[42:43], v[38:39], v[46:47], v[42:43] op_sel_hi:[0,1,1]
	v_add_f32_dpp v90, v97, v97 row_mirror row_mask:0xf bank_mask:0xf bound_ctrl:1
	v_add_f32_dpp v30, v31, v31 row_mirror row_mask:0xf bank_mask:0xf bound_ctrl:1
	ds_write_b32 v37, v30 offset:43392
	ds_read_b128 v[28:31], v91 offset:11520
	v_pk_fma_f32 v[20:21], v[90:91], v[60:61], v[40:41] op_sel_hi:[0,1,1] neg_lo:[1,0,0] neg_hi:[1,0,0]
	v_pk_fma_f32 v[22:23], v[90:91], v[62:63], v[42:43] op_sel_hi:[0,1,1] neg_lo:[1,0,0] neg_hi:[1,0,0]
	ds_read_b128 v[40:43], v91 offset:12096
	ds_read_b128 v[60:63], v91 offset:12608
	ds_read_b128 v[44:47], v91 offset:12352
	ds_read_b128 v[94:97], v91 offset:13120
	ds_read_b32 v38, v92 offset:13376
	s_waitcnt lgkmcnt(7)
	v_pk_mul_f32 v[32:33], v[20:21], v[32:33]
	v_pk_mul_f32 v[64:65], v[20:21], v[64:65]
	v_pk_fma_f32 v[32:33], v[22:23], v[34:35], v[32:33]
	v_pk_fma_f32 v[64:65], v[22:23], v[66:67], v[64:65]
	v_add_f32_e32 v34, v32, v33
	v_add_f32_e32 v66, v64, v65
	v_pk_fma_f32 v[12:13], v[20:21], v[12:13], v[20:21] neg_lo:[1,0,0] neg_hi:[1,0,0]
	v_add_f32_dpp v35, v34, v34 quad_perm:[1,0,3,2] row_mask:0xf bank_mask:0xf bound_ctrl:1
	v_add_f32_dpp v67, v66, v66 quad_perm:[1,0,3,2] row_mask:0xf bank_mask:0xf bound_ctrl:1
	v_pk_fma_f32 v[14:15], v[22:23], v[14:15], v[22:23] neg_lo:[1,0,0] neg_hi:[1,0,0]
	v_add_f32_dpp v34, v35, v35 quad_perm:[2,3,0,1] row_mask:0xf bank_mask:0xf bound_ctrl:1
	v_add_f32_dpp v66, v67, v67 quad_perm:[2,3,0,1] row_mask:0xf bank_mask:0xf bound_ctrl:1
	v_pk_fma_f32 v[12:13], v[36:37], v[16:17], v[12:13] op_sel_hi:[0,1,1]
	v_add_f32_dpp v35, v34, v34 row_half_mirror row_mask:0xf bank_mask:0xf bound_ctrl:1
	v_add_f32_dpp v67, v66, v66 row_half_mirror row_mask:0xf bank_mask:0xf bound_ctrl:1
	v_pk_fma_f32 v[14:15], v[36:37], v[18:19], v[14:15] op_sel_hi:[0,1,1]
	v_add_f32_dpp v90, v35, v35 row_mirror row_mask:0xf bank_mask:0xf bound_ctrl:1
	v_add_f32_dpp v66, v67, v67 row_mirror row_mask:0xf bank_mask:0xf bound_ctrl:1
	ds_write_b32 v37, v66 offset:43456
	ds_read_b128 v[64:67], v91 offset:12864
	v_pk_fma_f32 v[20:21], v[90:91], v[24:25], v[12:13] op_sel_hi:[0,1,1] neg_lo:[1,0,0] neg_hi:[1,0,0]
	v_pk_fma_f32 v[22:23], v[90:91], v[26:27], v[14:15] op_sel_hi:[0,1,1] neg_lo:[1,0,0] neg_hi:[1,0,0]
	ds_read_b128 v[12:15], v91 offset:13440
	ds_read_b128 v[24:27], v91 offset:13952
	ds_read_b128 v[16:19], v91 offset:13696
	ds_read_b128 v[32:35], v91 offset:14464
	ds_read_b32 v36, v92 offset:14720
	s_waitcnt lgkmcnt(7)
; #define DPP_ADD(v, ctrl) ((v) + __builtin_bit_cast(float, __builtin_amdgcn_update_dpp(0, __builtin_bit_cast(int, (v)), (ctrl), 0xf, 0xf, true)))
; __device__ __forceinline__ void rwkv_scan_unit(const Params& p, int unit, char* smem) {
;     ...
;         for (int u = 0; u < SCH; ++u) {
;             f32x4 ne = e4, nkd = kd4, nka = ka4, nr = r4, nkk = kk4; float nv = vv;
;             if (u + 1 < SCH) { const char* q = lb + (u + 1) * STEPB;
;                 ne = *(const f32x4*)(q); nkd = *(const f32x4*)(q + 256); nka = *(const f32x4*)(q + 512); nr = *(const f32x4*)(q + 768); nkk = *(const f32x4*)(q + 1024);
;                 nv = *(const float*)(vb + (u + 1) * STEPB); }
;             const f32x2 v2 = {vv, vv}, c2 = {c, c};
;             const f32x2 tA = __builtin_elementwise_fma(v2, (f32x2){kd4[0], kd4[1]}, __builtin_elementwise_fma(-sA, (f32x2){e4[0], e4[1]}, sA));
;             const f32x2 tB = __builtin_elementwise_fma(v2, (f32x2){kd4[2], kd4[3]}, __builtin_elementwise_fma(-sB, (f32x2){e4[2], e4[3]}, sB));
;             sA = __builtin_elementwise_fma(-c2, (f32x2){ka4[0], ka4[1]}, tA);
;             sB = __builtin_elementwise_fma(-c2, (f32x2){ka4[2], ka4[3]}, tB);
;             const f32x2 yv = __builtin_elementwise_fma(sB, (f32x2){r4[2], r4[3]}, sA * (f32x2){r4[0], r4[1]});
;             float y = yv[0] + yv[1];
;             if (u + 1 < SCH) {
;                 const f32x2 cv = __builtin_elementwise_fma(sB, (f32x2){nkk[2], nkk[3]}, sA * (f32x2){nkk[0], nkk[1]});
;                 float cn = cv[0] + cv[1];
;                 cn = DPP_ADD(cn, 0xB1);  y = DPP_ADD(y, 0xB1);
;                 cn = DPP_ADD(cn, 0x4E);  y = DPP_ADD(y, 0x4E);
;                 cn = DPP_ADD(cn, 0x141); y = DPP_ADD(y, 0x141);
;                 cn = DPP_ADD(cn, 0x140); y = DPP_ADD(y, 0x140);
;                 c = cn;
;             } else y = red16(y);
;             if (ks == 0) yl[u * 16] = y;
;             e4 = ne; kd4 = nkd; ka4 = nka; r4 = nr; kk4 = nkk; vv = nv;
;         }
	v_pk_mul_f32 v[94:95], v[20:21], v[94:95]
	v_pk_mul_f32 v[28:29], v[20:21], v[28:29]
	v_pk_fma_f32 v[94:95], v[22:23], v[96:97], v[94:95]
	v_pk_fma_f32 v[28:29], v[22:23], v[30:31], v[28:29]
	v_add_f32_e32 v96, v94, v95
	v_add_f32_e32 v30, v28, v29
	v_pk_fma_f32 v[40:41], v[20:21], v[40:41], v[20:21] neg_lo:[1,0,0] neg_hi:[1,0,0]
	v_add_f32_dpp v97, v96, v96 quad_perm:[1,0,3,2] row_mask:0xf bank_mask:0xf bound_ctrl:1
	v_add_f32_dpp v31, v30, v30 quad_perm:[1,0,3,2] row_mask:0xf bank_mask:0xf bound_ctrl:1
	v_pk_fma_f32 v[42:43], v[22:23], v[42:43], v[22:23] neg_lo:[1,0,0] neg_hi:[1,0,0]
	v_add_f32_dpp v96, v97, v97 quad_perm:[2,3,0,1] row_mask:0xf bank_mask:0xf bound_ctrl:1
	v_add_f32_dpp v30, v31, v31 quad_perm:[2,3,0,1] row_mask:0xf bank_mask:0xf bound_ctrl:1
	v_pk_fma_f32 v[40:41], v[38:39], v[44:45], v[40:41] op_sel_hi:[0,1,1]
	v_add_f32_dpp v97, v96, v96 row_half_mirror row_mask:0xf bank_mask:0xf bound_ctrl:1
	v_add_f32_dpp v31, v30, v30 row_half_mirror row_mask:0xf bank_mask:0xf bound_ctrl:1
	v_pk_fma_f32 v[42:43], v[38:39], v[46:47], v[42:43] op_sel_hi:[0,1,1]
	v_add_f32_dpp v90, v97, v97 row_mirror row_mask:0xf bank_mask:0xf bound_ctrl:1
	v_add_f32_dpp v30, v31, v31 row_mirror row_mask:0xf bank_mask:0xf bound_ctrl:1
	ds_write_b32 v37, v30 offset:43520
	ds_read_b128 v[28:31], v91 offset:14208
	v_pk_fma_f32 v[20:21], v[90:91], v[60:61], v[40:41] op_sel_hi:[0,1,1] neg_lo:[1,0,0] neg_hi:[1,0,0]
	v_pk_fma_f32 v[22:23], v[90:91], v[62:63], v[42:43] op_sel_hi:[0,1,1] neg_lo:[1,0,0] neg_hi:[1,0,0]
	ds_read_b128 v[40:43], v91 offset:14784
	ds_read_b128 v[60:63], v91 offset:15296
	ds_read_b128 v[44:47], v91 offset:15040
	ds_read_b128 v[94:97], v91 offset:15808
	ds_read_b32 v38, v92 offset:16064
	s_waitcnt lgkmcnt(7)
	v_pk_mul_f32 v[32:33], v[20:21], v[32:33]
	v_pk_mul_f32 v[64:65], v[20:21], v[64:65]
	v_pk_fma_f32 v[32:33], v[22:23], v[34:35], v[32:33]
	v_pk_fma_f32 v[64:65], v[22:23], v[66:67], v[64:65]
	v_add_f32_e32 v34, v32, v33
	v_add_f32_e32 v66, v64, v65
	v_pk_fma_f32 v[12:13], v[20:21], v[12:13], v[20:21] neg_lo:[1,0,0] neg_hi:[1,0,0]
	v_add_f32_dpp v35, v34, v34 quad_perm:[1,0,3,2] row_mask:0xf bank_mask:0xf bound_ctrl:1
	v_add_f32_dpp v67, v66, v66 quad_perm:[1,0,3,2] row_mask:0xf bank_mask:0xf bound_ctrl:1
	v_pk_fma_f32 v[14:15], v[22:23], v[14:15], v[22:23] neg_lo:[1,0,0] neg_hi:[1,0,0]
	v_add_f32_dpp v34, v35, v35 quad_perm:[2,3,0,1] row_mask:0xf bank_mask:0xf bound_ctrl:1
	v_add_f32_dpp v66, v67, v67 quad_perm:[2,3,0,1] row_mask:0xf bank_mask:0xf bound_ctrl:1
	v_pk_fma_f32 v[12:13], v[36:37], v[16:17], v[12:13] op_sel_hi:[0,1,1]
	v_add_f32_dpp v35, v34, v34 row_half_mirror row_mask:0xf bank_mask:0xf bound_ctrl:1
	v_add_f32_dpp v67, v66, v66 row_half_mirror row_mask:0xf bank_mask:0xf bound_ctrl:1
	v_pk_fma_f32 v[14:15], v[36:37], v[18:19], v[14:15] op_sel_hi:[0,1,1]
	v_add_f32_dpp v90, v35, v35 row_mirror row_mask:0xf bank_mask:0xf bound_ctrl:1
	v_add_f32_dpp v66, v67, v67 row_mirror row_mask:0xf bank_mask:0xf bound_ctrl:1
	ds_write_b32 v37, v66 offset:43584
	ds_read_b128 v[64:67], v91 offset:15552
	v_pk_fma_f32 v[20:21], v[90:91], v[24:25], v[12:13] op_sel_hi:[0,1,1] neg_lo:[1,0,0] neg_hi:[1,0,0]
	v_pk_fma_f32 v[22:23], v[90:91], v[26:27], v[14:15] op_sel_hi:[0,1,1] neg_lo:[1,0,0] neg_hi:[1,0,0]
	ds_read_b128 v[12:15], v91 offset:16128
	ds_read_b128 v[24:27], v91 offset:16640
	ds_read_b128 v[16:19], v91 offset:16384
	ds_read_b128 v[32:35], v91 offset:17152
	ds_read_b32 v36, v92 offset:17408
	s_waitcnt lgkmcnt(7)
	v_pk_mul_f32 v[94:95], v[20:21], v[94:95]
	v_pk_mul_f32 v[28:29], v[20:21], v[28:29]
	v_pk_fma_f32 v[94:95], v[22:23], v[96:97], v[94:95]
	v_pk_fma_f32 v[28:29], v[22:23], v[30:31], v[28:29]
	v_add_f32_e32 v96, v94, v95
	v_add_f32_e32 v30, v28, v29
	v_pk_fma_f32 v[40:41], v[20:21], v[40:41], v[20:21] neg_lo:[1,0,0] neg_hi:[1,0,0]
	v_add_f32_dpp v97, v96, v96 quad_perm:[1,0,3,2] row_mask:0xf bank_mask:0xf bound_ctrl:1
	v_add_f32_dpp v31, v30, v30 quad_perm:[1,0,3,2] row_mask:0xf bank_mask:0xf bound_ctrl:1
	v_pk_fma_f32 v[42:43], v[22:23], v[42:43], v[22:23] neg_lo:[1,0,0] neg_hi:[1,0,0]
	v_add_f32_dpp v96, v97, v97 quad_perm:[2,3,0,1] row_mask:0xf bank_mask:0xf bound_ctrl:1
	v_add_f32_dpp v30, v31, v31 quad_perm:[2,3,0,1] row_mask:0xf bank_mask:0xf bound_ctrl:1
	v_pk_fma_f32 v[40:41], v[38:39], v[44:45], v[40:41] op_sel_hi:[0,1,1]
	v_add_f32_dpp v97, v96, v96 row_half_mirror row_mask:0xf bank_mask:0xf bound_ctrl:1
	v_add_f32_dpp v31, v30, v30 row_half_mirror row_mask:0xf bank_mask:0xf bound_ctrl:1
	v_pk_fma_f32 v[42:43], v[38:39], v[46:47], v[42:43] op_sel_hi:[0,1,1]
	v_add_f32_dpp v90, v97, v97 row_mirror row_mask:0xf bank_mask:0xf bound_ctrl:1
	v_add_f32_dpp v30, v31, v31 row_mirror row_mask:0xf bank_mask:0xf bound_ctrl:1
	ds_write_b32 v37, v30 offset:43648
	ds_read_b128 v[28:31], v91 offset:16896
	v_pk_fma_f32 v[20:21], v[90:91], v[60:61], v[40:41] op_sel_hi:[0,1,1] neg_lo:[1,0,0] neg_hi:[1,0,0]
	v_pk_fma_f32 v[22:23], v[90:91], v[62:63], v[42:43] op_sel_hi:[0,1,1] neg_lo:[1,0,0] neg_hi:[1,0,0]
	ds_read_b128 v[40:43], v91 offset:17472
	ds_read_b128 v[60:63], v91 offset:17984
	ds_read_b128 v[44:47], v91 offset:17728
	ds_read_b128 v[94:97], v91 offset:18496
	ds_read_b32 v38, v92 offset:18752
	s_waitcnt lgkmcnt(7)
; #define DPP_ADD(v, ctrl) ((v) + __builtin_bit_cast(float, __builtin_amdgcn_update_dpp(0, __builtin_bit_cast(int, (v)), (ctrl), 0xf, 0xf, true)))
; __device__ __forceinline__ void rwkv_scan_unit(const Params& p, int unit, char* smem) {
;     ...
;         for (int u = 0; u < SCH; ++u) {
;             f32x4 ne = e4, nkd = kd4, nka = ka4, nr = r4, nkk = kk4; float nv = vv;
;             if (u + 1 < SCH) { const char* q = lb + (u + 1) * STEPB;
;                 ne = *(const f32x4*)(q); nkd = *(const f32x4*)(q + 256); nka = *(const f32x4*)(q + 512); nr = *(const f32x4*)(q + 768); nkk = *(const f32x4*)(q + 1024);
;                 nv = *(const float*)(vb + (u + 1) * STEPB); }
;             const f32x2 v2 = {vv, vv}, c2 = {c, c};
;             const f32x2 tA = __builtin_elementwise_fma(v2, (f32x2){kd4[0], kd4[1]}, __builtin_elementwise_fma(-sA, (f32x2){e4[0], e4[1]}, sA));
;             const f32x2 tB = __builtin_elementwise_fma(v2, (f32x2){kd4[2], kd4[3]}, __builtin_elementwise_fma(-sB, (f32x2){e4[2], e4[3]}, sB));
;             sA = __builtin_elementwise_fma(-c2, (f32x2){ka4[0], ka4[1]}, tA);
;             sB = __builtin_elementwise_fma(-c2, (f32x2){ka4[2], ka4[3]}, tB);
;             const f32x2 yv = __builtin_elementwise_fma(sB, (f32x2){r4[2], r4[3]}, sA * (f32x2){r4[0], r4[1]});
;             float y = yv[0] + yv[1];
;             if (u + 1 < SCH) {
;                 const f32x2 cv = __builtin_elementwise_fma(sB, (f32x2){nkk[2], nkk[3]}, sA * (f32x2){nkk[0], nkk[1]});
;                 float cn = cv[0] + cv[1];
;                 cn = DPP_ADD(cn, 0xB1);  y = DPP_ADD(y, 0xB1);
;                 cn = DPP_ADD(cn, 0x4E);  y = DPP_ADD(y, 0x4E);
;                 cn = DPP_ADD(cn, 0x141); y = DPP_ADD(y, 0x141);
;                 cn = DPP_ADD(cn, 0x140); y = DPP_ADD(y, 0x140);
;                 c = cn;
;             } else y = red16(y);
;             if (ks == 0) yl[u * 16] = y;
;             e4 = ne; kd4 = nkd; ka4 = nka; r4 = nr; kk4 = nkk; vv = nv;
;         }
	v_pk_mul_f32 v[32:33], v[20:21], v[32:33]
	v_pk_mul_f32 v[64:65], v[20:21], v[64:65]
	v_pk_fma_f32 v[32:33], v[22:23], v[34:35], v[32:33]
	v_pk_fma_f32 v[64:65], v[22:23], v[66:67], v[64:65]
	v_add_f32_e32 v34, v32, v33
	v_add_f32_e32 v66, v64, v65
	v_pk_fma_f32 v[12:13], v[20:21], v[12:13], v[20:21] neg_lo:[1,0,0] neg_hi:[1,0,0]
	v_add_f32_dpp v35, v34, v34 quad_perm:[1,0,3,2] row_mask:0xf bank_mask:0xf bound_ctrl:1
	v_add_f32_dpp v67, v66, v66 quad_perm:[1,0,3,2] row_mask:0xf bank_mask:0xf bound_ctrl:1
	v_pk_fma_f32 v[14:15], v[22:23], v[14:15], v[22:23] neg_lo:[1,0,0] neg_hi:[1,0,0]
	v_add_f32_dpp v34, v35, v35 quad_perm:[2,3,0,1] row_mask:0xf bank_mask:0xf bound_ctrl:1
	v_add_f32_dpp v66, v67, v67 quad_perm:[2,3,0,1] row_mask:0xf bank_mask:0xf bound_ctrl:1
	v_pk_fma_f32 v[12:13], v[36:37], v[16:17], v[12:13] op_sel_hi:[0,1,1]
	v_add_f32_dpp v35, v34, v34 row_half_mirror row_mask:0xf bank_mask:0xf bound_ctrl:1
	v_add_f32_dpp v67, v66, v66 row_half_mirror row_mask:0xf bank_mask:0xf bound_ctrl:1
	v_pk_fma_f32 v[14:15], v[36:37], v[18:19], v[14:15] op_sel_hi:[0,1,1]
	v_add_f32_dpp v90, v35, v35 row_mirror row_mask:0xf bank_mask:0xf bound_ctrl:1
	v_add_f32_dpp v66, v67, v67 row_mirror row_mask:0xf bank_mask:0xf bound_ctrl:1
	ds_write_b32 v37, v66 offset:43712
	ds_read_b128 v[64:67], v91 offset:18240
	v_pk_fma_f32 v[20:21], v[90:91], v[24:25], v[12:13] op_sel_hi:[0,1,1] neg_lo:[1,0,0] neg_hi:[1,0,0]
	v_pk_fma_f32 v[22:23], v[90:91], v[26:27], v[14:15] op_sel_hi:[0,1,1] neg_lo:[1,0,0] neg_hi:[1,0,0]
	ds_read_b128 v[12:15], v91 offset:18816
	ds_read_b128 v[24:27], v91 offset:19328
	ds_read_b128 v[16:19], v91 offset:19072
	ds_read_b128 v[32:35], v91 offset:19840
	ds_read_b32 v36, v92 offset:20096
	s_waitcnt lgkmcnt(7)
	v_pk_mul_f32 v[94:95], v[20:21], v[94:95]
	v_pk_mul_f32 v[28:29], v[20:21], v[28:29]
	v_pk_fma_f32 v[94:95], v[22:23], v[96:97], v[94:95]
	v_pk_fma_f32 v[28:29], v[22:23], v[30:31], v[28:29]
	v_add_f32_e32 v96, v94, v95
	v_add_f32_e32 v30, v28, v29
	v_pk_fma_f32 v[40:41], v[20:21], v[40:41], v[20:21] neg_lo:[1,0,0] neg_hi:[1,0,0]
	v_add_f32_dpp v97, v96, v96 quad_perm:[1,0,3,2] row_mask:0xf bank_mask:0xf bound_ctrl:1
	v_add_f32_dpp v31, v30, v30 quad_perm:[1,0,3,2] row_mask:0xf bank_mask:0xf bound_ctrl:1
	v_pk_fma_f32 v[42:43], v[22:23], v[42:43], v[22:23] neg_lo:[1,0,0] neg_hi:[1,0,0]
	v_add_f32_dpp v96, v97, v97 quad_perm:[2,3,0,1] row_mask:0xf bank_mask:0xf bound_ctrl:1
	v_add_f32_dpp v30, v31, v31 quad_perm:[2,3,0,1] row_mask:0xf bank_mask:0xf bound_ctrl:1
	v_pk_fma_f32 v[40:41], v[38:39], v[44:45], v[40:41] op_sel_hi:[0,1,1]
	v_add_f32_dpp v97, v96, v96 row_half_mirror row_mask:0xf bank_mask:0xf bound_ctrl:1
	v_add_f32_dpp v31, v30, v30 row_half_mirror row_mask:0xf bank_mask:0xf bound_ctrl:1
	v_pk_fma_f32 v[42:43], v[38:39], v[46:47], v[42:43] op_sel_hi:[0,1,1]
	v_add_f32_dpp v90, v97, v97 row_mirror row_mask:0xf bank_mask:0xf bound_ctrl:1
	v_add_f32_dpp v30, v31, v31 row_mirror row_mask:0xf bank_mask:0xf bound_ctrl:1
	ds_write_b32 v37, v30 offset:43776
	ds_read_b128 v[28:31], v91 offset:19584
	v_pk_fma_f32 v[20:21], v[90:91], v[60:61], v[40:41] op_sel_hi:[0,1,1] neg_lo:[1,0,0] neg_hi:[1,0,0]
	v_pk_fma_f32 v[22:23], v[90:91], v[62:63], v[42:43] op_sel_hi:[0,1,1] neg_lo:[1,0,0] neg_hi:[1,0,0]
	ds_read_b128 v[40:43], v91 offset:20160
	ds_read_b128 v[60:63], v91 offset:20672
	ds_read_b128 v[44:47], v91 offset:20416
	ds_read_b128 v[94:97], v91 offset:21184
	ds_read_b32 v38, v92 offset:21440
	s_waitcnt lgkmcnt(7)
	v_pk_mul_f32 v[32:33], v[20:21], v[32:33]
	v_pk_mul_f32 v[64:65], v[20:21], v[64:65]
	v_pk_fma_f32 v[32:33], v[22:23], v[34:35], v[32:33]
	v_pk_fma_f32 v[64:65], v[22:23], v[66:67], v[64:65]
	v_add_f32_e32 v34, v32, v33
	v_add_f32_e32 v66, v64, v65
	v_pk_fma_f32 v[12:13], v[20:21], v[12:13], v[20:21] neg_lo:[1,0,0] neg_hi:[1,0,0]
	v_add_f32_dpp v35, v34, v34 quad_perm:[1,0,3,2] row_mask:0xf bank_mask:0xf bound_ctrl:1
	v_add_f32_dpp v67, v66, v66 quad_perm:[1,0,3,2] row_mask:0xf bank_mask:0xf bound_ctrl:1
	v_pk_fma_f32 v[14:15], v[22:23], v[14:15], v[22:23] neg_lo:[1,0,0] neg_hi:[1,0,0]
	v_add_f32_dpp v34, v35, v35 quad_perm:[2,3,0,1] row_mask:0xf bank_mask:0xf bound_ctrl:1
	v_add_f32_dpp v66, v67, v67 quad_perm:[2,3,0,1] row_mask:0xf bank_mask:0xf bound_ctrl:1
	v_pk_fma_f32 v[12:13], v[36:37], v[16:17], v[12:13] op_sel_hi:[0,1,1]
	v_add_f32_dpp v35, v34, v34 row_half_mirror row_mask:0xf bank_mask:0xf bound_ctrl:1
	v_add_f32_dpp v67, v66, v66 row_half_mirror row_mask:0xf bank_mask:0xf bound_ctrl:1
	v_pk_fma_f32 v[14:15], v[36:37], v[18:19], v[14:15] op_sel_hi:[0,1,1]
	v_add_f32_dpp v90, v35, v35 row_mirror row_mask:0xf bank_mask:0xf bound_ctrl:1
	v_add_f32_dpp v66, v67, v67 row_mirror row_mask:0xf bank_mask:0xf bound_ctrl:1
	ds_write_b32 v37, v66 offset:43840
	ds_read_b128 v[64:67], v91 offset:20928
	v_pk_fma_f32 v[20:21], v[90:91], v[24:25], v[12:13] op_sel_hi:[0,1,1] neg_lo:[1,0,0] neg_hi:[1,0,0]
	v_pk_fma_f32 v[22:23], v[90:91], v[26:27], v[14:15] op_sel_hi:[0,1,1] neg_lo:[1,0,0] neg_hi:[1,0,0]
	s_waitcnt lgkmcnt(2)
; #define DPP_ADD(v, ctrl) ((v) + __builtin_bit_cast(float, __builtin_amdgcn_update_dpp(0, __builtin_bit_cast(int, (v)), (ctrl), 0xf, 0xf, true)))
; __device__ __forceinline__ void rwkv_scan_unit(const Params& p, int unit, char* smem) {
;     ...
;         for (int u = 0; u < SCH; ++u) {
;             f32x4 ne = e4, nkd = kd4, nka = ka4, nr = r4, nkk = kk4; float nv = vv;
;             if (u + 1 < SCH) { const char* q = lb + (u + 1) * STEPB;
;                 ne = *(const f32x4*)(q); nkd = *(const f32x4*)(q + 256); nka = *(const f32x4*)(q + 512); nr = *(const f32x4*)(q + 768); nkk = *(const f32x4*)(q + 1024);
;                 nv = *(const float*)(vb + (u + 1) * STEPB); }
;             const f32x2 v2 = {vv, vv}, c2 = {c, c};
;             const f32x2 tA = __builtin_elementwise_fma(v2, (f32x2){kd4[0], kd4[1]}, __builtin_elementwise_fma(-sA, (f32x2){e4[0], e4[1]}, sA));
;             const f32x2 tB = __builtin_elementwise_fma(v2, (f32x2){kd4[2], kd4[3]}, __builtin_elementwise_fma(-sB, (f32x2){e4[2], e4[3]}, sB));
;             sA = __builtin_elementwise_fma(-c2, (f32x2){ka4[0], ka4[1]}, tA);
;             sB = __builtin_elementwise_fma(-c2, (f32x2){ka4[2], ka4[3]}, tB);
;             const f32x2 yv = __builtin_elementwise_fma(sB, (f32x2){r4[2], r4[3]}, sA * (f32x2){r4[0], r4[1]});
;             float y = yv[0] + yv[1];
;             if (u + 1 < SCH) {
;                 const f32x2 cv = __builtin_elementwise_fma(sB, (f32x2){nkk[2], nkk[3]}, sA * (f32x2){nkk[0], nkk[1]});
;                 float cn = cv[0] + cv[1];
;                 cn = DPP_ADD(cn, 0xB1);  y = DPP_ADD(y, 0xB1);
;                 cn = DPP_ADD(cn, 0x4E);  y = DPP_ADD(y, 0x4E);
;                 cn = DPP_ADD(cn, 0x141); y = DPP_ADD(y, 0x141);
;                 cn = DPP_ADD(cn, 0x140); y = DPP_ADD(y, 0x140);
;                 c = cn;
;             } else y = red16(y);
;             if (ks == 0) yl[u * 16] = y;
;             e4 = ne; kd4 = nkd; ka4 = nka; r4 = nr; kk4 = nkk; vv = nv;
;         }
;         s0 = sA[0]; s1 = sA[1]; s2 = sB[0]; s3 = sB[1];
;         __builtin_amdgcn_sched_barrier(0);
;         if (ci + 1 < NCH) { SC_LSTORE(((ci + 1) & 1) * STG) }
;         __syncthreads();
;         {
;             const int u = tid >> 4, r = tid & 15;
;             Yb[((size_t)b * TT + step_tok(ci * SCH + u, d)) * 1024 + r] = f2bf(*((const float*)(smem + YOFF + (ci & 1) * 1024) + u * 16 + r));
;         }
	v_pk_mul_f32 v[94:95], v[20:21], v[94:95]
	v_pk_mul_f32 v[28:29], v[20:21], v[28:29]
	v_pk_fma_f32 v[94:95], v[22:23], v[96:97], v[94:95]
	v_pk_fma_f32 v[28:29], v[22:23], v[30:31], v[28:29]
	v_add_f32_e32 v96, v94, v95
	v_add_f32_e32 v30, v28, v29
	v_pk_fma_f32 v[40:41], v[20:21], v[40:41], v[20:21] neg_lo:[1,0,0] neg_hi:[1,0,0]
	v_add_f32_dpp v97, v96, v96 quad_perm:[1,0,3,2] row_mask:0xf bank_mask:0xf bound_ctrl:1
	v_add_f32_dpp v31, v30, v30 quad_perm:[1,0,3,2] row_mask:0xf bank_mask:0xf bound_ctrl:1
	v_pk_fma_f32 v[42:43], v[22:23], v[42:43], v[22:23] neg_lo:[1,0,0] neg_hi:[1,0,0]
	v_add_f32_dpp v96, v97, v97 quad_perm:[2,3,0,1] row_mask:0xf bank_mask:0xf bound_ctrl:1
	v_add_f32_dpp v30, v31, v31 quad_perm:[2,3,0,1] row_mask:0xf bank_mask:0xf bound_ctrl:1
	v_pk_fma_f32 v[40:41], v[38:39], v[44:45], v[40:41] op_sel_hi:[0,1,1]
	v_add_f32_dpp v97, v96, v96 row_half_mirror row_mask:0xf bank_mask:0xf bound_ctrl:1
	v_add_f32_dpp v31, v30, v30 row_half_mirror row_mask:0xf bank_mask:0xf bound_ctrl:1
	v_pk_fma_f32 v[42:43], v[38:39], v[46:47], v[42:43] op_sel_hi:[0,1,1]
	v_add_f32_dpp v90, v97, v97 row_mirror row_mask:0xf bank_mask:0xf bound_ctrl:1
	v_add_f32_dpp v30, v31, v31 row_mirror row_mask:0xf bank_mask:0xf bound_ctrl:1
	ds_write_b32 v37, v30 offset:43904
	v_pk_fma_f32 v[20:21], v[90:91], v[60:61], v[40:41] op_sel_hi:[0,1,1] neg_lo:[1,0,0] neg_hi:[1,0,0]
	v_pk_fma_f32 v[22:23], v[90:91], v[62:63], v[42:43] op_sel_hi:[0,1,1] neg_lo:[1,0,0] neg_hi:[1,0,0]
	s_waitcnt lgkmcnt(1)
	v_pk_mul_f32 v[64:65], v[20:21], v[64:65]
	v_pk_fma_f32 v[64:65], v[22:23], v[66:67], v[64:65]
	s_nop 0
	v_add_f32_e32 v66, v64, v65
	s_nop 1
	v_add_f32_dpp v67, v66, v66 quad_perm:[1,0,3,2] row_mask:0xf bank_mask:0xf bound_ctrl:1
	s_nop 1
	v_add_f32_dpp v66, v67, v67 quad_perm:[2,3,0,1] row_mask:0xf bank_mask:0xf bound_ctrl:1
	s_nop 1
	v_add_f32_dpp v67, v66, v66 row_half_mirror row_mask:0xf bank_mask:0xf bound_ctrl:1
	s_nop 1
	v_add_f32_dpp v66, v67, v67 row_mirror row_mask:0xf bank_mask:0xf bound_ctrl:1
	ds_write_b32 v37, v66 offset:43968
	s_bitcmp1_b32 s64, 0
	s_cselect_b32 s0, 0x5400, 0
	s_waitcnt vmcnt(13)
	v_add3_u32 v16, s0, v74, v75
	v_cvt_f32_f16_sdwa v13, v0 dst_sel:DWORD dst_unused:UNUSED_PAD src0_sel:WORD_1
	v_cvt_f32_f16_e32 v12, v0
	v_cvt_f32_f16_sdwa v15, v1 dst_sel:DWORD dst_unused:UNUSED_PAD src0_sel:WORD_1
	v_cvt_f32_f16_e32 v14, v1
	ds_write_b128 v16, v[12:15]
	v_cvt_f32_f16_sdwa v13, v2 dst_sel:DWORD dst_unused:UNUSED_PAD src0_sel:WORD_1
	v_cvt_f32_f16_e32 v12, v2
	v_cvt_f32_f16_sdwa v15, v3 dst_sel:DWORD dst_unused:UNUSED_PAD src0_sel:WORD_1
	v_cvt_f32_f16_e32 v14, v3
	ds_write_b128 v16, v[12:15] offset:16
	v_add3_u32 v16, s0, v76, v77
	v_cvt_f32_f16_sdwa v13, v4 dst_sel:DWORD dst_unused:UNUSED_PAD src0_sel:WORD_1
	v_cvt_f32_f16_e32 v12, v4
	v_cvt_f32_f16_sdwa v15, v5 dst_sel:DWORD dst_unused:UNUSED_PAD src0_sel:WORD_1
	v_cvt_f32_f16_e32 v14, v5
	ds_write_b128 v16, v[12:15]
	v_cvt_f32_f16_sdwa v13, v6 dst_sel:DWORD dst_unused:UNUSED_PAD src0_sel:WORD_1
	v_cvt_f32_f16_e32 v12, v6
	v_cvt_f32_f16_sdwa v15, v7 dst_sel:DWORD dst_unused:UNUSED_PAD src0_sel:WORD_1
	v_cvt_f32_f16_e32 v14, v7
	ds_write_b128 v16, v[12:15] offset:16
	v_add3_u32 v16, s0, v78, v79
	v_cvt_f32_f16_sdwa v13, v8 dst_sel:DWORD dst_unused:UNUSED_PAD src0_sel:WORD_1
	v_cvt_f32_f16_e32 v12, v8
	v_cvt_f32_f16_sdwa v15, v9 dst_sel:DWORD dst_unused:UNUSED_PAD src0_sel:WORD_1
	v_cvt_f32_f16_e32 v14, v9
	ds_write_b128 v16, v[12:15]
	v_cvt_f32_f16_sdwa v13, v10 dst_sel:DWORD dst_unused:UNUSED_PAD src0_sel:WORD_1
	v_cvt_f32_f16_e32 v12, v10
	v_cvt_f32_f16_sdwa v15, v11 dst_sel:DWORD dst_unused:UNUSED_PAD src0_sel:WORD_1
	v_cvt_f32_f16_e32 v14, v11
	ds_write_b128 v16, v[12:15] offset:16
.Lsc_p0_flush:
	v_lshlrev_b32_e32 v246, 2, v73
	v_add3_u32 v246, s52, v89, v246
	s_waitcnt lgkmcnt(0)
	s_barrier
	ds_read_b32 v246, v246 offset:43008
	v_add_u32_e32 v245, s55, v71
	v_cmp_lt_i32_e32 vcc, s2, v245
	s_add_i32 s55, s55, 16
	v_cndmask_b32_e32 v244, v196, v197, vcc
	v_add_u32_e32 v244, v244, v82
	v_cndmask_b32_e64 v244, v244, v245, s[44:45]
	v_ashrrev_i32_e32 v245, 31, v244
	v_lshl_add_u64 v[244:245], v[244:245], 0, s[88:89]
	v_lshlrev_b64 v[244:245], 11, v[244:245]
	s_add_i32 s64, s64, 1
	v_lshl_add_u64 v[244:245], v[48:49], 0, v[244:245]
	v_add_u32_e32 v82, -16, v82
	s_mov_b32 s100, 1
	s_cmpk_lg_i32 s55, 0x1100

; __device__ __forceinline__ void rwkv_scan_unit(const Params& p, int unit, char* smem) {
;     ...
;         const char* lb = smem + st + ks * 16;
;         const char* vb = smem + st + 1280 + rl * 4;
;         float* yl = (float*)(smem + YOFF + (ci & 1) * 1024) + rl;
;         f32x4 e4 = *(const f32x4*)(lb), kd4 = *(const f32x4*)(lb + 256), ka4 = *(const f32x4*)(lb + 512), r4 = *(const f32x4*)(lb + 768), kk4 = *(const f32x4*)(lb + 1024);
;         float vv = *(const float*)vb;
;         f32x2 sA = {s0, s1}, sB = {s2, s3};
;         float c;
;         { const f32x2 cv = sA * (f32x2){kk4[0], kk4[1]} + sB * (f32x2){kk4[2], kk4[3]}; c = red16(cv[0] + cv[1]); }
; #pragma unroll
;         for (int u = 0; u < SCH; ++u) {
;             f32x4 ne = e4, nkd = kd4, nka = ka4, nr = r4, nkk = kk4; float nv = vv;
;             if (u + 1 < SCH) { const char* q = lb + (u + 1) * STEPB;
;                 ne = *(const f32x4*)(q); nkd = *(const f32x4*)(q + 256); nka = *(const f32x4*)(q + 512); nr = *(const f32x4*)(q + 768); nkk = *(const f32x4*)(q + 1024);
;                 nv = *(const float*)(vb + (u + 1) * STEPB); }
;             const f32x2 v2 = {vv, vv}, c2 = {c, c};
;             const f32x2 tA = __builtin_elementwise_fma(v2, (f32x2){kd4[0], kd4[1]}, __builtin_elementwise_fma(-sA, (f32x2){e4[0], e4[1]}, sA));
;             const f32x2 tB = __builtin_elementwise_fma(v2, (f32x2){kd4[2], kd4[3]}, __builtin_elementwise_fma(-sB, (f32x2){e4[2], e4[3]}, sB));
;             sA = __builtin_elementwise_fma(-c2, (f32x2){ka4[0], ka4[1]}, tA);
;             sB = __builtin_elementwise_fma(-c2, (f32x2){ka4[2], ka4[3]}, tB);
;             const f32x2 yv = __builtin_elementwise_fma(sB, (f32x2){r4[2], r4[3]}, sA * (f32x2){r4[0], r4[1]});
;             float y = yv[0] + yv[1];
;             if (u + 1 < SCH) {
;                 const f32x2 cv = __builtin_elementwise_fma(sB, (f32x2){nkk[2], nkk[3]}, sA * (f32x2){nkk[0], nkk[1]});
;                 float cn = cv[0] + cv[1];
;                 cn = DPP_ADD(cn, 0xB1);  y = DPP_ADD(y, 0xB1);
;                 cn = DPP_ADD(cn, 0x4E);  y = DPP_ADD(y, 0x4E);
;                 cn = DPP_ADD(cn, 0x141); y = DPP_ADD(y, 0x141);
;                 cn = DPP_ADD(cn, 0x140); y = DPP_ADD(y, 0x140);
;                 c = cn;
;             } else y = red16(y);
;             if (ks == 0) yl[u * 16] = y;
.Lsc_p1_body:
	s_add_i32 s30, s64, -1
	s_and_b32 s30, s30, 1
	s_mul_i32 s52, s30, 0x5400
	v_or_b32_e32 v91, s52, v80
	v_add_u32_e32 v92, s52, v81
	ds_read_b128 v[32:35], v91 offset:1024
	ds_read_b128 v[12:15], v91 offset:0
	ds_read_b128 v[16:19], v91 offset:256
	ds_read_b32 v36, v92 offset:1280
	ds_read_b128 v[24:27], v91 offset:512
	ds_read_b128 v[28:31], v91 offset:768
	ds_read_b128 v[40:43], v91 offset:1344
	ds_read_b128 v[60:63], v91 offset:1856
	ds_read_b128 v[44:47], v91 offset:1600
	ds_read_b128 v[94:97], v91 offset:2368
	ds_read_b32 v38, v92 offset:2624
	ds_read_b128 v[64:67], v91 offset:2112
	s_waitcnt lgkmcnt(12)
	v_bfe_u32 v247, v246, 16, 1
	s_movk_i32 s0, 0x7fff
	v_add3_u32 v247, v246, v247, s0
	global_store_short_d16_hi v[244:245], v247, off
	s_lshl_b32 s52, s30, 10
	v_lshl_add_u32 v37, v72, 2, s52
	v_lshlrev_b32_e32 v90, 2, v109
	v_add_u32_e32 v90, 0x800, v90
	v_cndmask_b32_e64 v37, v90, v37, s[50:51]
	s_waitcnt lgkmcnt(11)
	v_pk_mul_f32 v[32:33], v[20:21], v[32:33]
	s_waitcnt lgkmcnt(10)
	v_pk_fma_f32 v[12:13], v[20:21], v[12:13], v[20:21] neg_lo:[1,0,0] neg_hi:[1,0,0]
	v_pk_fma_f32 v[32:33], v[22:23], v[34:35], v[32:33]
	v_pk_fma_f32 v[14:15], v[22:23], v[14:15], v[22:23] neg_lo:[1,0,0] neg_hi:[1,0,0]
	v_add_f32_e32 v34, v32, v33
	s_waitcnt lgkmcnt(8)
	v_pk_fma_f32 v[12:13], v[36:37], v[16:17], v[12:13] op_sel_hi:[0,1,1]
	v_pk_fma_f32 v[14:15], v[36:37], v[18:19], v[14:15] op_sel_hi:[0,1,1]
	v_add_f32_dpp v35, v34, v34 quad_perm:[1,0,3,2] row_mask:0xf bank_mask:0xf bound_ctrl:1
	s_nop 1
	v_add_f32_dpp v34, v35, v35 quad_perm:[2,3,0,1] row_mask:0xf bank_mask:0xf bound_ctrl:1
	s_nop 1
	v_add_f32_dpp v35, v34, v34 row_half_mirror row_mask:0xf bank_mask:0xf bound_ctrl:1
	s_nop 1
	v_add_f32_dpp v90, v35, v35 row_mirror row_mask:0xf bank_mask:0xf bound_ctrl:1
	ds_read_b128 v[16:19], v91 offset:2944
	ds_read_b128 v[32:35], v91 offset:3712
	ds_read_b32 v36, v92 offset:3968
	s_waitcnt lgkmcnt(10)
	v_pk_fma_f32 v[20:21], v[90:91], v[24:25], v[12:13] op_sel_hi:[0,1,1] neg_lo:[1,0,0] neg_hi:[1,0,0]
	v_pk_fma_f32 v[22:23], v[90:91], v[26:27], v[14:15] op_sel_hi:[0,1,1] neg_lo:[1,0,0] neg_hi:[1,0,0]
	ds_read_b128 v[12:15], v91 offset:2688
	ds_read_b128 v[24:27], v91 offset:3200
	s_waitcnt lgkmcnt(7)
	v_pk_mul_f32 v[94:95], v[20:21], v[94:95]
	v_pk_mul_f32 v[28:29], v[20:21], v[28:29]
	v_pk_fma_f32 v[94:95], v[22:23], v[96:97], v[94:95]
	v_pk_fma_f32 v[28:29], v[22:23], v[30:31], v[28:29]
	v_add_f32_e32 v96, v94, v95
	v_add_f32_e32 v30, v28, v29
	v_pk_fma_f32 v[40:41], v[20:21], v[40:41], v[20:21] neg_lo:[1,0,0] neg_hi:[1,0,0]
	v_add_f32_dpp v97, v96, v96 quad_perm:[1,0,3,2] row_mask:0xf bank_mask:0xf bound_ctrl:1
	v_add_f32_dpp v31, v30, v30 quad_perm:[1,0,3,2] row_mask:0xf bank_mask:0xf bound_ctrl:1
	v_pk_fma_f32 v[42:43], v[22:23], v[42:43], v[22:23] neg_lo:[1,0,0] neg_hi:[1,0,0]
	v_add_f32_dpp v96, v97, v97 quad_perm:[2,3,0,1] row_mask:0xf bank_mask:0xf bound_ctrl:1
	v_add_f32_dpp v30, v31, v31 quad_perm:[2,3,0,1] row_mask:0xf bank_mask:0xf bound_ctrl:1
	s_waitcnt lgkmcnt(6)
	v_pk_fma_f32 v[40:41], v[38:39], v[44:45], v[40:41] op_sel_hi:[0,1,1]
	v_add_f32_dpp v97, v96, v96 row_half_mirror row_mask:0xf bank_mask:0xf bound_ctrl:1
	v_add_f32_dpp v31, v30, v30 row_half_mirror row_mask:0xf bank_mask:0xf bound_ctrl:1
	v_pk_fma_f32 v[42:43], v[38:39], v[46:47], v[42:43] op_sel_hi:[0,1,1]
	v_add_f32_dpp v90, v97, v97 row_mirror row_mask:0xf bank_mask:0xf bound_ctrl:1
	v_add_f32_dpp v30, v31, v31 row_mirror row_mask:0xf bank_mask:0xf bound_ctrl:1
	ds_write_b32 v37, v30 offset:43008
	ds_read_b128 v[28:31], v91 offset:3456
	v_pk_fma_f32 v[20:21], v[90:91], v[60:61], v[40:41] op_sel_hi:[0,1,1] neg_lo:[1,0,0] neg_hi:[1,0,0]
	v_pk_fma_f32 v[22:23], v[90:91], v[62:63], v[42:43] op_sel_hi:[0,1,1] neg_lo:[1,0,0] neg_hi:[1,0,0]
	ds_read_b128 v[40:43], v91 offset:4032
	ds_read_b128 v[60:63], v91 offset:4544
	ds_read_b128 v[44:47], v91 offset:4288
	ds_read_b128 v[94:97], v91 offset:5056
	ds_read_b32 v38, v92 offset:5312
	s_waitcnt lgkmcnt(8)
	v_pk_mul_f32 v[32:33], v[20:21], v[32:33]
	v_pk_mul_f32 v[64:65], v[20:21], v[64:65]
	v_pk_fma_f32 v[32:33], v[22:23], v[34:35], v[32:33]
	v_pk_fma_f32 v[64:65], v[22:23], v[66:67], v[64:65]
	v_add_f32_e32 v34, v32, v33
	v_add_f32_e32 v66, v64, v65
	v_pk_fma_f32 v[12:13], v[20:21], v[12:13], v[20:21] neg_lo:[1,0,0] neg_hi:[1,0,0]
	v_add_f32_dpp v35, v34, v34 quad_perm:[1,0,3,2] row_mask:0xf bank_mask:0xf bound_ctrl:1
	v_add_f32_dpp v67, v66, v66 quad_perm:[1,0,3,2] row_mask:0xf bank_mask:0xf bound_ctrl:1
	v_pk_fma_f32 v[14:15], v[22:23], v[14:15], v[22:23] neg_lo:[1,0,0] neg_hi:[1,0,0]
	v_add_f32_dpp v34, v35, v35 quad_perm:[2,3,0,1] row_mask:0xf bank_mask:0xf bound_ctrl:1
	v_add_f32_dpp v66, v67, v67 quad_perm:[2,3,0,1] row_mask:0xf bank_mask:0xf bound_ctrl:1
	v_pk_fma_f32 v[12:13], v[36:37], v[16:17], v[12:13] op_sel_hi:[0,1,1]
	v_add_f32_dpp v35, v34, v34 row_half_mirror row_mask:0xf bank_mask:0xf bound_ctrl:1
	v_add_f32_dpp v67, v66, v66 row_half_mirror row_mask:0xf bank_mask:0xf bound_ctrl:1
	v_pk_fma_f32 v[14:15], v[36:37], v[18:19], v[14:15] op_sel_hi:[0,1,1]
	v_add_f32_dpp v90, v35, v35 row_mirror row_mask:0xf bank_mask:0xf bound_ctrl:1
	v_add_f32_dpp v66, v67, v67 row_mirror row_mask:0xf bank_mask:0xf bound_ctrl:1
	ds_write_b32 v37, v66 offset:43072
	ds_read_b128 v[64:67], v91 offset:4800
	s_waitcnt lgkmcnt(9)
	v_pk_fma_f32 v[20:21], v[90:91], v[24:25], v[12:13] op_sel_hi:[0,1,1] neg_lo:[1,0,0] neg_hi:[1,0,0]
	v_pk_fma_f32 v[22:23], v[90:91], v[26:27], v[14:15] op_sel_hi:[0,1,1] neg_lo:[1,0,0] neg_hi:[1,0,0]
	ds_read_b128 v[12:15], v91 offset:5376
	ds_read_b128 v[24:27], v91 offset:5888
	ds_read_b128 v[16:19], v91 offset:5632
	ds_read_b128 v[32:35], v91 offset:6400
	ds_read_b32 v36, v92 offset:6656
	s_waitcnt lgkmcnt(7)
; #define DPP_ADD(v, ctrl) ((v) + __builtin_bit_cast(float, __builtin_amdgcn_update_dpp(0, __builtin_bit_cast(int, (v)), (ctrl), 0xf, 0xf, true)))
; __device__ __forceinline__ void rwkv_scan_unit(const Params& p, int unit, char* smem) {
;     ...
;         for (int u = 0; u < SCH; ++u) {
;             f32x4 ne = e4, nkd = kd4, nka = ka4, nr = r4, nkk = kk4; float nv = vv;
;             if (u + 1 < SCH) { const char* q = lb + (u + 1) * STEPB;
;                 ne = *(const f32x4*)(q); nkd = *(const f32x4*)(q + 256); nka = *(const f32x4*)(q + 512); nr = *(const f32x4*)(q + 768); nkk = *(const f32x4*)(q + 1024);
;                 nv = *(const float*)(vb + (u + 1) * STEPB); }
;             const f32x2 v2 = {vv, vv}, c2 = {c, c};
;             const f32x2 tA = __builtin_elementwise_fma(v2, (f32x2){kd4[0], kd4[1]}, __builtin_elementwise_fma(-sA, (f32x2){e4[0], e4[1]}, sA));
;             const f32x2 tB = __builtin_elementwise_fma(v2, (f32x2){kd4[2], kd4[3]}, __builtin_elementwise_fma(-sB, (f32x2){e4[2], e4[3]}, sB));
;             sA = __builtin_elementwise_fma(-c2, (f32x2){ka4[0], ka4[1]}, tA);
;             sB = __builtin_elementwise_fma(-c2, (f32x2){ka4[2], ka4[3]}, tB);
;             const f32x2 yv = __builtin_elementwise_fma(sB, (f32x2){r4[2], r4[3]}, sA * (f32x2){r4[0], r4[1]});
;             float y = yv[0] + yv[1];
;             if (u + 1 < SCH) {
;                 const f32x2 cv = __builtin_elementwise_fma(sB, (f32x2){nkk[2], nkk[3]}, sA * (f32x2){nkk[0], nkk[1]});
;                 float cn = cv[0] + cv[1];
;                 cn = DPP_ADD(cn, 0xB1);  y = DPP_ADD(y, 0xB1);
;                 cn = DPP_ADD(cn, 0x4E);  y = DPP_ADD(y, 0x4E);
;                 cn = DPP_ADD(cn, 0x141); y = DPP_ADD(y, 0x141);
;                 cn = DPP_ADD(cn, 0x140); y = DPP_ADD(y, 0x140);
;                 c = cn;
;             } else y = red16(y);
;             if (ks == 0) yl[u * 16] = y;
;             e4 = ne; kd4 = nkd; ka4 = nka; r4 = nr; kk4 = nkk; vv = nv;
;         }
	v_pk_mul_f32 v[94:95], v[20:21], v[94:95]
	v_pk_mul_f32 v[28:29], v[20:21], v[28:29]
	v_pk_fma_f32 v[94:95], v[22:23], v[96:97], v[94:95]
	v_pk_fma_f32 v[28:29], v[22:23], v[30:31], v[28:29]
	v_add_f32_e32 v96, v94, v95
	v_add_f32_e32 v30, v28, v29
	v_pk_fma_f32 v[40:41], v[20:21], v[40:41], v[20:21] neg_lo:[1,0,0] neg_hi:[1,0,0]
	v_add_f32_dpp v97, v96, v96 quad_perm:[1,0,3,2] row_mask:0xf bank_mask:0xf bound_ctrl:1
	v_add_f32_dpp v31, v30, v30 quad_perm:[1,0,3,2] row_mask:0xf bank_mask:0xf bound_ctrl:1
	v_pk_fma_f32 v[42:43], v[22:23], v[42:43], v[22:23] neg_lo:[1,0,0] neg_hi:[1,0,0]
	v_add_f32_dpp v96, v97, v97 quad_perm:[2,3,0,1] row_mask:0xf bank_mask:0xf bound_ctrl:1
	v_add_f32_dpp v30, v31, v31 quad_perm:[2,3,0,1] row_mask:0xf bank_mask:0xf bound_ctrl:1
	v_pk_fma_f32 v[40:41], v[38:39], v[44:45], v[40:41] op_sel_hi:[0,1,1]
	v_add_f32_dpp v97, v96, v96 row_half_mirror row_mask:0xf bank_mask:0xf bound_ctrl:1
	v_add_f32_dpp v31, v30, v30 row_half_mirror row_mask:0xf bank_mask:0xf bound_ctrl:1
	v_pk_fma_f32 v[42:43], v[38:39], v[46:47], v[42:43] op_sel_hi:[0,1,1]
	v_add_f32_dpp v90, v97, v97 row_mirror row_mask:0xf bank_mask:0xf bound_ctrl:1
	v_add_f32_dpp v30, v31, v31 row_mirror row_mask:0xf bank_mask:0xf bound_ctrl:1
	ds_write_b32 v37, v30 offset:43136
	ds_read_b128 v[28:31], v91 offset:6144
	v_pk_fma_f32 v[20:21], v[90:91], v[60:61], v[40:41] op_sel_hi:[0,1,1] neg_lo:[1,0,0] neg_hi:[1,0,0]
	v_pk_fma_f32 v[22:23], v[90:91], v[62:63], v[42:43] op_sel_hi:[0,1,1] neg_lo:[1,0,0] neg_hi:[1,0,0]
	ds_read_b128 v[40:43], v91 offset:6720
	ds_read_b128 v[60:63], v91 offset:7232
	ds_read_b128 v[44:47], v91 offset:6976
	ds_read_b128 v[94:97], v91 offset:7744
	ds_read_b32 v38, v92 offset:8000
	s_waitcnt lgkmcnt(7)
	v_pk_mul_f32 v[32:33], v[20:21], v[32:33]
	v_pk_mul_f32 v[64:65], v[20:21], v[64:65]
	v_pk_fma_f32 v[32:33], v[22:23], v[34:35], v[32:33]
	v_pk_fma_f32 v[64:65], v[22:23], v[66:67], v[64:65]
	v_add_f32_e32 v34, v32, v33
	v_add_f32_e32 v66, v64, v65
	v_pk_fma_f32 v[12:13], v[20:21], v[12:13], v[20:21] neg_lo:[1,0,0] neg_hi:[1,0,0]
	v_add_f32_dpp v35, v34, v34 quad_perm:[1,0,3,2] row_mask:0xf bank_mask:0xf bound_ctrl:1
	v_add_f32_dpp v67, v66, v66 quad_perm:[1,0,3,2] row_mask:0xf bank_mask:0xf bound_ctrl:1
	v_pk_fma_f32 v[14:15], v[22:23], v[14:15], v[22:23] neg_lo:[1,0,0] neg_hi:[1,0,0]
	v_add_f32_dpp v34, v35, v35 quad_perm:[2,3,0,1] row_mask:0xf bank_mask:0xf bound_ctrl:1
	v_add_f32_dpp v66, v67, v67 quad_perm:[2,3,0,1] row_mask:0xf bank_mask:0xf bound_ctrl:1
	v_pk_fma_f32 v[12:13], v[36:37], v[16:17], v[12:13] op_sel_hi:[0,1,1]
	v_add_f32_dpp v35, v34, v34 row_half_mirror row_mask:0xf bank_mask:0xf bound_ctrl:1
	v_add_f32_dpp v67, v66, v66 row_half_mirror row_mask:0xf bank_mask:0xf bound_ctrl:1
	v_pk_fma_f32 v[14:15], v[36:37], v[18:19], v[14:15] op_sel_hi:[0,1,1]
	v_add_f32_dpp v90, v35, v35 row_mirror row_mask:0xf bank_mask:0xf bound_ctrl:1
	v_add_f32_dpp v66, v67, v67 row_mirror row_mask:0xf bank_mask:0xf bound_ctrl:1
	ds_write_b32 v37, v66 offset:43200
	ds_read_b128 v[64:67], v91 offset:7488
	v_pk_fma_f32 v[20:21], v[90:91], v[24:25], v[12:13] op_sel_hi:[0,1,1] neg_lo:[1,0,0] neg_hi:[1,0,0]
	v_pk_fma_f32 v[22:23], v[90:91], v[26:27], v[14:15] op_sel_hi:[0,1,1] neg_lo:[1,0,0] neg_hi:[1,0,0]
	ds_read_b128 v[12:15], v91 offset:8064
	ds_read_b128 v[24:27], v91 offset:8576
	ds_read_b128 v[16:19], v91 offset:8320
	ds_read_b128 v[32:35], v91 offset:9088
	ds_read_b32 v36, v92 offset:9344
	s_waitcnt lgkmcnt(7)
	v_pk_mul_f32 v[94:95], v[20:21], v[94:95]
	v_pk_mul_f32 v[28:29], v[20:21], v[28:29]
	v_pk_fma_f32 v[94:95], v[22:23], v[96:97], v[94:95]
	v_pk_fma_f32 v[28:29], v[22:23], v[30:31], v[28:29]
	v_add_f32_e32 v96, v94, v95
	v_add_f32_e32 v30, v28, v29
	v_pk_fma_f32 v[40:41], v[20:21], v[40:41], v[20:21] neg_lo:[1,0,0] neg_hi:[1,0,0]
	v_add_f32_dpp v97, v96, v96 quad_perm:[1,0,3,2] row_mask:0xf bank_mask:0xf bound_ctrl:1
	v_add_f32_dpp v31, v30, v30 quad_perm:[1,0,3,2] row_mask:0xf bank_mask:0xf bound_ctrl:1
	v_pk_fma_f32 v[42:43], v[22:23], v[42:43], v[22:23] neg_lo:[1,0,0] neg_hi:[1,0,0]
	v_add_f32_dpp v96, v97, v97 quad_perm:[2,3,0,1] row_mask:0xf bank_mask:0xf bound_ctrl:1
	v_add_f32_dpp v30, v31, v31 quad_perm:[2,3,0,1] row_mask:0xf bank_mask:0xf bound_ctrl:1
	v_pk_fma_f32 v[40:41], v[38:39], v[44:45], v[40:41] op_sel_hi:[0,1,1]
	v_add_f32_dpp v97, v96, v96 row_half_mirror row_mask:0xf bank_mask:0xf bound_ctrl:1
	v_add_f32_dpp v31, v30, v30 row_half_mirror row_mask:0xf bank_mask:0xf bound_ctrl:1
	v_pk_fma_f32 v[42:43], v[38:39], v[46:47], v[42:43] op_sel_hi:[0,1,1]
	v_add_f32_dpp v90, v97, v97 row_mirror row_mask:0xf bank_mask:0xf bound_ctrl:1
	v_add_f32_dpp v30, v31, v31 row_mirror row_mask:0xf bank_mask:0xf bound_ctrl:1
	ds_write_b32 v37, v30 offset:43264
	ds_read_b128 v[28:31], v91 offset:8832
	v_pk_fma_f32 v[20:21], v[90:91], v[60:61], v[40:41] op_sel_hi:[0,1,1] neg_lo:[1,0,0] neg_hi:[1,0,0]
	v_pk_fma_f32 v[22:23], v[90:91], v[62:63], v[42:43] op_sel_hi:[0,1,1] neg_lo:[1,0,0] neg_hi:[1,0,0]
	ds_read_b128 v[40:43], v91 offset:9408
	ds_read_b128 v[60:63], v91 offset:9920
	ds_read_b128 v[44:47], v91 offset:9664
	ds_read_b128 v[94:97], v91 offset:10432
	ds_read_b32 v38, v92 offset:10688
	s_waitcnt lgkmcnt(7)
; #define DPP_ADD(v, ctrl) ((v) + __builtin_bit_cast(float, __builtin_amdgcn_update_dpp(0, __builtin_bit_cast(int, (v)), (ctrl), 0xf, 0xf, true)))
; __device__ __forceinline__ void rwkv_scan_unit(const Params& p, int unit, char* smem) {
;     ...
;         for (int u = 0; u < SCH; ++u) {
;             f32x4 ne = e4, nkd = kd4, nka = ka4, nr = r4, nkk = kk4; float nv = vv;
;             if (u + 1 < SCH) { const char* q = lb + (u + 1) * STEPB;
;                 ne = *(const f32x4*)(q); nkd = *(const f32x4*)(q + 256); nka = *(const f32x4*)(q + 512); nr = *(const f32x4*)(q + 768); nkk = *(const f32x4*)(q + 1024);
;                 nv = *(const float*)(vb + (u + 1) * STEPB); }
;             const f32x2 v2 = {vv, vv}, c2 = {c, c};
;             const f32x2 tA = __builtin_elementwise_fma(v2, (f32x2){kd4[0], kd4[1]}, __builtin_elementwise_fma(-sA, (f32x2){e4[0], e4[1]}, sA));
;             const f32x2 tB = __builtin_elementwise_fma(v2, (f32x2){kd4[2], kd4[3]}, __builtin_elementwise_fma(-sB, (f32x2){e4[2], e4[3]}, sB));
;             sA = __builtin_elementwise_fma(-c2, (f32x2){ka4[0], ka4[1]}, tA);
;             sB = __builtin_elementwise_fma(-c2, (f32x2){ka4[2], ka4[3]}, tB);
;             const f32x2 yv = __builtin_elementwise_fma(sB, (f32x2){r4[2], r4[3]}, sA * (f32x2){r4[0], r4[1]});
;             float y = yv[0] + yv[1];
;             if (u + 1 < SCH) {
;                 const f32x2 cv = __builtin_elementwise_fma(sB, (f32x2){nkk[2], nkk[3]}, sA * (f32x2){nkk[0], nkk[1]});
;                 float cn = cv[0] + cv[1];
;                 cn = DPP_ADD(cn, 0xB1);  y = DPP_ADD(y, 0xB1);
;                 cn = DPP_ADD(cn, 0x4E);  y = DPP_ADD(y, 0x4E);
;                 cn = DPP_ADD(cn, 0x141); y = DPP_ADD(y, 0x141);
;                 cn = DPP_ADD(cn, 0x140); y = DPP_ADD(y, 0x140);
;                 c = cn;
;             } else y = red16(y);
;             if (ks == 0) yl[u * 16] = y;
;             e4 = ne; kd4 = nkd; ka4 = nka; r4 = nr; kk4 = nkk; vv = nv;
;         }
	v_pk_mul_f32 v[32:33], v[20:21], v[32:33]
	v_pk_mul_f32 v[64:65], v[20:21], v[64:65]
	v_pk_fma_f32 v[32:33], v[22:23], v[34:35], v[32:33]
	v_pk_fma_f32 v[64:65], v[22:23], v[66:67], v[64:65]
	v_add_f32_e32 v34, v32, v33
	v_add_f32_e32 v66, v64, v65
	v_pk_fma_f32 v[12:13], v[20:21], v[12:13], v[20:21] neg_lo:[1,0,0] neg_hi:[1,0,0]
	v_add_f32_dpp v35, v34, v34 quad_perm:[1,0,3,2] row_mask:0xf bank_mask:0xf bound_ctrl:1
	v_add_f32_dpp v67, v66, v66 quad_perm:[1,0,3,2] row_mask:0xf bank_mask:0xf bound_ctrl:1
	v_pk_fma_f32 v[14:15], v[22:23], v[14:15], v[22:23] neg_lo:[1,0,0] neg_hi:[1,0,0]
	v_add_f32_dpp v34, v35, v35 quad_perm:[2,3,0,1] row_mask:0xf bank_mask:0xf bound_ctrl:1
	v_add_f32_dpp v66, v67, v67 quad_perm:[2,3,0,1] row_mask:0xf bank_mask:0xf bound_ctrl:1
	v_pk_fma_f32 v[12:13], v[36:37], v[16:17], v[12:13] op_sel_hi:[0,1,1]
	v_add_f32_dpp v35, v34, v34 row_half_mirror row_mask:0xf bank_mask:0xf bound_ctrl:1
	v_add_f32_dpp v67, v66, v66 row_half_mirror row_mask:0xf bank_mask:0xf bound_ctrl:1
	v_pk_fma_f32 v[14:15], v[36:37], v[18:19], v[14:15] op_sel_hi:[0,1,1]
	v_add_f32_dpp v90, v35, v35 row_mirror row_mask:0xf bank_mask:0xf bound_ctrl:1
	v_add_f32_dpp v66, v67, v67 row_mirror row_mask:0xf bank_mask:0xf bound_ctrl:1
	ds_write_b32 v37, v66 offset:43328
	ds_read_b128 v[64:67], v91 offset:10176
	v_pk_fma_f32 v[20:21], v[90:91], v[24:25], v[12:13] op_sel_hi:[0,1,1] neg_lo:[1,0,0] neg_hi:[1,0,0]
	v_pk_fma_f32 v[22:23], v[90:91], v[26:27], v[14:15] op_sel_hi:[0,1,1] neg_lo:[1,0,0] neg_hi:[1,0,0]
	ds_read_b128 v[12:15], v91 offset:10752
	ds_read_b128 v[24:27], v91 offset:11264
	ds_read_b128 v[16:19], v91 offset:11008
	ds_read_b128 v[32:35], v91 offset:11776
	ds_read_b32 v36, v92 offset:12032
	s_waitcnt lgkmcnt(7)
	v_pk_mul_f32 v[94:95], v[20:21], v[94:95]
	v_pk_mul_f32 v[28:29], v[20:21], v[28:29]
	v_pk_fma_f32 v[94:95], v[22:23], v[96:97], v[94:95]
	v_pk_fma_f32 v[28:29], v[22:23], v[30:31], v[28:29]
	v_add_f32_e32 v96, v94, v95
	v_add_f32_e32 v30, v28, v29
	v_pk_fma_f32 v[40:41], v[20:21], v[40:41], v[20:21] neg_lo:[1,0,0] neg_hi:[1,0,0]
	v_add_f32_dpp v97, v96, v96 quad_perm:[1,0,3,2] row_mask:0xf bank_mask:0xf bound_ctrl:1
	v_add_f32_dpp v31, v30, v30 quad_perm:[1,0,3,2] row_mask:0xf bank_mask:0xf bound_ctrl:1
	v_pk_fma_f32 v[42:43], v[22:23], v[42:43], v[22:23] neg_lo:[1,0,0] neg_hi:[1,0,0]
	v_add_f32_dpp v96, v97, v97 quad_perm:[2,3,0,1] row_mask:0xf bank_mask:0xf bound_ctrl:1
	v_add_f32_dpp v30, v31, v31 quad_perm:[2,3,0,1] row_mask:0xf bank_mask:0xf bound_ctrl:1
	v_pk_fma_f32 v[40:41], v[38:39], v[44:45], v[40:41] op_sel_hi:[0,1,1]
	v_add_f32_dpp v97, v96, v96 row_half_mirror row_mask:0xf bank_mask:0xf bound_ctrl:1
	v_add_f32_dpp v31, v30, v30 row_half_mirror row_mask:0xf bank_mask:0xf bound_ctrl:1
	v_pk_fma_f32 v[42:43], v[38:39], v[46:47], v[42:43] op_sel_hi:[0,1,1]
	v_add_f32_dpp v90, v97, v97 row_mirror row_mask:0xf bank_mask:0xf bound_ctrl:1
	v_add_f32_dpp v30, v31, v31 row_mirror row_mask:0xf bank_mask:0xf bound_ctrl:1
	ds_write_b32 v37, v30 offset:43392
	ds_read_b128 v[28:31], v91 offset:11520
	v_pk_fma_f32 v[20:21], v[90:91], v[60:61], v[40:41] op_sel_hi:[0,1,1] neg_lo:[1,0,0] neg_hi:[1,0,0]
	v_pk_fma_f32 v[22:23], v[90:91], v[62:63], v[42:43] op_sel_hi:[0,1,1] neg_lo:[1,0,0] neg_hi:[1,0,0]
	ds_read_b128 v[40:43], v91 offset:12096
	ds_read_b128 v[60:63], v91 offset:12608
	ds_read_b128 v[44:47], v91 offset:12352
	ds_read_b128 v[94:97], v91 offset:13120
	ds_read_b32 v38, v92 offset:13376
	s_waitcnt lgkmcnt(7)
	v_pk_mul_f32 v[32:33], v[20:21], v[32:33]
	v_pk_mul_f32 v[64:65], v[20:21], v[64:65]
	v_pk_fma_f32 v[32:33], v[22:23], v[34:35], v[32:33]
	v_pk_fma_f32 v[64:65], v[22:23], v[66:67], v[64:65]
	v_add_f32_e32 v34, v32, v33
	v_add_f32_e32 v66, v64, v65
	v_pk_fma_f32 v[12:13], v[20:21], v[12:13], v[20:21] neg_lo:[1,0,0] neg_hi:[1,0,0]
	v_add_f32_dpp v35, v34, v34 quad_perm:[1,0,3,2] row_mask:0xf bank_mask:0xf bound_ctrl:1
	v_add_f32_dpp v67, v66, v66 quad_perm:[1,0,3,2] row_mask:0xf bank_mask:0xf bound_ctrl:1
	v_pk_fma_f32 v[14:15], v[22:23], v[14:15], v[22:23] neg_lo:[1,0,0] neg_hi:[1,0,0]
	v_add_f32_dpp v34, v35, v35 quad_perm:[2,3,0,1] row_mask:0xf bank_mask:0xf bound_ctrl:1
	v_add_f32_dpp v66, v67, v67 quad_perm:[2,3,0,1] row_mask:0xf bank_mask:0xf bound_ctrl:1
	v_pk_fma_f32 v[12:13], v[36:37], v[16:17], v[12:13] op_sel_hi:[0,1,1]
	v_add_f32_dpp v35, v34, v34 row_half_mirror row_mask:0xf bank_mask:0xf bound_ctrl:1
	v_add_f32_dpp v67, v66, v66 row_half_mirror row_mask:0xf bank_mask:0xf bound_ctrl:1
	v_pk_fma_f32 v[14:15], v[36:37], v[18:19], v[14:15] op_sel_hi:[0,1,1]
	v_add_f32_dpp v90, v35, v35 row_mirror row_mask:0xf bank_mask:0xf bound_ctrl:1
	v_add_f32_dpp v66, v67, v67 row_mirror row_mask:0xf bank_mask:0xf bound_ctrl:1
	ds_write_b32 v37, v66 offset:43456
	ds_read_b128 v[64:67], v91 offset:12864
	v_pk_fma_f32 v[20:21], v[90:91], v[24:25], v[12:13] op_sel_hi:[0,1,1] neg_lo:[1,0,0] neg_hi:[1,0,0]
	v_pk_fma_f32 v[22:23], v[90:91], v[26:27], v[14:15] op_sel_hi:[0,1,1] neg_lo:[1,0,0] neg_hi:[1,0,0]
	ds_read_b128 v[12:15], v91 offset:13440
	ds_read_b128 v[24:27], v91 offset:13952
	ds_read_b128 v[16:19], v91 offset:13696
	ds_read_b128 v[32:35], v91 offset:14464
	ds_read_b32 v36, v92 offset:14720
	s_waitcnt lgkmcnt(7)
; #define DPP_ADD(v, ctrl) ((v) + __builtin_bit_cast(float, __builtin_amdgcn_update_dpp(0, __builtin_bit_cast(int, (v)), (ctrl), 0xf, 0xf, true)))
; __device__ __forceinline__ void rwkv_scan_unit(const Params& p, int unit, char* smem) {
;     ...
;         for (int u = 0; u < SCH; ++u) {
;             f32x4 ne = e4, nkd = kd4, nka = ka4, nr = r4, nkk = kk4; float nv = vv;
;             if (u + 1 < SCH) { const char* q = lb + (u + 1) * STEPB;
;                 ne = *(const f32x4*)(q); nkd = *(const f32x4*)(q + 256); nka = *(const f32x4*)(q + 512); nr = *(const f32x4*)(q + 768); nkk = *(const f32x4*)(q + 1024);
;                 nv = *(const float*)(vb + (u + 1) * STEPB); }
;             const f32x2 v2 = {vv, vv}, c2 = {c, c};
;             const f32x2 tA = __builtin_elementwise_fma(v2, (f32x2){kd4[0], kd4[1]}, __builtin_elementwise_fma(-sA, (f32x2){e4[0], e4[1]}, sA));
;             const f32x2 tB = __builtin_elementwise_fma(v2, (f32x2){kd4[2], kd4[3]}, __builtin_elementwise_fma(-sB, (f32x2){e4[2], e4[3]}, sB));
;             sA = __builtin_elementwise_fma(-c2, (f32x2){ka4[0], ka4[1]}, tA);
;             sB = __builtin_elementwise_fma(-c2, (f32x2){ka4[2], ka4[3]}, tB);
;             const f32x2 yv = __builtin_elementwise_fma(sB, (f32x2){r4[2], r4[3]}, sA * (f32x2){r4[0], r4[1]});
;             float y = yv[0] + yv[1];
;             if (u + 1 < SCH) {
;                 const f32x2 cv = __builtin_elementwise_fma(sB, (f32x2){nkk[2], nkk[3]}, sA * (f32x2){nkk[0], nkk[1]});
;                 float cn = cv[0] + cv[1];
;                 cn = DPP_ADD(cn, 0xB1);  y = DPP_ADD(y, 0xB1);
;                 cn = DPP_ADD(cn, 0x4E);  y = DPP_ADD(y, 0x4E);
;                 cn = DPP_ADD(cn, 0x141); y = DPP_ADD(y, 0x141);
;                 cn = DPP_ADD(cn, 0x140); y = DPP_ADD(y, 0x140);
;                 c = cn;
;             } else y = red16(y);
;             if (ks == 0) yl[u * 16] = y;
;             e4 = ne; kd4 = nkd; ka4 = nka; r4 = nr; kk4 = nkk; vv = nv;
;         }
	v_pk_mul_f32 v[94:95], v[20:21], v[94:95]
	v_pk_mul_f32 v[28:29], v[20:21], v[28:29]
	v_pk_fma_f32 v[94:95], v[22:23], v[96:97], v[94:95]
	v_pk_fma_f32 v[28:29], v[22:23], v[30:31], v[28:29]
	v_add_f32_e32 v96, v94, v95
	v_add_f32_e32 v30, v28, v29
	v_pk_fma_f32 v[40:41], v[20:21], v[40:41], v[20:21] neg_lo:[1,0,0] neg_hi:[1,0,0]
	v_add_f32_dpp v97, v96, v96 quad_perm:[1,0,3,2] row_mask:0xf bank_mask:0xf bound_ctrl:1
	v_add_f32_dpp v31, v30, v30 quad_perm:[1,0,3,2] row_mask:0xf bank_mask:0xf bound_ctrl:1
	v_pk_fma_f32 v[42:43], v[22:23], v[42:43], v[22:23] neg_lo:[1,0,0] neg_hi:[1,0,0]
	v_add_f32_dpp v96, v97, v97 quad_perm:[2,3,0,1] row_mask:0xf bank_mask:0xf bound_ctrl:1
	v_add_f32_dpp v30, v31, v31 quad_perm:[2,3,0,1] row_mask:0xf bank_mask:0xf bound_ctrl:1
	v_pk_fma_f32 v[40:41], v[38:39], v[44:45], v[40:41] op_sel_hi:[0,1,1]
	v_add_f32_dpp v97, v96, v96 row_half_mirror row_mask:0xf bank_mask:0xf bound_ctrl:1
	v_add_f32_dpp v31, v30, v30 row_half_mirror row_mask:0xf bank_mask:0xf bound_ctrl:1
	v_pk_fma_f32 v[42:43], v[38:39], v[46:47], v[42:43] op_sel_hi:[0,1,1]
	v_add_f32_dpp v90, v97, v97 row_mirror row_mask:0xf bank_mask:0xf bound_ctrl:1
	v_add_f32_dpp v30, v31, v31 row_mirror row_mask:0xf bank_mask:0xf bound_ctrl:1
	ds_write_b32 v37, v30 offset:43520
	ds_read_b128 v[28:31], v91 offset:14208
	v_pk_fma_f32 v[20:21], v[90:91], v[60:61], v[40:41] op_sel_hi:[0,1,1] neg_lo:[1,0,0] neg_hi:[1,0,0]
	v_pk_fma_f32 v[22:23], v[90:91], v[62:63], v[42:43] op_sel_hi:[0,1,1] neg_lo:[1,0,0] neg_hi:[1,0,0]
	ds_read_b128 v[40:43], v91 offset:14784
	ds_read_b128 v[60:63], v91 offset:15296
	ds_read_b128 v[44:47], v91 offset:15040
	ds_read_b128 v[94:97], v91 offset:15808
	ds_read_b32 v38, v92 offset:16064
	s_waitcnt lgkmcnt(7)
	v_pk_mul_f32 v[32:33], v[20:21], v[32:33]
	v_pk_mul_f32 v[64:65], v[20:21], v[64:65]
	v_pk_fma_f32 v[32:33], v[22:23], v[34:35], v[32:33]
	v_pk_fma_f32 v[64:65], v[22:23], v[66:67], v[64:65]
	v_add_f32_e32 v34, v32, v33
	v_add_f32_e32 v66, v64, v65
	v_pk_fma_f32 v[12:13], v[20:21], v[12:13], v[20:21] neg_lo:[1,0,0] neg_hi:[1,0,0]
	v_add_f32_dpp v35, v34, v34 quad_perm:[1,0,3,2] row_mask:0xf bank_mask:0xf bound_ctrl:1
	v_add_f32_dpp v67, v66, v66 quad_perm:[1,0,3,2] row_mask:0xf bank_mask:0xf bound_ctrl:1
	v_pk_fma_f32 v[14:15], v[22:23], v[14:15], v[22:23] neg_lo:[1,0,0] neg_hi:[1,0,0]
	v_add_f32_dpp v34, v35, v35 quad_perm:[2,3,0,1] row_mask:0xf bank_mask:0xf bound_ctrl:1
	v_add_f32_dpp v66, v67, v67 quad_perm:[2,3,0,1] row_mask:0xf bank_mask:0xf bound_ctrl:1
	v_pk_fma_f32 v[12:13], v[36:37], v[16:17], v[12:13] op_sel_hi:[0,1,1]
	v_add_f32_dpp v35, v34, v34 row_half_mirror row_mask:0xf bank_mask:0xf bound_ctrl:1
	v_add_f32_dpp v67, v66, v66 row_half_mirror row_mask:0xf bank_mask:0xf bound_ctrl:1
	v_pk_fma_f32 v[14:15], v[36:37], v[18:19], v[14:15] op_sel_hi:[0,1,1]
	v_add_f32_dpp v90, v35, v35 row_mirror row_mask:0xf bank_mask:0xf bound_ctrl:1
	v_add_f32_dpp v66, v67, v67 row_mirror row_mask:0xf bank_mask:0xf bound_ctrl:1
	ds_write_b32 v37, v66 offset:43584
	ds_read_b128 v[64:67], v91 offset:15552
	v_pk_fma_f32 v[20:21], v[90:91], v[24:25], v[12:13] op_sel_hi:[0,1,1] neg_lo:[1,0,0] neg_hi:[1,0,0]
	v_pk_fma_f32 v[22:23], v[90:91], v[26:27], v[14:15] op_sel_hi:[0,1,1] neg_lo:[1,0,0] neg_hi:[1,0,0]
	ds_read_b128 v[12:15], v91 offset:16128
	ds_read_b128 v[24:27], v91 offset:16640
	ds_read_b128 v[16:19], v91 offset:16384
	ds_read_b128 v[32:35], v91 offset:17152
	ds_read_b32 v36, v92 offset:17408
	s_waitcnt lgkmcnt(7)
	v_pk_mul_f32 v[94:95], v[20:21], v[94:95]
	v_pk_mul_f32 v[28:29], v[20:21], v[28:29]
	v_pk_fma_f32 v[94:95], v[22:23], v[96:97], v[94:95]
	v_pk_fma_f32 v[28:29], v[22:23], v[30:31], v[28:29]
	v_add_f32_e32 v96, v94, v95
	v_add_f32_e32 v30, v28, v29
	v_pk_fma_f32 v[40:41], v[20:21], v[40:41], v[20:21] neg_lo:[1,0,0] neg_hi:[1,0,0]
	v_add_f32_dpp v97, v96, v96 quad_perm:[1,0,3,2] row_mask:0xf bank_mask:0xf bound_ctrl:1
	v_add_f32_dpp v31, v30, v30 quad_perm:[1,0,3,2] row_mask:0xf bank_mask:0xf bound_ctrl:1
	v_pk_fma_f32 v[42:43], v[22:23], v[42:43], v[22:23] neg_lo:[1,0,0] neg_hi:[1,0,0]
	v_add_f32_dpp v96, v97, v97 quad_perm:[2,3,0,1] row_mask:0xf bank_mask:0xf bound_ctrl:1
	v_add_f32_dpp v30, v31, v31 quad_perm:[2,3,0,1] row_mask:0xf bank_mask:0xf bound_ctrl:1
	v_pk_fma_f32 v[40:41], v[38:39], v[44:45], v[40:41] op_sel_hi:[0,1,1]
	v_add_f32_dpp v97, v96, v96 row_half_mirror row_mask:0xf bank_mask:0xf bound_ctrl:1
	v_add_f32_dpp v31, v30, v30 row_half_mirror row_mask:0xf bank_mask:0xf bound_ctrl:1
	v_pk_fma_f32 v[42:43], v[38:39], v[46:47], v[42:43] op_sel_hi:[0,1,1]
	v_add_f32_dpp v90, v97, v97 row_mirror row_mask:0xf bank_mask:0xf bound_ctrl:1
	v_add_f32_dpp v30, v31, v31 row_mirror row_mask:0xf bank_mask:0xf bound_ctrl:1
	ds_write_b32 v37, v30 offset:43648
	ds_read_b128 v[28:31], v91 offset:16896
	v_pk_fma_f32 v[20:21], v[90:91], v[60:61], v[40:41] op_sel_hi:[0,1,1] neg_lo:[1,0,0] neg_hi:[1,0,0]
	v_pk_fma_f32 v[22:23], v[90:91], v[62:63], v[42:43] op_sel_hi:[0,1,1] neg_lo:[1,0,0] neg_hi:[1,0,0]
	ds_read_b128 v[40:43], v91 offset:17472
	ds_read_b128 v[60:63], v91 offset:17984
	ds_read_b128 v[44:47], v91 offset:17728
	ds_read_b128 v[94:97], v91 offset:18496
	ds_read_b32 v38, v92 offset:18752
	s_waitcnt lgkmcnt(7)
; #define DPP_ADD(v, ctrl) ((v) + __builtin_bit_cast(float, __builtin_amdgcn_update_dpp(0, __builtin_bit_cast(int, (v)), (ctrl), 0xf, 0xf, true)))
; __device__ __forceinline__ void rwkv_scan_unit(const Params& p, int unit, char* smem) {
;     ...
;         for (int u = 0; u < SCH; ++u) {
;             f32x4 ne = e4, nkd = kd4, nka = ka4, nr = r4, nkk = kk4; float nv = vv;
;             if (u + 1 < SCH) { const char* q = lb + (u + 1) * STEPB;
;                 ne = *(const f32x4*)(q); nkd = *(const f32x4*)(q + 256); nka = *(const f32x4*)(q + 512); nr = *(const f32x4*)(q + 768); nkk = *(const f32x4*)(q + 1024);
;                 nv = *(const float*)(vb + (u + 1) * STEPB); }
;             const f32x2 v2 = {vv, vv}, c2 = {c, c};
;             const f32x2 tA = __builtin_elementwise_fma(v2, (f32x2){kd4[0], kd4[1]}, __builtin_elementwise_fma(-sA, (f32x2){e4[0], e4[1]}, sA));
;             const f32x2 tB = __builtin_elementwise_fma(v2, (f32x2){kd4[2], kd4[3]}, __builtin_elementwise_fma(-sB, (f32x2){e4[2], e4[3]}, sB));
;             sA = __builtin_elementwise_fma(-c2, (f32x2){ka4[0], ka4[1]}, tA);
;             sB = __builtin_elementwise_fma(-c2, (f32x2){ka4[2], ka4[3]}, tB);
;             const f32x2 yv = __builtin_elementwise_fma(sB, (f32x2){r4[2], r4[3]}, sA * (f32x2){r4[0], r4[1]});
;             float y = yv[0] + yv[1];
;             if (u + 1 < SCH) {
;                 const f32x2 cv = __builtin_elementwise_fma(sB, (f32x2){nkk[2], nkk[3]}, sA * (f32x2){nkk[0], nkk[1]});
;                 float cn = cv[0] + cv[1];
;                 cn = DPP_ADD(cn, 0xB1);  y = DPP_ADD(y, 0xB1);
;                 cn = DPP_ADD(cn, 0x4E);  y = DPP_ADD(y, 0x4E);
;                 cn = DPP_ADD(cn, 0x141); y = DPP_ADD(y, 0x141);
;                 cn = DPP_ADD(cn, 0x140); y = DPP_ADD(y, 0x140);
;                 c = cn;
;             } else y = red16(y);
;             if (ks == 0) yl[u * 16] = y;
;             e4 = ne; kd4 = nkd; ka4 = nka; r4 = nr; kk4 = nkk; vv = nv;
;         }
	v_pk_mul_f32 v[32:33], v[20:21], v[32:33]
	v_pk_mul_f32 v[64:65], v[20:21], v[64:65]
	v_pk_fma_f32 v[32:33], v[22:23], v[34:35], v[32:33]
	v_pk_fma_f32 v[64:65], v[22:23], v[66:67], v[64:65]
	v_add_f32_e32 v34, v32, v33
	v_add_f32_e32 v66, v64, v65
	v_pk_fma_f32 v[12:13], v[20:21], v[12:13], v[20:21] neg_lo:[1,0,0] neg_hi:[1,0,0]
	v_add_f32_dpp v35, v34, v34 quad_perm:[1,0,3,2] row_mask:0xf bank_mask:0xf bound_ctrl:1
	v_add_f32_dpp v67, v66, v66 quad_perm:[1,0,3,2] row_mask:0xf bank_mask:0xf bound_ctrl:1
	v_pk_fma_f32 v[14:15], v[22:23], v[14:15], v[22:23] neg_lo:[1,0,0] neg_hi:[1,0,0]
	v_add_f32_dpp v34, v35, v35 quad_perm:[2,3,0,1] row_mask:0xf bank_mask:0xf bound_ctrl:1
	v_add_f32_dpp v66, v67, v67 quad_perm:[2,3,0,1] row_mask:0xf bank_mask:0xf bound_ctrl:1
	v_pk_fma_f32 v[12:13], v[36:37], v[16:17], v[12:13] op_sel_hi:[0,1,1]
	v_add_f32_dpp v35, v34, v34 row_half_mirror row_mask:0xf bank_mask:0xf bound_ctrl:1
	v_add_f32_dpp v67, v66, v66 row_half_mirror row_mask:0xf bank_mask:0xf bound_ctrl:1
	v_pk_fma_f32 v[14:15], v[36:37], v[18:19], v[14:15] op_sel_hi:[0,1,1]
	v_add_f32_dpp v90, v35, v35 row_mirror row_mask:0xf bank_mask:0xf bound_ctrl:1
	v_add_f32_dpp v66, v67, v67 row_mirror row_mask:0xf bank_mask:0xf bound_ctrl:1
	ds_write_b32 v37, v66 offset:43712
	ds_read_b128 v[64:67], v91 offset:18240
	v_pk_fma_f32 v[20:21], v[90:91], v[24:25], v[12:13] op_sel_hi:[0,1,1] neg_lo:[1,0,0] neg_hi:[1,0,0]
	v_pk_fma_f32 v[22:23], v[90:91], v[26:27], v[14:15] op_sel_hi:[0,1,1] neg_lo:[1,0,0] neg_hi:[1,0,0]
	ds_read_b128 v[12:15], v91 offset:18816
	ds_read_b128 v[24:27], v91 offset:19328
	ds_read_b128 v[16:19], v91 offset:19072
	ds_read_b128 v[32:35], v91 offset:19840
	ds_read_b32 v36, v92 offset:20096
	s_waitcnt lgkmcnt(7)
	v_pk_mul_f32 v[94:95], v[20:21], v[94:95]
	v_pk_mul_f32 v[28:29], v[20:21], v[28:29]
	v_pk_fma_f32 v[94:95], v[22:23], v[96:97], v[94:95]
	v_pk_fma_f32 v[28:29], v[22:23], v[30:31], v[28:29]
	v_add_f32_e32 v96, v94, v95
	v_add_f32_e32 v30, v28, v29
	v_pk_fma_f32 v[40:41], v[20:21], v[40:41], v[20:21] neg_lo:[1,0,0] neg_hi:[1,0,0]
	v_add_f32_dpp v97, v96, v96 quad_perm:[1,0,3,2] row_mask:0xf bank_mask:0xf bound_ctrl:1
	v_add_f32_dpp v31, v30, v30 quad_perm:[1,0,3,2] row_mask:0xf bank_mask:0xf bound_ctrl:1
	v_pk_fma_f32 v[42:43], v[22:23], v[42:43], v[22:23] neg_lo:[1,0,0] neg_hi:[1,0,0]
	v_add_f32_dpp v96, v97, v97 quad_perm:[2,3,0,1] row_mask:0xf bank_mask:0xf bound_ctrl:1
	v_add_f32_dpp v30, v31, v31 quad_perm:[2,3,0,1] row_mask:0xf bank_mask:0xf bound_ctrl:1
	v_pk_fma_f32 v[40:41], v[38:39], v[44:45], v[40:41] op_sel_hi:[0,1,1]
	v_add_f32_dpp v97, v96, v96 row_half_mirror row_mask:0xf bank_mask:0xf bound_ctrl:1
	v_add_f32_dpp v31, v30, v30 row_half_mirror row_mask:0xf bank_mask:0xf bound_ctrl:1
	v_pk_fma_f32 v[42:43], v[38:39], v[46:47], v[42:43] op_sel_hi:[0,1,1]
	v_add_f32_dpp v90, v97, v97 row_mirror row_mask:0xf bank_mask:0xf bound_ctrl:1
	v_add_f32_dpp v30, v31, v31 row_mirror row_mask:0xf bank_mask:0xf bound_ctrl:1
	ds_write_b32 v37, v30 offset:43776
	ds_read_b128 v[28:31], v91 offset:19584
	v_pk_fma_f32 v[20:21], v[90:91], v[60:61], v[40:41] op_sel_hi:[0,1,1] neg_lo:[1,0,0] neg_hi:[1,0,0]
	v_pk_fma_f32 v[22:23], v[90:91], v[62:63], v[42:43] op_sel_hi:[0,1,1] neg_lo:[1,0,0] neg_hi:[1,0,0]
	ds_read_b128 v[40:43], v91 offset:20160
	ds_read_b128 v[60:63], v91 offset:20672
	ds_read_b128 v[44:47], v91 offset:20416
	ds_read_b128 v[94:97], v91 offset:21184
	ds_read_b32 v38, v92 offset:21440
	s_waitcnt lgkmcnt(7)
	v_pk_mul_f32 v[32:33], v[20:21], v[32:33]
	v_pk_mul_f32 v[64:65], v[20:21], v[64:65]
	v_pk_fma_f32 v[32:33], v[22:23], v[34:35], v[32:33]
	v_pk_fma_f32 v[64:65], v[22:23], v[66:67], v[64:65]
	v_add_f32_e32 v34, v32, v33
	v_add_f32_e32 v66, v64, v65
	v_pk_fma_f32 v[12:13], v[20:21], v[12:13], v[20:21] neg_lo:[1,0,0] neg_hi:[1,0,0]
	v_add_f32_dpp v35, v34, v34 quad_perm:[1,0,3,2] row_mask:0xf bank_mask:0xf bound_ctrl:1
	v_add_f32_dpp v67, v66, v66 quad_perm:[1,0,3,2] row_mask:0xf bank_mask:0xf bound_ctrl:1
	v_pk_fma_f32 v[14:15], v[22:23], v[14:15], v[22:23] neg_lo:[1,0,0] neg_hi:[1,0,0]
	v_add_f32_dpp v34, v35, v35 quad_perm:[2,3,0,1] row_mask:0xf bank_mask:0xf bound_ctrl:1
	v_add_f32_dpp v66, v67, v67 quad_perm:[2,3,0,1] row_mask:0xf bank_mask:0xf bound_ctrl:1
	v_pk_fma_f32 v[12:13], v[36:37], v[16:17], v[12:13] op_sel_hi:[0,1,1]
	v_add_f32_dpp v35, v34, v34 row_half_mirror row_mask:0xf bank_mask:0xf bound_ctrl:1
	v_add_f32_dpp v67, v66, v66 row_half_mirror row_mask:0xf bank_mask:0xf bound_ctrl:1
	v_pk_fma_f32 v[14:15], v[36:37], v[18:19], v[14:15] op_sel_hi:[0,1,1]
	v_add_f32_dpp v90, v35, v35 row_mirror row_mask:0xf bank_mask:0xf bound_ctrl:1
	v_add_f32_dpp v66, v67, v67 row_mirror row_mask:0xf bank_mask:0xf bound_ctrl:1
	ds_write_b32 v37, v66 offset:43840
	ds_read_b128 v[64:67], v91 offset:20928
	v_pk_fma_f32 v[20:21], v[90:91], v[24:25], v[12:13] op_sel_hi:[0,1,1] neg_lo:[1,0,0] neg_hi:[1,0,0]
	v_pk_fma_f32 v[22:23], v[90:91], v[26:27], v[14:15] op_sel_hi:[0,1,1] neg_lo:[1,0,0] neg_hi:[1,0,0]
	s_waitcnt lgkmcnt(2)
; #define DPP_ADD(v, ctrl) ((v) + __builtin_bit_cast(float, __builtin_amdgcn_update_dpp(0, __builtin_bit_cast(int, (v)), (ctrl), 0xf, 0xf, true)))
; #define SC_LSTORE(st_) { SC_S1(st_, 0, rg0) SC_S1(st_, 1, rg1) SC_S1(st_, 2, rg2) }
; __device__ __forceinline__ void rwkv_scan_unit(const Params& p, int unit, char* smem) {
;     ...
;         for (int u = 0; u < SCH; ++u) {
;             f32x4 ne = e4, nkd = kd4, nka = ka4, nr = r4, nkk = kk4; float nv = vv;
;             if (u + 1 < SCH) { const char* q = lb + (u + 1) * STEPB;
;                 ne = *(const f32x4*)(q); nkd = *(const f32x4*)(q + 256); nka = *(const f32x4*)(q + 512); nr = *(const f32x4*)(q + 768); nkk = *(const f32x4*)(q + 1024);
;                 nv = *(const float*)(vb + (u + 1) * STEPB); }
;             const f32x2 v2 = {vv, vv}, c2 = {c, c};
;             const f32x2 tA = __builtin_elementwise_fma(v2, (f32x2){kd4[0], kd4[1]}, __builtin_elementwise_fma(-sA, (f32x2){e4[0], e4[1]}, sA));
;             const f32x2 tB = __builtin_elementwise_fma(v2, (f32x2){kd4[2], kd4[3]}, __builtin_elementwise_fma(-sB, (f32x2){e4[2], e4[3]}, sB));
;             sA = __builtin_elementwise_fma(-c2, (f32x2){ka4[0], ka4[1]}, tA);
;             sB = __builtin_elementwise_fma(-c2, (f32x2){ka4[2], ka4[3]}, tB);
;             const f32x2 yv = __builtin_elementwise_fma(sB, (f32x2){r4[2], r4[3]}, sA * (f32x2){r4[0], r4[1]});
;             float y = yv[0] + yv[1];
;             if (u + 1 < SCH) {
;                 const f32x2 cv = __builtin_elementwise_fma(sB, (f32x2){nkk[2], nkk[3]}, sA * (f32x2){nkk[0], nkk[1]});
;                 float cn = cv[0] + cv[1];
;                 cn = DPP_ADD(cn, 0xB1);  y = DPP_ADD(y, 0xB1);
;                 cn = DPP_ADD(cn, 0x4E);  y = DPP_ADD(y, 0x4E);
;                 cn = DPP_ADD(cn, 0x141); y = DPP_ADD(y, 0x141);
;                 cn = DPP_ADD(cn, 0x140); y = DPP_ADD(y, 0x140);
;                 c = cn;
;             } else y = red16(y);
;             if (ks == 0) yl[u * 16] = y;
;             e4 = ne; kd4 = nkd; ka4 = nka; r4 = nr; kk4 = nkk; vv = nv;
;         }
;         s0 = sA[0]; s1 = sA[1]; s2 = sB[0]; s3 = sB[1];
;         __builtin_amdgcn_sched_barrier(0);
;         if (ci + 1 < NCH) { SC_LSTORE(((ci + 1) & 1) * STG) }
	v_pk_mul_f32 v[94:95], v[20:21], v[94:95]
	v_pk_mul_f32 v[28:29], v[20:21], v[28:29]
	v_pk_fma_f32 v[94:95], v[22:23], v[96:97], v[94:95]
	v_pk_fma_f32 v[28:29], v[22:23], v[30:31], v[28:29]
	v_add_f32_e32 v96, v94, v95
	v_add_f32_e32 v30, v28, v29
	v_pk_fma_f32 v[40:41], v[20:21], v[40:41], v[20:21] neg_lo:[1,0,0] neg_hi:[1,0,0]
	v_add_f32_dpp v97, v96, v96 quad_perm:[1,0,3,2] row_mask:0xf bank_mask:0xf bound_ctrl:1
	v_add_f32_dpp v31, v30, v30 quad_perm:[1,0,3,2] row_mask:0xf bank_mask:0xf bound_ctrl:1
	v_pk_fma_f32 v[42:43], v[22:23], v[42:43], v[22:23] neg_lo:[1,0,0] neg_hi:[1,0,0]
	v_add_f32_dpp v96, v97, v97 quad_perm:[2,3,0,1] row_mask:0xf bank_mask:0xf bound_ctrl:1
	v_add_f32_dpp v30, v31, v31 quad_perm:[2,3,0,1] row_mask:0xf bank_mask:0xf bound_ctrl:1
	v_pk_fma_f32 v[40:41], v[38:39], v[44:45], v[40:41] op_sel_hi:[0,1,1]
	v_add_f32_dpp v97, v96, v96 row_half_mirror row_mask:0xf bank_mask:0xf bound_ctrl:1
	v_add_f32_dpp v31, v30, v30 row_half_mirror row_mask:0xf bank_mask:0xf bound_ctrl:1
	v_pk_fma_f32 v[42:43], v[38:39], v[46:47], v[42:43] op_sel_hi:[0,1,1]
	v_add_f32_dpp v90, v97, v97 row_mirror row_mask:0xf bank_mask:0xf bound_ctrl:1
	v_add_f32_dpp v30, v31, v31 row_mirror row_mask:0xf bank_mask:0xf bound_ctrl:1
	ds_write_b32 v37, v30 offset:43904
	v_pk_fma_f32 v[20:21], v[90:91], v[60:61], v[40:41] op_sel_hi:[0,1,1] neg_lo:[1,0,0] neg_hi:[1,0,0]
	v_pk_fma_f32 v[22:23], v[90:91], v[62:63], v[42:43] op_sel_hi:[0,1,1] neg_lo:[1,0,0] neg_hi:[1,0,0]
	s_waitcnt lgkmcnt(1)
	v_pk_mul_f32 v[64:65], v[20:21], v[64:65]
	v_pk_fma_f32 v[64:65], v[22:23], v[66:67], v[64:65]
	s_nop 0
	v_add_f32_e32 v66, v64, v65
	s_nop 1
	v_add_f32_dpp v67, v66, v66 quad_perm:[1,0,3,2] row_mask:0xf bank_mask:0xf bound_ctrl:1
	s_nop 1
	v_add_f32_dpp v66, v67, v67 quad_perm:[2,3,0,1] row_mask:0xf bank_mask:0xf bound_ctrl:1
	s_nop 1
	v_add_f32_dpp v67, v66, v66 row_half_mirror row_mask:0xf bank_mask:0xf bound_ctrl:1
	s_nop 1
	v_add_f32_dpp v66, v67, v67 row_mirror row_mask:0xf bank_mask:0xf bound_ctrl:1
	ds_write_b32 v37, v66 offset:43968
	s_bitcmp1_b32 s64, 0
	s_cselect_b32 s0, 0x5400, 0
	s_waitcnt vmcnt(13)
	v_add3_u32 v16, s0, v74, v75
	v_cvt_f32_f16_sdwa v13, v140 dst_sel:DWORD dst_unused:UNUSED_PAD src0_sel:WORD_1
	v_cvt_f32_f16_e32 v12, v140
	v_cvt_f32_f16_sdwa v15, v141 dst_sel:DWORD dst_unused:UNUSED_PAD src0_sel:WORD_1
	v_cvt_f32_f16_e32 v14, v141
	ds_write_b128 v16, v[12:15]
	v_cvt_f32_f16_sdwa v13, v142 dst_sel:DWORD dst_unused:UNUSED_PAD src0_sel:WORD_1
	v_cvt_f32_f16_e32 v12, v142
	v_cvt_f32_f16_sdwa v15, v143 dst_sel:DWORD dst_unused:UNUSED_PAD src0_sel:WORD_1
	v_cvt_f32_f16_e32 v14, v143
	ds_write_b128 v16, v[12:15] offset:16
	v_add3_u32 v16, s0, v76, v77
	v_cvt_f32_f16_sdwa v13, v144 dst_sel:DWORD dst_unused:UNUSED_PAD src0_sel:WORD_1
	v_cvt_f32_f16_e32 v12, v144
	v_cvt_f32_f16_sdwa v15, v145 dst_sel:DWORD dst_unused:UNUSED_PAD src0_sel:WORD_1
	v_cvt_f32_f16_e32 v14, v145
	ds_write_b128 v16, v[12:15]
	v_cvt_f32_f16_sdwa v13, v146 dst_sel:DWORD dst_unused:UNUSED_PAD src0_sel:WORD_1
	v_cvt_f32_f16_e32 v12, v146
	v_cvt_f32_f16_sdwa v15, v147 dst_sel:DWORD dst_unused:UNUSED_PAD src0_sel:WORD_1
	v_cvt_f32_f16_e32 v14, v147
	ds_write_b128 v16, v[12:15] offset:16
	v_add3_u32 v16, s0, v78, v79
	v_cvt_f32_f16_sdwa v13, v148 dst_sel:DWORD dst_unused:UNUSED_PAD src0_sel:WORD_1
	v_cvt_f32_f16_e32 v12, v148
	v_cvt_f32_f16_sdwa v15, v149 dst_sel:DWORD dst_unused:UNUSED_PAD src0_sel:WORD_1
	v_cvt_f32_f16_e32 v14, v149
	ds_write_b128 v16, v[12:15]
	v_cvt_f32_f16_sdwa v13, v150 dst_sel:DWORD dst_unused:UNUSED_PAD src0_sel:WORD_1
	v_cvt_f32_f16_e32 v12, v150
	v_cvt_f32_f16_sdwa v15, v151 dst_sel:DWORD dst_unused:UNUSED_PAD src0_sel:WORD_1
	v_cvt_f32_f16_e32 v14, v151
	ds_write_b128 v16, v[12:15] offset:16

; __device__ __forceinline__ void rwkv_scan_unit(const Params& p, int unit, char* smem) {
;     ...
;         const char* lb = smem + st + ks * 16;
;         const char* vb = smem + st + 1280 + rl * 4;
;         float* yl = (float*)(smem + YOFF + (ci & 1) * 1024) + rl;
;         f32x4 e4 = *(const f32x4*)(lb), kd4 = *(const f32x4*)(lb + 256), ka4 = *(const f32x4*)(lb + 512), r4 = *(const f32x4*)(lb + 768), kk4 = *(const f32x4*)(lb + 1024);
;         float vv = *(const float*)vb;
;         f32x2 sA = {s0, s1}, sB = {s2, s3};
;         float c;
;         { const f32x2 cv = sA * (f32x2){kk4[0], kk4[1]} + sB * (f32x2){kk4[2], kk4[3]}; c = red16(cv[0] + cv[1]); }
; #pragma unroll
;         for (int u = 0; u < SCH; ++u) {
;             f32x4 ne = e4, nkd = kd4, nka = ka4, nr = r4, nkk = kk4; float nv = vv;
;             if (u + 1 < SCH) { const char* q = lb + (u + 1) * STEPB;
;                 ne = *(const f32x4*)(q); nkd = *(const f32x4*)(q + 256); nka = *(const f32x4*)(q + 512); nr = *(const f32x4*)(q + 768); nkk = *(const f32x4*)(q + 1024);
;                 nv = *(const float*)(vb + (u + 1) * STEPB); }
;             const f32x2 v2 = {vv, vv}, c2 = {c, c};
;             const f32x2 tA = __builtin_elementwise_fma(v2, (f32x2){kd4[0], kd4[1]}, __builtin_elementwise_fma(-sA, (f32x2){e4[0], e4[1]}, sA));
;             const f32x2 tB = __builtin_elementwise_fma(v2, (f32x2){kd4[2], kd4[3]}, __builtin_elementwise_fma(-sB, (f32x2){e4[2], e4[3]}, sB));
;             sA = __builtin_elementwise_fma(-c2, (f32x2){ka4[0], ka4[1]}, tA);
;             sB = __builtin_elementwise_fma(-c2, (f32x2){ka4[2], ka4[3]}, tB);
;             const f32x2 yv = __builtin_elementwise_fma(sB, (f32x2){r4[2], r4[3]}, sA * (f32x2){r4[0], r4[1]});
;             float y = yv[0] + yv[1];
;             if (u + 1 < SCH) {
;                 const f32x2 cv = __builtin_elementwise_fma(sB, (f32x2){nkk[2], nkk[3]}, sA * (f32x2){nkk[0], nkk[1]});
;                 float cn = cv[0] + cv[1];
;                 cn = DPP_ADD(cn, 0xB1);  y = DPP_ADD(y, 0xB1);
;                 cn = DPP_ADD(cn, 0x4E);  y = DPP_ADD(y, 0x4E);
;                 cn = DPP_ADD(cn, 0x141); y = DPP_ADD(y, 0x141);
;                 cn = DPP_ADD(cn, 0x140); y = DPP_ADD(y, 0x140);
;                 c = cn;
;             } else y = red16(y);
;             if (ks == 0) yl[u * 16] = y;
.Lsc_p2_body:
	s_add_i32 s30, s64, -1
	s_and_b32 s30, s30, 1
	s_mul_i32 s52, s30, 0x5400
	v_or_b32_e32 v91, s52, v80
	v_add_u32_e32 v92, s52, v81
	ds_read_b128 v[32:35], v91 offset:1024
	ds_read_b128 v[12:15], v91 offset:0
	ds_read_b128 v[16:19], v91 offset:256
	ds_read_b32 v36, v92 offset:1280
	ds_read_b128 v[24:27], v91 offset:512
	ds_read_b128 v[28:31], v91 offset:768
	ds_read_b128 v[40:43], v91 offset:1344
	ds_read_b128 v[60:63], v91 offset:1856
	ds_read_b128 v[44:47], v91 offset:1600
	ds_read_b128 v[94:97], v91 offset:2368
	ds_read_b32 v38, v92 offset:2624
	ds_read_b128 v[64:67], v91 offset:2112
	s_waitcnt lgkmcnt(12)
	v_bfe_u32 v247, v246, 16, 1
	s_movk_i32 s0, 0x7fff
	v_add3_u32 v247, v246, v247, s0
	global_store_short_d16_hi v[244:245], v247, off
	s_lshl_b32 s52, s30, 10
	v_lshl_add_u32 v37, v72, 2, s52
	v_lshlrev_b32_e32 v90, 2, v109
	v_add_u32_e32 v90, 0x800, v90
	v_cndmask_b32_e64 v37, v90, v37, s[50:51]
	s_waitcnt lgkmcnt(11)
	v_pk_mul_f32 v[32:33], v[20:21], v[32:33]
	s_waitcnt lgkmcnt(10)
	v_pk_fma_f32 v[12:13], v[20:21], v[12:13], v[20:21] neg_lo:[1,0,0] neg_hi:[1,0,0]
	v_pk_fma_f32 v[32:33], v[22:23], v[34:35], v[32:33]
	v_pk_fma_f32 v[14:15], v[22:23], v[14:15], v[22:23] neg_lo:[1,0,0] neg_hi:[1,0,0]
	v_add_f32_e32 v34, v32, v33
	s_waitcnt lgkmcnt(8)
	v_pk_fma_f32 v[12:13], v[36:37], v[16:17], v[12:13] op_sel_hi:[0,1,1]
	v_pk_fma_f32 v[14:15], v[36:37], v[18:19], v[14:15] op_sel_hi:[0,1,1]
	v_add_f32_dpp v35, v34, v34 quad_perm:[1,0,3,2] row_mask:0xf bank_mask:0xf bound_ctrl:1
	s_nop 1
	v_add_f32_dpp v34, v35, v35 quad_perm:[2,3,0,1] row_mask:0xf bank_mask:0xf bound_ctrl:1
	s_nop 1
	v_add_f32_dpp v35, v34, v34 row_half_mirror row_mask:0xf bank_mask:0xf bound_ctrl:1
	s_nop 1
	v_add_f32_dpp v90, v35, v35 row_mirror row_mask:0xf bank_mask:0xf bound_ctrl:1
	ds_read_b128 v[16:19], v91 offset:2944
	ds_read_b128 v[32:35], v91 offset:3712
	ds_read_b32 v36, v92 offset:3968
	s_waitcnt lgkmcnt(10)
	v_pk_fma_f32 v[20:21], v[90:91], v[24:25], v[12:13] op_sel_hi:[0,1,1] neg_lo:[1,0,0] neg_hi:[1,0,0]
	v_pk_fma_f32 v[22:23], v[90:91], v[26:27], v[14:15] op_sel_hi:[0,1,1] neg_lo:[1,0,0] neg_hi:[1,0,0]
	ds_read_b128 v[12:15], v91 offset:2688
	ds_read_b128 v[24:27], v91 offset:3200
	s_waitcnt lgkmcnt(7)
	v_pk_mul_f32 v[94:95], v[20:21], v[94:95]
	v_pk_mul_f32 v[28:29], v[20:21], v[28:29]
	v_pk_fma_f32 v[94:95], v[22:23], v[96:97], v[94:95]
	v_pk_fma_f32 v[28:29], v[22:23], v[30:31], v[28:29]
	v_add_f32_e32 v96, v94, v95
	v_add_f32_e32 v30, v28, v29
	v_pk_fma_f32 v[40:41], v[20:21], v[40:41], v[20:21] neg_lo:[1,0,0] neg_hi:[1,0,0]
	v_add_f32_dpp v97, v96, v96 quad_perm:[1,0,3,2] row_mask:0xf bank_mask:0xf bound_ctrl:1
	v_add_f32_dpp v31, v30, v30 quad_perm:[1,0,3,2] row_mask:0xf bank_mask:0xf bound_ctrl:1
	v_pk_fma_f32 v[42:43], v[22:23], v[42:43], v[22:23] neg_lo:[1,0,0] neg_hi:[1,0,0]
	v_add_f32_dpp v96, v97, v97 quad_perm:[2,3,0,1] row_mask:0xf bank_mask:0xf bound_ctrl:1
	v_add_f32_dpp v30, v31, v31 quad_perm:[2,3,0,1] row_mask:0xf bank_mask:0xf bound_ctrl:1
	s_waitcnt lgkmcnt(6)
	v_pk_fma_f32 v[40:41], v[38:39], v[44:45], v[40:41] op_sel_hi:[0,1,1]
	v_add_f32_dpp v97, v96, v96 row_half_mirror row_mask:0xf bank_mask:0xf bound_ctrl:1
	v_add_f32_dpp v31, v30, v30 row_half_mirror row_mask:0xf bank_mask:0xf bound_ctrl:1
	v_pk_fma_f32 v[42:43], v[38:39], v[46:47], v[42:43] op_sel_hi:[0,1,1]
	v_add_f32_dpp v90, v97, v97 row_mirror row_mask:0xf bank_mask:0xf bound_ctrl:1
	v_add_f32_dpp v30, v31, v31 row_mirror row_mask:0xf bank_mask:0xf bound_ctrl:1
	ds_write_b32 v37, v30 offset:43008
	ds_read_b128 v[28:31], v91 offset:3456
	v_pk_fma_f32 v[20:21], v[90:91], v[60:61], v[40:41] op_sel_hi:[0,1,1] neg_lo:[1,0,0] neg_hi:[1,0,0]
	v_pk_fma_f32 v[22:23], v[90:91], v[62:63], v[42:43] op_sel_hi:[0,1,1] neg_lo:[1,0,0] neg_hi:[1,0,0]
	ds_read_b128 v[40:43], v91 offset:4032
	ds_read_b128 v[60:63], v91 offset:4544
	ds_read_b128 v[44:47], v91 offset:4288
	ds_read_b128 v[94:97], v91 offset:5056
	ds_read_b32 v38, v92 offset:5312
	s_waitcnt lgkmcnt(8)
	v_pk_mul_f32 v[32:33], v[20:21], v[32:33]
	v_pk_mul_f32 v[64:65], v[20:21], v[64:65]
	v_pk_fma_f32 v[32:33], v[22:23], v[34:35], v[32:33]
	v_pk_fma_f32 v[64:65], v[22:23], v[66:67], v[64:65]
	v_add_f32_e32 v34, v32, v33
	v_add_f32_e32 v66, v64, v65
	v_pk_fma_f32 v[12:13], v[20:21], v[12:13], v[20:21] neg_lo:[1,0,0] neg_hi:[1,0,0]
	v_add_f32_dpp v35, v34, v34 quad_perm:[1,0,3,2] row_mask:0xf bank_mask:0xf bound_ctrl:1
	v_add_f32_dpp v67, v66, v66 quad_perm:[1,0,3,2] row_mask:0xf bank_mask:0xf bound_ctrl:1
	v_pk_fma_f32 v[14:15], v[22:23], v[14:15], v[22:23] neg_lo:[1,0,0] neg_hi:[1,0,0]
	v_add_f32_dpp v34, v35, v35 quad_perm:[2,3,0,1] row_mask:0xf bank_mask:0xf bound_ctrl:1
	v_add_f32_dpp v66, v67, v67 quad_perm:[2,3,0,1] row_mask:0xf bank_mask:0xf bound_ctrl:1
	v_pk_fma_f32 v[12:13], v[36:37], v[16:17], v[12:13] op_sel_hi:[0,1,1]
	v_add_f32_dpp v35, v34, v34 row_half_mirror row_mask:0xf bank_mask:0xf bound_ctrl:1
	v_add_f32_dpp v67, v66, v66 row_half_mirror row_mask:0xf bank_mask:0xf bound_ctrl:1
	v_pk_fma_f32 v[14:15], v[36:37], v[18:19], v[14:15] op_sel_hi:[0,1,1]
	v_add_f32_dpp v90, v35, v35 row_mirror row_mask:0xf bank_mask:0xf bound_ctrl:1
	v_add_f32_dpp v66, v67, v67 row_mirror row_mask:0xf bank_mask:0xf bound_ctrl:1
	ds_write_b32 v37, v66 offset:43072
	ds_read_b128 v[64:67], v91 offset:4800
	s_waitcnt lgkmcnt(9)
	v_pk_fma_f32 v[20:21], v[90:91], v[24:25], v[12:13] op_sel_hi:[0,1,1] neg_lo:[1,0,0] neg_hi:[1,0,0]
	v_pk_fma_f32 v[22:23], v[90:91], v[26:27], v[14:15] op_sel_hi:[0,1,1] neg_lo:[1,0,0] neg_hi:[1,0,0]
	ds_read_b128 v[12:15], v91 offset:5376
	ds_read_b128 v[24:27], v91 offset:5888
	ds_read_b128 v[16:19], v91 offset:5632
	ds_read_b128 v[32:35], v91 offset:6400
	ds_read_b32 v36, v92 offset:6656
	s_waitcnt lgkmcnt(7)
; #define DPP_ADD(v, ctrl) ((v) + __builtin_bit_cast(float, __builtin_amdgcn_update_dpp(0, __builtin_bit_cast(int, (v)), (ctrl), 0xf, 0xf, true)))
; __device__ __forceinline__ void rwkv_scan_unit(const Params& p, int unit, char* smem) {
;     ...
;         for (int u = 0; u < SCH; ++u) {
;             f32x4 ne = e4, nkd = kd4, nka = ka4, nr = r4, nkk = kk4; float nv = vv;
;             if (u + 1 < SCH) { const char* q = lb + (u + 1) * STEPB;
;                 ne = *(const f32x4*)(q); nkd = *(const f32x4*)(q + 256); nka = *(const f32x4*)(q + 512); nr = *(const f32x4*)(q + 768); nkk = *(const f32x4*)(q + 1024);
;                 nv = *(const float*)(vb + (u + 1) * STEPB); }
;             const f32x2 v2 = {vv, vv}, c2 = {c, c};
;             const f32x2 tA = __builtin_elementwise_fma(v2, (f32x2){kd4[0], kd4[1]}, __builtin_elementwise_fma(-sA, (f32x2){e4[0], e4[1]}, sA));
;             const f32x2 tB = __builtin_elementwise_fma(v2, (f32x2){kd4[2], kd4[3]}, __builtin_elementwise_fma(-sB, (f32x2){e4[2], e4[3]}, sB));
;             sA = __builtin_elementwise_fma(-c2, (f32x2){ka4[0], ka4[1]}, tA);
;             sB = __builtin_elementwise_fma(-c2, (f32x2){ka4[2], ka4[3]}, tB);
;             const f32x2 yv = __builtin_elementwise_fma(sB, (f32x2){r4[2], r4[3]}, sA * (f32x2){r4[0], r4[1]});
;             float y = yv[0] + yv[1];
;             if (u + 1 < SCH) {
;                 const f32x2 cv = __builtin_elementwise_fma(sB, (f32x2){nkk[2], nkk[3]}, sA * (f32x2){nkk[0], nkk[1]});
;                 float cn = cv[0] + cv[1];
;                 cn = DPP_ADD(cn, 0xB1);  y = DPP_ADD(y, 0xB1);
;                 cn = DPP_ADD(cn, 0x4E);  y = DPP_ADD(y, 0x4E);
;                 cn = DPP_ADD(cn, 0x141); y = DPP_ADD(y, 0x141);
;                 cn = DPP_ADD(cn, 0x140); y = DPP_ADD(y, 0x140);
;                 c = cn;
;             } else y = red16(y);
;             if (ks == 0) yl[u * 16] = y;
;             e4 = ne; kd4 = nkd; ka4 = nka; r4 = nr; kk4 = nkk; vv = nv;
;         }
	v_pk_mul_f32 v[94:95], v[20:21], v[94:95]
	v_pk_mul_f32 v[28:29], v[20:21], v[28:29]
	v_pk_fma_f32 v[94:95], v[22:23], v[96:97], v[94:95]
	v_pk_fma_f32 v[28:29], v[22:23], v[30:31], v[28:29]
	v_add_f32_e32 v96, v94, v95
	v_add_f32_e32 v30, v28, v29
	v_pk_fma_f32 v[40:41], v[20:21], v[40:41], v[20:21] neg_lo:[1,0,0] neg_hi:[1,0,0]
	v_add_f32_dpp v97, v96, v96 quad_perm:[1,0,3,2] row_mask:0xf bank_mask:0xf bound_ctrl:1
	v_add_f32_dpp v31, v30, v30 quad_perm:[1,0,3,2] row_mask:0xf bank_mask:0xf bound_ctrl:1
	v_pk_fma_f32 v[42:43], v[22:23], v[42:43], v[22:23] neg_lo:[1,0,0] neg_hi:[1,0,0]
	v_add_f32_dpp v96, v97, v97 quad_perm:[2,3,0,1] row_mask:0xf bank_mask:0xf bound_ctrl:1
	v_add_f32_dpp v30, v31, v31 quad_perm:[2,3,0,1] row_mask:0xf bank_mask:0xf bound_ctrl:1
	v_pk_fma_f32 v[40:41], v[38:39], v[44:45], v[40:41] op_sel_hi:[0,1,1]
	v_add_f32_dpp v97, v96, v96 row_half_mirror row_mask:0xf bank_mask:0xf bound_ctrl:1
	v_add_f32_dpp v31, v30, v30 row_half_mirror row_mask:0xf bank_mask:0xf bound_ctrl:1
	v_pk_fma_f32 v[42:43], v[38:39], v[46:47], v[42:43] op_sel_hi:[0,1,1]
	v_add_f32_dpp v90, v97, v97 row_mirror row_mask:0xf bank_mask:0xf bound_ctrl:1
	v_add_f32_dpp v30, v31, v31 row_mirror row_mask:0xf bank_mask:0xf bound_ctrl:1
	ds_write_b32 v37, v30 offset:43136
	ds_read_b128 v[28:31], v91 offset:6144
	v_pk_fma_f32 v[20:21], v[90:91], v[60:61], v[40:41] op_sel_hi:[0,1,1] neg_lo:[1,0,0] neg_hi:[1,0,0]
	v_pk_fma_f32 v[22:23], v[90:91], v[62:63], v[42:43] op_sel_hi:[0,1,1] neg_lo:[1,0,0] neg_hi:[1,0,0]
	ds_read_b128 v[40:43], v91 offset:6720
	ds_read_b128 v[60:63], v91 offset:7232
	ds_read_b128 v[44:47], v91 offset:6976
	ds_read_b128 v[94:97], v91 offset:7744
	ds_read_b32 v38, v92 offset:8000
	s_waitcnt lgkmcnt(7)
	v_pk_mul_f32 v[32:33], v[20:21], v[32:33]
	v_pk_mul_f32 v[64:65], v[20:21], v[64:65]
	v_pk_fma_f32 v[32:33], v[22:23], v[34:35], v[32:33]
	v_pk_fma_f32 v[64:65], v[22:23], v[66:67], v[64:65]
	v_add_f32_e32 v34, v32, v33
	v_add_f32_e32 v66, v64, v65
	v_pk_fma_f32 v[12:13], v[20:21], v[12:13], v[20:21] neg_lo:[1,0,0] neg_hi:[1,0,0]
	v_add_f32_dpp v35, v34, v34 quad_perm:[1,0,3,2] row_mask:0xf bank_mask:0xf bound_ctrl:1
	v_add_f32_dpp v67, v66, v66 quad_perm:[1,0,3,2] row_mask:0xf bank_mask:0xf bound_ctrl:1
	v_pk_fma_f32 v[14:15], v[22:23], v[14:15], v[22:23] neg_lo:[1,0,0] neg_hi:[1,0,0]
	v_add_f32_dpp v34, v35, v35 quad_perm:[2,3,0,1] row_mask:0xf bank_mask:0xf bound_ctrl:1
	v_add_f32_dpp v66, v67, v67 quad_perm:[2,3,0,1] row_mask:0xf bank_mask:0xf bound_ctrl:1
	v_pk_fma_f32 v[12:13], v[36:37], v[16:17], v[12:13] op_sel_hi:[0,1,1]
	v_add_f32_dpp v35, v34, v34 row_half_mirror row_mask:0xf bank_mask:0xf bound_ctrl:1
	v_add_f32_dpp v67, v66, v66 row_half_mirror row_mask:0xf bank_mask:0xf bound_ctrl:1
	v_pk_fma_f32 v[14:15], v[36:37], v[18:19], v[14:15] op_sel_hi:[0,1,1]
	v_add_f32_dpp v90, v35, v35 row_mirror row_mask:0xf bank_mask:0xf bound_ctrl:1
	v_add_f32_dpp v66, v67, v67 row_mirror row_mask:0xf bank_mask:0xf bound_ctrl:1
	ds_write_b32 v37, v66 offset:43200
	ds_read_b128 v[64:67], v91 offset:7488
	v_pk_fma_f32 v[20:21], v[90:91], v[24:25], v[12:13] op_sel_hi:[0,1,1] neg_lo:[1,0,0] neg_hi:[1,0,0]
	v_pk_fma_f32 v[22:23], v[90:91], v[26:27], v[14:15] op_sel_hi:[0,1,1] neg_lo:[1,0,0] neg_hi:[1,0,0]
	ds_read_b128 v[12:15], v91 offset:8064
	ds_read_b128 v[24:27], v91 offset:8576
	ds_read_b128 v[16:19], v91 offset:8320
	ds_read_b128 v[32:35], v91 offset:9088
	ds_read_b32 v36, v92 offset:9344
	s_waitcnt lgkmcnt(7)
	v_pk_mul_f32 v[94:95], v[20:21], v[94:95]
	v_pk_mul_f32 v[28:29], v[20:21], v[28:29]
	v_pk_fma_f32 v[94:95], v[22:23], v[96:97], v[94:95]
	v_pk_fma_f32 v[28:29], v[22:23], v[30:31], v[28:29]
	v_add_f32_e32 v96, v94, v95
	v_add_f32_e32 v30, v28, v29
	v_pk_fma_f32 v[40:41], v[20:21], v[40:41], v[20:21] neg_lo:[1,0,0] neg_hi:[1,0,0]
	v_add_f32_dpp v97, v96, v96 quad_perm:[1,0,3,2] row_mask:0xf bank_mask:0xf bound_ctrl:1
	v_add_f32_dpp v31, v30, v30 quad_perm:[1,0,3,2] row_mask:0xf bank_mask:0xf bound_ctrl:1
	v_pk_fma_f32 v[42:43], v[22:23], v[42:43], v[22:23] neg_lo:[1,0,0] neg_hi:[1,0,0]
	v_add_f32_dpp v96, v97, v97 quad_perm:[2,3,0,1] row_mask:0xf bank_mask:0xf bound_ctrl:1
	v_add_f32_dpp v30, v31, v31 quad_perm:[2,3,0,1] row_mask:0xf bank_mask:0xf bound_ctrl:1
	v_pk_fma_f32 v[40:41], v[38:39], v[44:45], v[40:41] op_sel_hi:[0,1,1]
	v_add_f32_dpp v97, v96, v96 row_half_mirror row_mask:0xf bank_mask:0xf bound_ctrl:1
	v_add_f32_dpp v31, v30, v30 row_half_mirror row_mask:0xf bank_mask:0xf bound_ctrl:1
	v_pk_fma_f32 v[42:43], v[38:39], v[46:47], v[42:43] op_sel_hi:[0,1,1]
	v_add_f32_dpp v90, v97, v97 row_mirror row_mask:0xf bank_mask:0xf bound_ctrl:1
	v_add_f32_dpp v30, v31, v31 row_mirror row_mask:0xf bank_mask:0xf bound_ctrl:1
	ds_write_b32 v37, v30 offset:43264
	ds_read_b128 v[28:31], v91 offset:8832
	v_pk_fma_f32 v[20:21], v[90:91], v[60:61], v[40:41] op_sel_hi:[0,1,1] neg_lo:[1,0,0] neg_hi:[1,0,0]
	v_pk_fma_f32 v[22:23], v[90:91], v[62:63], v[42:43] op_sel_hi:[0,1,1] neg_lo:[1,0,0] neg_hi:[1,0,0]
	ds_read_b128 v[40:43], v91 offset:9408
	ds_read_b128 v[60:63], v91 offset:9920
	ds_read_b128 v[44:47], v91 offset:9664
	ds_read_b128 v[94:97], v91 offset:10432
	ds_read_b32 v38, v92 offset:10688
	s_waitcnt lgkmcnt(7)
; #define DPP_ADD(v, ctrl) ((v) + __builtin_bit_cast(float, __builtin_amdgcn_update_dpp(0, __builtin_bit_cast(int, (v)), (ctrl), 0xf, 0xf, true)))
; __device__ __forceinline__ void rwkv_scan_unit(const Params& p, int unit, char* smem) {
;     ...
;         for (int u = 0; u < SCH; ++u) {
;             f32x4 ne = e4, nkd = kd4, nka = ka4, nr = r4, nkk = kk4; float nv = vv;
;             if (u + 1 < SCH) { const char* q = lb + (u + 1) * STEPB;
;                 ne = *(const f32x4*)(q); nkd = *(const f32x4*)(q + 256); nka = *(const f32x4*)(q + 512); nr = *(const f32x4*)(q + 768); nkk = *(const f32x4*)(q + 1024);
;                 nv = *(const float*)(vb + (u + 1) * STEPB); }
;             const f32x2 v2 = {vv, vv}, c2 = {c, c};
;             const f32x2 tA = __builtin_elementwise_fma(v2, (f32x2){kd4[0], kd4[1]}, __builtin_elementwise_fma(-sA, (f32x2){e4[0], e4[1]}, sA));
;             const f32x2 tB = __builtin_elementwise_fma(v2, (f32x2){kd4[2], kd4[3]}, __builtin_elementwise_fma(-sB, (f32x2){e4[2], e4[3]}, sB));
;             sA = __builtin_elementwise_fma(-c2, (f32x2){ka4[0], ka4[1]}, tA);
;             sB = __builtin_elementwise_fma(-c2, (f32x2){ka4[2], ka4[3]}, tB);
;             const f32x2 yv = __builtin_elementwise_fma(sB, (f32x2){r4[2], r4[3]}, sA * (f32x2){r4[0], r4[1]});
;             float y = yv[0] + yv[1];
;             if (u + 1 < SCH) {
;                 const f32x2 cv = __builtin_elementwise_fma(sB, (f32x2){nkk[2], nkk[3]}, sA * (f32x2){nkk[0], nkk[1]});
;                 float cn = cv[0] + cv[1];
;                 cn = DPP_ADD(cn, 0xB1);  y = DPP_ADD(y, 0xB1);
;                 cn = DPP_ADD(cn, 0x4E);  y = DPP_ADD(y, 0x4E);
;                 cn = DPP_ADD(cn, 0x141); y = DPP_ADD(y, 0x141);
;                 cn = DPP_ADD(cn, 0x140); y = DPP_ADD(y, 0x140);
;                 c = cn;
;             } else y = red16(y);
;             if (ks == 0) yl[u * 16] = y;
;             e4 = ne; kd4 = nkd; ka4 = nka; r4 = nr; kk4 = nkk; vv = nv;
;         }
	v_pk_mul_f32 v[32:33], v[20:21], v[32:33]
	v_pk_mul_f32 v[64:65], v[20:21], v[64:65]
	v_pk_fma_f32 v[32:33], v[22:23], v[34:35], v[32:33]
	v_pk_fma_f32 v[64:65], v[22:23], v[66:67], v[64:65]
	v_add_f32_e32 v34, v32, v33
	v_add_f32_e32 v66, v64, v65
	v_pk_fma_f32 v[12:13], v[20:21], v[12:13], v[20:21] neg_lo:[1,0,0] neg_hi:[1,0,0]
	v_add_f32_dpp v35, v34, v34 quad_perm:[1,0,3,2] row_mask:0xf bank_mask:0xf bound_ctrl:1
	v_add_f32_dpp v67, v66, v66 quad_perm:[1,0,3,2] row_mask:0xf bank_mask:0xf bound_ctrl:1
	v_pk_fma_f32 v[14:15], v[22:23], v[14:15], v[22:23] neg_lo:[1,0,0] neg_hi:[1,0,0]
	v_add_f32_dpp v34, v35, v35 quad_perm:[2,3,0,1] row_mask:0xf bank_mask:0xf bound_ctrl:1
	v_add_f32_dpp v66, v67, v67 quad_perm:[2,3,0,1] row_mask:0xf bank_mask:0xf bound_ctrl:1
	v_pk_fma_f32 v[12:13], v[36:37], v[16:17], v[12:13] op_sel_hi:[0,1,1]
	v_add_f32_dpp v35, v34, v34 row_half_mirror row_mask:0xf bank_mask:0xf bound_ctrl:1
	v_add_f32_dpp v67, v66, v66 row_half_mirror row_mask:0xf bank_mask:0xf bound_ctrl:1
	v_pk_fma_f32 v[14:15], v[36:37], v[18:19], v[14:15] op_sel_hi:[0,1,1]
	v_add_f32_dpp v90, v35, v35 row_mirror row_mask:0xf bank_mask:0xf bound_ctrl:1
	v_add_f32_dpp v66, v67, v67 row_mirror row_mask:0xf bank_mask:0xf bound_ctrl:1
	ds_write_b32 v37, v66 offset:43328
	ds_read_b128 v[64:67], v91 offset:10176
	v_pk_fma_f32 v[20:21], v[90:91], v[24:25], v[12:13] op_sel_hi:[0,1,1] neg_lo:[1,0,0] neg_hi:[1,0,0]
	v_pk_fma_f32 v[22:23], v[90:91], v[26:27], v[14:15] op_sel_hi:[0,1,1] neg_lo:[1,0,0] neg_hi:[1,0,0]
	ds_read_b128 v[12:15], v91 offset:10752
	ds_read_b128 v[24:27], v91 offset:11264
	ds_read_b128 v[16:19], v91 offset:11008
	ds_read_b128 v[32:35], v91 offset:11776
	ds_read_b32 v36, v92 offset:12032
	s_waitcnt lgkmcnt(7)
	v_pk_mul_f32 v[94:95], v[20:21], v[94:95]
	v_pk_mul_f32 v[28:29], v[20:21], v[28:29]
	v_pk_fma_f32 v[94:95], v[22:23], v[96:97], v[94:95]
	v_pk_fma_f32 v[28:29], v[22:23], v[30:31], v[28:29]
	v_add_f32_e32 v96, v94, v95
	v_add_f32_e32 v30, v28, v29
	v_pk_fma_f32 v[40:41], v[20:21], v[40:41], v[20:21] neg_lo:[1,0,0] neg_hi:[1,0,0]
	v_add_f32_dpp v97, v96, v96 quad_perm:[1,0,3,2] row_mask:0xf bank_mask:0xf bound_ctrl:1
	v_add_f32_dpp v31, v30, v30 quad_perm:[1,0,3,2] row_mask:0xf bank_mask:0xf bound_ctrl:1
	v_pk_fma_f32 v[42:43], v[22:23], v[42:43], v[22:23] neg_lo:[1,0,0] neg_hi:[1,0,0]
	v_add_f32_dpp v96, v97, v97 quad_perm:[2,3,0,1] row_mask:0xf bank_mask:0xf bound_ctrl:1
	v_add_f32_dpp v30, v31, v31 quad_perm:[2,3,0,1] row_mask:0xf bank_mask:0xf bound_ctrl:1
	v_pk_fma_f32 v[40:41], v[38:39], v[44:45], v[40:41] op_sel_hi:[0,1,1]
	v_add_f32_dpp v97, v96, v96 row_half_mirror row_mask:0xf bank_mask:0xf bound_ctrl:1
	v_add_f32_dpp v31, v30, v30 row_half_mirror row_mask:0xf bank_mask:0xf bound_ctrl:1
	v_pk_fma_f32 v[42:43], v[38:39], v[46:47], v[42:43] op_sel_hi:[0,1,1]
	v_add_f32_dpp v90, v97, v97 row_mirror row_mask:0xf bank_mask:0xf bound_ctrl:1
	v_add_f32_dpp v30, v31, v31 row_mirror row_mask:0xf bank_mask:0xf bound_ctrl:1
	ds_write_b32 v37, v30 offset:43392
	ds_read_b128 v[28:31], v91 offset:11520
	v_pk_fma_f32 v[20:21], v[90:91], v[60:61], v[40:41] op_sel_hi:[0,1,1] neg_lo:[1,0,0] neg_hi:[1,0,0]
	v_pk_fma_f32 v[22:23], v[90:91], v[62:63], v[42:43] op_sel_hi:[0,1,1] neg_lo:[1,0,0] neg_hi:[1,0,0]
	ds_read_b128 v[40:43], v91 offset:12096
	ds_read_b128 v[60:63], v91 offset:12608
	ds_read_b128 v[44:47], v91 offset:12352
	ds_read_b128 v[94:97], v91 offset:13120
	ds_read_b32 v38, v92 offset:13376
	s_waitcnt lgkmcnt(7)
	v_pk_mul_f32 v[32:33], v[20:21], v[32:33]
	v_pk_mul_f32 v[64:65], v[20:21], v[64:65]
	v_pk_fma_f32 v[32:33], v[22:23], v[34:35], v[32:33]
	v_pk_fma_f32 v[64:65], v[22:23], v[66:67], v[64:65]
	v_add_f32_e32 v34, v32, v33
	v_add_f32_e32 v66, v64, v65
	v_pk_fma_f32 v[12:13], v[20:21], v[12:13], v[20:21] neg_lo:[1,0,0] neg_hi:[1,0,0]
	v_add_f32_dpp v35, v34, v34 quad_perm:[1,0,3,2] row_mask:0xf bank_mask:0xf bound_ctrl:1
	v_add_f32_dpp v67, v66, v66 quad_perm:[1,0,3,2] row_mask:0xf bank_mask:0xf bound_ctrl:1
	v_pk_fma_f32 v[14:15], v[22:23], v[14:15], v[22:23] neg_lo:[1,0,0] neg_hi:[1,0,0]
	v_add_f32_dpp v34, v35, v35 quad_perm:[2,3,0,1] row_mask:0xf bank_mask:0xf bound_ctrl:1
	v_add_f32_dpp v66, v67, v67 quad_perm:[2,3,0,1] row_mask:0xf bank_mask:0xf bound_ctrl:1
	v_pk_fma_f32 v[12:13], v[36:37], v[16:17], v[12:13] op_sel_hi:[0,1,1]
	v_add_f32_dpp v35, v34, v34 row_half_mirror row_mask:0xf bank_mask:0xf bound_ctrl:1
	v_add_f32_dpp v67, v66, v66 row_half_mirror row_mask:0xf bank_mask:0xf bound_ctrl:1
	v_pk_fma_f32 v[14:15], v[36:37], v[18:19], v[14:15] op_sel_hi:[0,1,1]
	v_add_f32_dpp v90, v35, v35 row_mirror row_mask:0xf bank_mask:0xf bound_ctrl:1
	v_add_f32_dpp v66, v67, v67 row_mirror row_mask:0xf bank_mask:0xf bound_ctrl:1
	ds_write_b32 v37, v66 offset:43456
	ds_read_b128 v[64:67], v91 offset:12864
	v_pk_fma_f32 v[20:21], v[90:91], v[24:25], v[12:13] op_sel_hi:[0,1,1] neg_lo:[1,0,0] neg_hi:[1,0,0]
	v_pk_fma_f32 v[22:23], v[90:91], v[26:27], v[14:15] op_sel_hi:[0,1,1] neg_lo:[1,0,0] neg_hi:[1,0,0]
	ds_read_b128 v[12:15], v91 offset:13440
	ds_read_b128 v[24:27], v91 offset:13952
	ds_read_b128 v[16:19], v91 offset:13696
	ds_read_b128 v[32:35], v91 offset:14464
	ds_read_b32 v36, v92 offset:14720
	s_waitcnt lgkmcnt(7)
; #define DPP_ADD(v, ctrl) ((v) + __builtin_bit_cast(float, __builtin_amdgcn_update_dpp(0, __builtin_bit_cast(int, (v)), (ctrl), 0xf, 0xf, true)))
; __device__ __forceinline__ void rwkv_scan_unit(const Params& p, int unit, char* smem) {
;     ...
;         for (int u = 0; u < SCH; ++u) {
;             f32x4 ne = e4, nkd = kd4, nka = ka4, nr = r4, nkk = kk4; float nv = vv;
;             if (u + 1 < SCH) { const char* q = lb + (u + 1) * STEPB;
;                 ne = *(const f32x4*)(q); nkd = *(const f32x4*)(q + 256); nka = *(const f32x4*)(q + 512); nr = *(const f32x4*)(q + 768); nkk = *(const f32x4*)(q + 1024);
;                 nv = *(const float*)(vb + (u + 1) * STEPB); }
;             const f32x2 v2 = {vv, vv}, c2 = {c, c};
;             const f32x2 tA = __builtin_elementwise_fma(v2, (f32x2){kd4[0], kd4[1]}, __builtin_elementwise_fma(-sA, (f32x2){e4[0], e4[1]}, sA));
;             const f32x2 tB = __builtin_elementwise_fma(v2, (f32x2){kd4[2], kd4[3]}, __builtin_elementwise_fma(-sB, (f32x2){e4[2], e4[3]}, sB));
;             sA = __builtin_elementwise_fma(-c2, (f32x2){ka4[0], ka4[1]}, tA);
;             sB = __builtin_elementwise_fma(-c2, (f32x2){ka4[2], ka4[3]}, tB);
;             const f32x2 yv = __builtin_elementwise_fma(sB, (f32x2){r4[2], r4[3]}, sA * (f32x2){r4[0], r4[1]});
;             float y = yv[0] + yv[1];
;             if (u + 1 < SCH) {
;                 const f32x2 cv = __builtin_elementwise_fma(sB, (f32x2){nkk[2], nkk[3]}, sA * (f32x2){nkk[0], nkk[1]});
;                 float cn = cv[0] + cv[1];
;                 cn = DPP_ADD(cn, 0xB1);  y = DPP_ADD(y, 0xB1);
;                 cn = DPP_ADD(cn, 0x4E);  y = DPP_ADD(y, 0x4E);
;                 cn = DPP_ADD(cn, 0x141); y = DPP_ADD(y, 0x141);
;                 cn = DPP_ADD(cn, 0x140); y = DPP_ADD(y, 0x140);
;                 c = cn;
;             } else y = red16(y);
;             if (ks == 0) yl[u * 16] = y;
;             e4 = ne; kd4 = nkd; ka4 = nka; r4 = nr; kk4 = nkk; vv = nv;
;         }
	v_pk_mul_f32 v[94:95], v[20:21], v[94:95]
	v_pk_mul_f32 v[28:29], v[20:21], v[28:29]
	v_pk_fma_f32 v[94:95], v[22:23], v[96:97], v[94:95]
	v_pk_fma_f32 v[28:29], v[22:23], v[30:31], v[28:29]
	v_add_f32_e32 v96, v94, v95
	v_add_f32_e32 v30, v28, v29
	v_pk_fma_f32 v[40:41], v[20:21], v[40:41], v[20:21] neg_lo:[1,0,0] neg_hi:[1,0,0]
	v_add_f32_dpp v97, v96, v96 quad_perm:[1,0,3,2] row_mask:0xf bank_mask:0xf bound_ctrl:1
	v_add_f32_dpp v31, v30, v30 quad_perm:[1,0,3,2] row_mask:0xf bank_mask:0xf bound_ctrl:1
	v_pk_fma_f32 v[42:43], v[22:23], v[42:43], v[22:23] neg_lo:[1,0,0] neg_hi:[1,0,0]
	v_add_f32_dpp v96, v97, v97 quad_perm:[2,3,0,1] row_mask:0xf bank_mask:0xf bound_ctrl:1
	v_add_f32_dpp v30, v31, v31 quad_perm:[2,3,0,1] row_mask:0xf bank_mask:0xf bound_ctrl:1
	v_pk_fma_f32 v[40:41], v[38:39], v[44:45], v[40:41] op_sel_hi:[0,1,1]
	v_add_f32_dpp v97, v96, v96 row_half_mirror row_mask:0xf bank_mask:0xf bound_ctrl:1
	v_add_f32_dpp v31, v30, v30 row_half_mirror row_mask:0xf bank_mask:0xf bound_ctrl:1
	v_pk_fma_f32 v[42:43], v[38:39], v[46:47], v[42:43] op_sel_hi:[0,1,1]
	v_add_f32_dpp v90, v97, v97 row_mirror row_mask:0xf bank_mask:0xf bound_ctrl:1
	v_add_f32_dpp v30, v31, v31 row_mirror row_mask:0xf bank_mask:0xf bound_ctrl:1
	ds_write_b32 v37, v30 offset:43520
	ds_read_b128 v[28:31], v91 offset:14208
	v_pk_fma_f32 v[20:21], v[90:91], v[60:61], v[40:41] op_sel_hi:[0,1,1] neg_lo:[1,0,0] neg_hi:[1,0,0]
	v_pk_fma_f32 v[22:23], v[90:91], v[62:63], v[42:43] op_sel_hi:[0,1,1] neg_lo:[1,0,0] neg_hi:[1,0,0]
	ds_read_b128 v[40:43], v91 offset:14784
	ds_read_b128 v[60:63], v91 offset:15296
	ds_read_b128 v[44:47], v91 offset:15040
	ds_read_b128 v[94:97], v91 offset:15808
	ds_read_b32 v38, v92 offset:16064
	s_waitcnt lgkmcnt(7)
	v_pk_mul_f32 v[32:33], v[20:21], v[32:33]
	v_pk_mul_f32 v[64:65], v[20:21], v[64:65]
	v_pk_fma_f32 v[32:33], v[22:23], v[34:35], v[32:33]
	v_pk_fma_f32 v[64:65], v[22:23], v[66:67], v[64:65]
	v_add_f32_e32 v34, v32, v33
	v_add_f32_e32 v66, v64, v65
	v_pk_fma_f32 v[12:13], v[20:21], v[12:13], v[20:21] neg_lo:[1,0,0] neg_hi:[1,0,0]
	v_add_f32_dpp v35, v34, v34 quad_perm:[1,0,3,2] row_mask:0xf bank_mask:0xf bound_ctrl:1
	v_add_f32_dpp v67, v66, v66 quad_perm:[1,0,3,2] row_mask:0xf bank_mask:0xf bound_ctrl:1
	v_pk_fma_f32 v[14:15], v[22:23], v[14:15], v[22:23] neg_lo:[1,0,0] neg_hi:[1,0,0]
	v_add_f32_dpp v34, v35, v35 quad_perm:[2,3,0,1] row_mask:0xf bank_mask:0xf bound_ctrl:1
	v_add_f32_dpp v66, v67, v67 quad_perm:[2,3,0,1] row_mask:0xf bank_mask:0xf bound_ctrl:1
	v_pk_fma_f32 v[12:13], v[36:37], v[16:17], v[12:13] op_sel_hi:[0,1,1]
	v_add_f32_dpp v35, v34, v34 row_half_mirror row_mask:0xf bank_mask:0xf bound_ctrl:1
	v_add_f32_dpp v67, v66, v66 row_half_mirror row_mask:0xf bank_mask:0xf bound_ctrl:1
	v_pk_fma_f32 v[14:15], v[36:37], v[18:19], v[14:15] op_sel_hi:[0,1,1]
	v_add_f32_dpp v90, v35, v35 row_mirror row_mask:0xf bank_mask:0xf bound_ctrl:1
	v_add_f32_dpp v66, v67, v67 row_mirror row_mask:0xf bank_mask:0xf bound_ctrl:1
	ds_write_b32 v37, v66 offset:43584
	ds_read_b128 v[64:67], v91 offset:15552
	v_pk_fma_f32 v[20:21], v[90:91], v[24:25], v[12:13] op_sel_hi:[0,1,1] neg_lo:[1,0,0] neg_hi:[1,0,0]
	v_pk_fma_f32 v[22:23], v[90:91], v[26:27], v[14:15] op_sel_hi:[0,1,1] neg_lo:[1,0,0] neg_hi:[1,0,0]
	ds_read_b128 v[12:15], v91 offset:16128
	ds_read_b128 v[24:27], v91 offset:16640
	ds_read_b128 v[16:19], v91 offset:16384
	ds_read_b128 v[32:35], v91 offset:17152
	ds_read_b32 v36, v92 offset:17408
	s_waitcnt lgkmcnt(7)
	v_pk_mul_f32 v[94:95], v[20:21], v[94:95]
	v_pk_mul_f32 v[28:29], v[20:21], v[28:29]
	v_pk_fma_f32 v[94:95], v[22:23], v[96:97], v[94:95]
	v_pk_fma_f32 v[28:29], v[22:23], v[30:31], v[28:29]
	v_add_f32_e32 v96, v94, v95
	v_add_f32_e32 v30, v28, v29
	v_pk_fma_f32 v[40:41], v[20:21], v[40:41], v[20:21] neg_lo:[1,0,0] neg_hi:[1,0,0]
	v_add_f32_dpp v97, v96, v96 quad_perm:[1,0,3,2] row_mask:0xf bank_mask:0xf bound_ctrl:1
	v_add_f32_dpp v31, v30, v30 quad_perm:[1,0,3,2] row_mask:0xf bank_mask:0xf bound_ctrl:1
	v_pk_fma_f32 v[42:43], v[22:23], v[42:43], v[22:23] neg_lo:[1,0,0] neg_hi:[1,0,0]
	v_add_f32_dpp v96, v97, v97 quad_perm:[2,3,0,1] row_mask:0xf bank_mask:0xf bound_ctrl:1
	v_add_f32_dpp v30, v31, v31 quad_perm:[2,3,0,1] row_mask:0xf bank_mask:0xf bound_ctrl:1
	v_pk_fma_f32 v[40:41], v[38:39], v[44:45], v[40:41] op_sel_hi:[0,1,1]
	v_add_f32_dpp v97, v96, v96 row_half_mirror row_mask:0xf bank_mask:0xf bound_ctrl:1
	v_add_f32_dpp v31, v30, v30 row_half_mirror row_mask:0xf bank_mask:0xf bound_ctrl:1
	v_pk_fma_f32 v[42:43], v[38:39], v[46:47], v[42:43] op_sel_hi:[0,1,1]
	v_add_f32_dpp v90, v97, v97 row_mirror row_mask:0xf bank_mask:0xf bound_ctrl:1
	v_add_f32_dpp v30, v31, v31 row_mirror row_mask:0xf bank_mask:0xf bound_ctrl:1
	ds_write_b32 v37, v30 offset:43648
	ds_read_b128 v[28:31], v91 offset:16896
	v_pk_fma_f32 v[20:21], v[90:91], v[60:61], v[40:41] op_sel_hi:[0,1,1] neg_lo:[1,0,0] neg_hi:[1,0,0]
	v_pk_fma_f32 v[22:23], v[90:91], v[62:63], v[42:43] op_sel_hi:[0,1,1] neg_lo:[1,0,0] neg_hi:[1,0,0]
	ds_read_b128 v[40:43], v91 offset:17472
	ds_read_b128 v[60:63], v91 offset:17984
	ds_read_b128 v[44:47], v91 offset:17728
	ds_read_b128 v[94:97], v91 offset:18496
	ds_read_b32 v38, v92 offset:18752
	s_waitcnt lgkmcnt(7)
; #define DPP_ADD(v, ctrl) ((v) + __builtin_bit_cast(float, __builtin_amdgcn_update_dpp(0, __builtin_bit_cast(int, (v)), (ctrl), 0xf, 0xf, true)))
; __device__ __forceinline__ void rwkv_scan_unit(const Params& p, int unit, char* smem) {
;     ...
;         for (int u = 0; u < SCH; ++u) {
;             f32x4 ne = e4, nkd = kd4, nka = ka4, nr = r4, nkk = kk4; float nv = vv;
;             if (u + 1 < SCH) { const char* q = lb + (u + 1) * STEPB;
;                 ne = *(const f32x4*)(q); nkd = *(const f32x4*)(q + 256); nka = *(const f32x4*)(q + 512); nr = *(const f32x4*)(q + 768); nkk = *(const f32x4*)(q + 1024);
;                 nv = *(const float*)(vb + (u + 1) * STEPB); }
;             const f32x2 v2 = {vv, vv}, c2 = {c, c};
;             const f32x2 tA = __builtin_elementwise_fma(v2, (f32x2){kd4[0], kd4[1]}, __builtin_elementwise_fma(-sA, (f32x2){e4[0], e4[1]}, sA));
;             const f32x2 tB = __builtin_elementwise_fma(v2, (f32x2){kd4[2], kd4[3]}, __builtin_elementwise_fma(-sB, (f32x2){e4[2], e4[3]}, sB));
;             sA = __builtin_elementwise_fma(-c2, (f32x2){ka4[0], ka4[1]}, tA);
;             sB = __builtin_elementwise_fma(-c2, (f32x2){ka4[2], ka4[3]}, tB);
;             const f32x2 yv = __builtin_elementwise_fma(sB, (f32x2){r4[2], r4[3]}, sA * (f32x2){r4[0], r4[1]});
;             float y = yv[0] + yv[1];
;             if (u + 1 < SCH) {
;                 const f32x2 cv = __builtin_elementwise_fma(sB, (f32x2){nkk[2], nkk[3]}, sA * (f32x2){nkk[0], nkk[1]});
;                 float cn = cv[0] + cv[1];
;                 cn = DPP_ADD(cn, 0xB1);  y = DPP_ADD(y, 0xB1);
;                 cn = DPP_ADD(cn, 0x4E);  y = DPP_ADD(y, 0x4E);
;                 cn = DPP_ADD(cn, 0x141); y = DPP_ADD(y, 0x141);
;                 cn = DPP_ADD(cn, 0x140); y = DPP_ADD(y, 0x140);
;                 c = cn;
;             } else y = red16(y);
;             if (ks == 0) yl[u * 16] = y;
;             e4 = ne; kd4 = nkd; ka4 = nka; r4 = nr; kk4 = nkk; vv = nv;
;         }
	v_pk_mul_f32 v[32:33], v[20:21], v[32:33]
	v_pk_mul_f32 v[64:65], v[20:21], v[64:65]
	v_pk_fma_f32 v[32:33], v[22:23], v[34:35], v[32:33]
	v_pk_fma_f32 v[64:65], v[22:23], v[66:67], v[64:65]
	v_add_f32_e32 v34, v32, v33
	v_add_f32_e32 v66, v64, v65
	v_pk_fma_f32 v[12:13], v[20:21], v[12:13], v[20:21] neg_lo:[1,0,0] neg_hi:[1,0,0]
	v_add_f32_dpp v35, v34, v34 quad_perm:[1,0,3,2] row_mask:0xf bank_mask:0xf bound_ctrl:1
	v_add_f32_dpp v67, v66, v66 quad_perm:[1,0,3,2] row_mask:0xf bank_mask:0xf bound_ctrl:1
	v_pk_fma_f32 v[14:15], v[22:23], v[14:15], v[22:23] neg_lo:[1,0,0] neg_hi:[1,0,0]
	v_add_f32_dpp v34, v35, v35 quad_perm:[2,3,0,1] row_mask:0xf bank_mask:0xf bound_ctrl:1
	v_add_f32_dpp v66, v67, v67 quad_perm:[2,3,0,1] row_mask:0xf bank_mask:0xf bound_ctrl:1
	v_pk_fma_f32 v[12:13], v[36:37], v[16:17], v[12:13] op_sel_hi:[0,1,1]
	v_add_f32_dpp v35, v34, v34 row_half_mirror row_mask:0xf bank_mask:0xf bound_ctrl:1
	v_add_f32_dpp v67, v66, v66 row_half_mirror row_mask:0xf bank_mask:0xf bound_ctrl:1
	v_pk_fma_f32 v[14:15], v[36:37], v[18:19], v[14:15] op_sel_hi:[0,1,1]
	v_add_f32_dpp v90, v35, v35 row_mirror row_mask:0xf bank_mask:0xf bound_ctrl:1
	v_add_f32_dpp v66, v67, v67 row_mirror row_mask:0xf bank_mask:0xf bound_ctrl:1
	ds_write_b32 v37, v66 offset:43712
	ds_read_b128 v[64:67], v91 offset:18240
	v_pk_fma_f32 v[20:21], v[90:91], v[24:25], v[12:13] op_sel_hi:[0,1,1] neg_lo:[1,0,0] neg_hi:[1,0,0]
	v_pk_fma_f32 v[22:23], v[90:91], v[26:27], v[14:15] op_sel_hi:[0,1,1] neg_lo:[1,0,0] neg_hi:[1,0,0]
	ds_read_b128 v[12:15], v91 offset:18816
	ds_read_b128 v[24:27], v91 offset:19328
	ds_read_b128 v[16:19], v91 offset:19072
	ds_read_b128 v[32:35], v91 offset:19840
	ds_read_b32 v36, v92 offset:20096
	s_waitcnt lgkmcnt(7)
	v_pk_mul_f32 v[94:95], v[20:21], v[94:95]
	v_pk_mul_f32 v[28:29], v[20:21], v[28:29]
	v_pk_fma_f32 v[94:95], v[22:23], v[96:97], v[94:95]
	v_pk_fma_f32 v[28:29], v[22:23], v[30:31], v[28:29]
	v_add_f32_e32 v96, v94, v95
	v_add_f32_e32 v30, v28, v29
	v_pk_fma_f32 v[40:41], v[20:21], v[40:41], v[20:21] neg_lo:[1,0,0] neg_hi:[1,0,0]
	v_add_f32_dpp v97, v96, v96 quad_perm:[1,0,3,2] row_mask:0xf bank_mask:0xf bound_ctrl:1
	v_add_f32_dpp v31, v30, v30 quad_perm:[1,0,3,2] row_mask:0xf bank_mask:0xf bound_ctrl:1
	v_pk_fma_f32 v[42:43], v[22:23], v[42:43], v[22:23] neg_lo:[1,0,0] neg_hi:[1,0,0]
	v_add_f32_dpp v96, v97, v97 quad_perm:[2,3,0,1] row_mask:0xf bank_mask:0xf bound_ctrl:1
	v_add_f32_dpp v30, v31, v31 quad_perm:[2,3,0,1] row_mask:0xf bank_mask:0xf bound_ctrl:1
	v_pk_fma_f32 v[40:41], v[38:39], v[44:45], v[40:41] op_sel_hi:[0,1,1]
	v_add_f32_dpp v97, v96, v96 row_half_mirror row_mask:0xf bank_mask:0xf bound_ctrl:1
	v_add_f32_dpp v31, v30, v30 row_half_mirror row_mask:0xf bank_mask:0xf bound_ctrl:1
	v_pk_fma_f32 v[42:43], v[38:39], v[46:47], v[42:43] op_sel_hi:[0,1,1]
	v_add_f32_dpp v90, v97, v97 row_mirror row_mask:0xf bank_mask:0xf bound_ctrl:1
	v_add_f32_dpp v30, v31, v31 row_mirror row_mask:0xf bank_mask:0xf bound_ctrl:1
	ds_write_b32 v37, v30 offset:43776
	ds_read_b128 v[28:31], v91 offset:19584
	v_pk_fma_f32 v[20:21], v[90:91], v[60:61], v[40:41] op_sel_hi:[0,1,1] neg_lo:[1,0,0] neg_hi:[1,0,0]
	v_pk_fma_f32 v[22:23], v[90:91], v[62:63], v[42:43] op_sel_hi:[0,1,1] neg_lo:[1,0,0] neg_hi:[1,0,0]
	ds_read_b128 v[40:43], v91 offset:20160
	ds_read_b128 v[60:63], v91 offset:20672
	ds_read_b128 v[44:47], v91 offset:20416
	ds_read_b128 v[94:97], v91 offset:21184
	ds_read_b32 v38, v92 offset:21440
	s_waitcnt lgkmcnt(7)
	v_pk_mul_f32 v[32:33], v[20:21], v[32:33]
	v_pk_mul_f32 v[64:65], v[20:21], v[64:65]
	v_pk_fma_f32 v[32:33], v[22:23], v[34:35], v[32:33]
	v_pk_fma_f32 v[64:65], v[22:23], v[66:67], v[64:65]
	v_add_f32_e32 v34, v32, v33
	v_add_f32_e32 v66, v64, v65
	v_pk_fma_f32 v[12:13], v[20:21], v[12:13], v[20:21] neg_lo:[1,0,0] neg_hi:[1,0,0]
	v_add_f32_dpp v35, v34, v34 quad_perm:[1,0,3,2] row_mask:0xf bank_mask:0xf bound_ctrl:1
	v_add_f32_dpp v67, v66, v66 quad_perm:[1,0,3,2] row_mask:0xf bank_mask:0xf bound_ctrl:1
	v_pk_fma_f32 v[14:15], v[22:23], v[14:15], v[22:23] neg_lo:[1,0,0] neg_hi:[1,0,0]
	v_add_f32_dpp v34, v35, v35 quad_perm:[2,3,0,1] row_mask:0xf bank_mask:0xf bound_ctrl:1
	v_add_f32_dpp v66, v67, v67 quad_perm:[2,3,0,1] row_mask:0xf bank_mask:0xf bound_ctrl:1
	v_pk_fma_f32 v[12:13], v[36:37], v[16:17], v[12:13] op_sel_hi:[0,1,1]
	v_add_f32_dpp v35, v34, v34 row_half_mirror row_mask:0xf bank_mask:0xf bound_ctrl:1
	v_add_f32_dpp v67, v66, v66 row_half_mirror row_mask:0xf bank_mask:0xf bound_ctrl:1
	v_pk_fma_f32 v[14:15], v[36:37], v[18:19], v[14:15] op_sel_hi:[0,1,1]
	v_add_f32_dpp v90, v35, v35 row_mirror row_mask:0xf bank_mask:0xf bound_ctrl:1
	v_add_f32_dpp v66, v67, v67 row_mirror row_mask:0xf bank_mask:0xf bound_ctrl:1
	ds_write_b32 v37, v66 offset:43840
	ds_read_b128 v[64:67], v91 offset:20928
	v_pk_fma_f32 v[20:21], v[90:91], v[24:25], v[12:13] op_sel_hi:[0,1,1] neg_lo:[1,0,0] neg_hi:[1,0,0]
	v_pk_fma_f32 v[22:23], v[90:91], v[26:27], v[14:15] op_sel_hi:[0,1,1] neg_lo:[1,0,0] neg_hi:[1,0,0]
	s_waitcnt lgkmcnt(2)
; #define DPP_ADD(v, ctrl) ((v) + __builtin_bit_cast(float, __builtin_amdgcn_update_dpp(0, __builtin_bit_cast(int, (v)), (ctrl), 0xf, 0xf, true)))
; #define SC_LSTORE(st_) { SC_S1(st_, 0, rg0) SC_S1(st_, 1, rg1) SC_S1(st_, 2, rg2) }
; __device__ __forceinline__ void rwkv_scan_unit(const Params& p, int unit, char* smem) {
;     ...
;         for (int u = 0; u < SCH; ++u) {
;             f32x4 ne = e4, nkd = kd4, nka = ka4, nr = r4, nkk = kk4; float nv = vv;
;             if (u + 1 < SCH) { const char* q = lb + (u + 1) * STEPB;
;                 ne = *(const f32x4*)(q); nkd = *(const f32x4*)(q + 256); nka = *(const f32x4*)(q + 512); nr = *(const f32x4*)(q + 768); nkk = *(const f32x4*)(q + 1024);
;                 nv = *(const float*)(vb + (u + 1) * STEPB); }
;             const f32x2 v2 = {vv, vv}, c2 = {c, c};
;             const f32x2 tA = __builtin_elementwise_fma(v2, (f32x2){kd4[0], kd4[1]}, __builtin_elementwise_fma(-sA, (f32x2){e4[0], e4[1]}, sA));
;             const f32x2 tB = __builtin_elementwise_fma(v2, (f32x2){kd4[2], kd4[3]}, __builtin_elementwise_fma(-sB, (f32x2){e4[2], e4[3]}, sB));
;             sA = __builtin_elementwise_fma(-c2, (f32x2){ka4[0], ka4[1]}, tA);
;             sB = __builtin_elementwise_fma(-c2, (f32x2){ka4[2], ka4[3]}, tB);
;             const f32x2 yv = __builtin_elementwise_fma(sB, (f32x2){r4[2], r4[3]}, sA * (f32x2){r4[0], r4[1]});
;             float y = yv[0] + yv[1];
;             if (u + 1 < SCH) {
;                 const f32x2 cv = __builtin_elementwise_fma(sB, (f32x2){nkk[2], nkk[3]}, sA * (f32x2){nkk[0], nkk[1]});
;                 float cn = cv[0] + cv[1];
;                 cn = DPP_ADD(cn, 0xB1);  y = DPP_ADD(y, 0xB1);
;                 cn = DPP_ADD(cn, 0x4E);  y = DPP_ADD(y, 0x4E);
;                 cn = DPP_ADD(cn, 0x141); y = DPP_ADD(y, 0x141);
;                 cn = DPP_ADD(cn, 0x140); y = DPP_ADD(y, 0x140);
;                 c = cn;
;             } else y = red16(y);
;             if (ks == 0) yl[u * 16] = y;
;             e4 = ne; kd4 = nkd; ka4 = nka; r4 = nr; kk4 = nkk; vv = nv;
;         }
;         s0 = sA[0]; s1 = sA[1]; s2 = sB[0]; s3 = sB[1];
;         __builtin_amdgcn_sched_barrier(0);
;         if (ci + 1 < NCH) { SC_LSTORE(((ci + 1) & 1) * STG) }
	v_pk_mul_f32 v[94:95], v[20:21], v[94:95]
	v_pk_mul_f32 v[28:29], v[20:21], v[28:29]
	v_pk_fma_f32 v[94:95], v[22:23], v[96:97], v[94:95]
	v_pk_fma_f32 v[28:29], v[22:23], v[30:31], v[28:29]
	v_add_f32_e32 v96, v94, v95
	v_add_f32_e32 v30, v28, v29
	v_pk_fma_f32 v[40:41], v[20:21], v[40:41], v[20:21] neg_lo:[1,0,0] neg_hi:[1,0,0]
	v_add_f32_dpp v97, v96, v96 quad_perm:[1,0,3,2] row_mask:0xf bank_mask:0xf bound_ctrl:1
	v_add_f32_dpp v31, v30, v30 quad_perm:[1,0,3,2] row_mask:0xf bank_mask:0xf bound_ctrl:1
	v_pk_fma_f32 v[42:43], v[22:23], v[42:43], v[22:23] neg_lo:[1,0,0] neg_hi:[1,0,0]
	v_add_f32_dpp v96, v97, v97 quad_perm:[2,3,0,1] row_mask:0xf bank_mask:0xf bound_ctrl:1
	v_add_f32_dpp v30, v31, v31 quad_perm:[2,3,0,1] row_mask:0xf bank_mask:0xf bound_ctrl:1
	v_pk_fma_f32 v[40:41], v[38:39], v[44:45], v[40:41] op_sel_hi:[0,1,1]
	v_add_f32_dpp v97, v96, v96 row_half_mirror row_mask:0xf bank_mask:0xf bound_ctrl:1
	v_add_f32_dpp v31, v30, v30 row_half_mirror row_mask:0xf bank_mask:0xf bound_ctrl:1
	v_pk_fma_f32 v[42:43], v[38:39], v[46:47], v[42:43] op_sel_hi:[0,1,1]
	v_add_f32_dpp v90, v97, v97 row_mirror row_mask:0xf bank_mask:0xf bound_ctrl:1
	v_add_f32_dpp v30, v31, v31 row_mirror row_mask:0xf bank_mask:0xf bound_ctrl:1
	ds_write_b32 v37, v30 offset:43904
	v_pk_fma_f32 v[20:21], v[90:91], v[60:61], v[40:41] op_sel_hi:[0,1,1] neg_lo:[1,0,0] neg_hi:[1,0,0]
	v_pk_fma_f32 v[22:23], v[90:91], v[62:63], v[42:43] op_sel_hi:[0,1,1] neg_lo:[1,0,0] neg_hi:[1,0,0]
	s_waitcnt lgkmcnt(1)
	v_pk_mul_f32 v[64:65], v[20:21], v[64:65]
	v_pk_fma_f32 v[64:65], v[22:23], v[66:67], v[64:65]
	s_nop 0
	v_add_f32_e32 v66, v64, v65
	s_nop 1
	v_add_f32_dpp v67, v66, v66 quad_perm:[1,0,3,2] row_mask:0xf bank_mask:0xf bound_ctrl:1
	s_nop 1
	v_add_f32_dpp v66, v67, v67 quad_perm:[2,3,0,1] row_mask:0xf bank_mask:0xf bound_ctrl:1
	s_nop 1
	v_add_f32_dpp v67, v66, v66 row_half_mirror row_mask:0xf bank_mask:0xf bound_ctrl:1
	s_nop 1
	v_add_f32_dpp v66, v67, v67 row_mirror row_mask:0xf bank_mask:0xf bound_ctrl:1
	ds_write_b32 v37, v66 offset:43968
	s_bitcmp1_b32 s64, 0
	s_cselect_b32 s0, 0x5400, 0
	s_waitcnt vmcnt(13)
	v_add3_u32 v16, s0, v74, v75
	v_cvt_f32_f16_sdwa v13, v124 dst_sel:DWORD dst_unused:UNUSED_PAD src0_sel:WORD_1
	v_cvt_f32_f16_e32 v12, v124
	v_cvt_f32_f16_sdwa v15, v125 dst_sel:DWORD dst_unused:UNUSED_PAD src0_sel:WORD_1
	v_cvt_f32_f16_e32 v14, v125
	ds_write_b128 v16, v[12:15]
	v_cvt_f32_f16_sdwa v13, v126 dst_sel:DWORD dst_unused:UNUSED_PAD src0_sel:WORD_1
	v_cvt_f32_f16_e32 v12, v126
	v_cvt_f32_f16_sdwa v15, v127 dst_sel:DWORD dst_unused:UNUSED_PAD src0_sel:WORD_1
	v_cvt_f32_f16_e32 v14, v127
	ds_write_b128 v16, v[12:15] offset:16
	v_add3_u32 v16, s0, v76, v77
	v_cvt_f32_f16_sdwa v13, v128 dst_sel:DWORD dst_unused:UNUSED_PAD src0_sel:WORD_1
	v_cvt_f32_f16_e32 v12, v128
	v_cvt_f32_f16_sdwa v15, v129 dst_sel:DWORD dst_unused:UNUSED_PAD src0_sel:WORD_1
	v_cvt_f32_f16_e32 v14, v129
	ds_write_b128 v16, v[12:15]
	v_cvt_f32_f16_sdwa v13, v130 dst_sel:DWORD dst_unused:UNUSED_PAD src0_sel:WORD_1
	v_cvt_f32_f16_e32 v12, v130
	v_cvt_f32_f16_sdwa v15, v131 dst_sel:DWORD dst_unused:UNUSED_PAD src0_sel:WORD_1
	v_cvt_f32_f16_e32 v14, v131
	ds_write_b128 v16, v[12:15] offset:16
	v_add3_u32 v16, s0, v78, v79
	v_cvt_f32_f16_sdwa v13, v132 dst_sel:DWORD dst_unused:UNUSED_PAD src0_sel:WORD_1
	v_cvt_f32_f16_e32 v12, v132
	v_cvt_f32_f16_sdwa v15, v133 dst_sel:DWORD dst_unused:UNUSED_PAD src0_sel:WORD_1
	v_cvt_f32_f16_e32 v14, v133
	ds_write_b128 v16, v[12:15]
	v_cvt_f32_f16_sdwa v13, v134 dst_sel:DWORD dst_unused:UNUSED_PAD src0_sel:WORD_1
	v_cvt_f32_f16_e32 v12, v134
	v_cvt_f32_f16_sdwa v15, v135 dst_sel:DWORD dst_unused:UNUSED_PAD src0_sel:WORD_1
	v_cvt_f32_f16_e32 v14, v135
	ds_write_b128 v16, v[12:15] offset:16

; __device__ __forceinline__ void rwkv_scan_unit(const Params& p, int unit, char* smem) {
;     ...
;         const char* lb = smem + st + ks * 16;
;         const char* vb = smem + st + 1280 + rl * 4;
;         float* yl = (float*)(smem + YOFF + (ci & 1) * 1024) + rl;
;         f32x4 e4 = *(const f32x4*)(lb), kd4 = *(const f32x4*)(lb + 256), ka4 = *(const f32x4*)(lb + 512), r4 = *(const f32x4*)(lb + 768), kk4 = *(const f32x4*)(lb + 1024);
;         float vv = *(const float*)vb;
;         f32x2 sA = {s0, s1}, sB = {s2, s3};
;         float c;
;         { const f32x2 cv = sA * (f32x2){kk4[0], kk4[1]} + sB * (f32x2){kk4[2], kk4[3]}; c = red16(cv[0] + cv[1]); }
; #pragma unroll
;         for (int u = 0; u < SCH; ++u) {
;             f32x4 ne = e4, nkd = kd4, nka = ka4, nr = r4, nkk = kk4; float nv = vv;
;             if (u + 1 < SCH) { const char* q = lb + (u + 1) * STEPB;
;                 ne = *(const f32x4*)(q); nkd = *(const f32x4*)(q + 256); nka = *(const f32x4*)(q + 512); nr = *(const f32x4*)(q + 768); nkk = *(const f32x4*)(q + 1024);
;                 nv = *(const float*)(vb + (u + 1) * STEPB); }
;             const f32x2 v2 = {vv, vv}, c2 = {c, c};
;             const f32x2 tA = __builtin_elementwise_fma(v2, (f32x2){kd4[0], kd4[1]}, __builtin_elementwise_fma(-sA, (f32x2){e4[0], e4[1]}, sA));
;             const f32x2 tB = __builtin_elementwise_fma(v2, (f32x2){kd4[2], kd4[3]}, __builtin_elementwise_fma(-sB, (f32x2){e4[2], e4[3]}, sB));
;             sA = __builtin_elementwise_fma(-c2, (f32x2){ka4[0], ka4[1]}, tA);
;             sB = __builtin_elementwise_fma(-c2, (f32x2){ka4[2], ka4[3]}, tB);
;             const f32x2 yv = __builtin_elementwise_fma(sB, (f32x2){r4[2], r4[3]}, sA * (f32x2){r4[0], r4[1]});
;             float y = yv[0] + yv[1];
;             if (u + 1 < SCH) {
;                 const f32x2 cv = __builtin_elementwise_fma(sB, (f32x2){nkk[2], nkk[3]}, sA * (f32x2){nkk[0], nkk[1]});
;                 float cn = cv[0] + cv[1];
;                 cn = DPP_ADD(cn, 0xB1);  y = DPP_ADD(y, 0xB1);
;                 cn = DPP_ADD(cn, 0x4E);  y = DPP_ADD(y, 0x4E);
;                 cn = DPP_ADD(cn, 0x141); y = DPP_ADD(y, 0x141);
;                 cn = DPP_ADD(cn, 0x140); y = DPP_ADD(y, 0x140);
;                 c = cn;
;             } else y = red16(y);
;             if (ks == 0) yl[u * 16] = y;
.Lsc_p3_body:
	s_add_i32 s30, s64, -1
	s_and_b32 s30, s30, 1
	s_mul_i32 s52, s30, 0x5400
	v_or_b32_e32 v91, s52, v80
	v_add_u32_e32 v92, s52, v81
	ds_read_b128 v[32:35], v91 offset:1024
	ds_read_b128 v[12:15], v91 offset:0
	ds_read_b128 v[16:19], v91 offset:256
	ds_read_b32 v36, v92 offset:1280
	ds_read_b128 v[24:27], v91 offset:512
	ds_read_b128 v[28:31], v91 offset:768
	ds_read_b128 v[40:43], v91 offset:1344
	ds_read_b128 v[60:63], v91 offset:1856
	ds_read_b128 v[44:47], v91 offset:1600
	ds_read_b128 v[94:97], v91 offset:2368
	ds_read_b32 v38, v92 offset:2624
	ds_read_b128 v[64:67], v91 offset:2112
	s_waitcnt lgkmcnt(12)
	v_bfe_u32 v247, v246, 16, 1
	s_movk_i32 s0, 0x7fff
	v_add3_u32 v247, v246, v247, s0
	global_store_short_d16_hi v[244:245], v247, off
	s_lshl_b32 s52, s30, 10
	v_lshl_add_u32 v37, v72, 2, s52
	v_lshlrev_b32_e32 v90, 2, v109
	v_add_u32_e32 v90, 0x800, v90
	v_cndmask_b32_e64 v37, v90, v37, s[50:51]
	s_waitcnt lgkmcnt(11)
	v_pk_mul_f32 v[32:33], v[20:21], v[32:33]
	s_waitcnt lgkmcnt(10)
	v_pk_fma_f32 v[12:13], v[20:21], v[12:13], v[20:21] neg_lo:[1,0,0] neg_hi:[1,0,0]
	v_pk_fma_f32 v[32:33], v[22:23], v[34:35], v[32:33]
	v_pk_fma_f32 v[14:15], v[22:23], v[14:15], v[22:23] neg_lo:[1,0,0] neg_hi:[1,0,0]
	v_add_f32_e32 v34, v32, v33
	s_waitcnt lgkmcnt(8)
	v_pk_fma_f32 v[12:13], v[36:37], v[16:17], v[12:13] op_sel_hi:[0,1,1]
	v_pk_fma_f32 v[14:15], v[36:37], v[18:19], v[14:15] op_sel_hi:[0,1,1]
	v_add_f32_dpp v35, v34, v34 quad_perm:[1,0,3,2] row_mask:0xf bank_mask:0xf bound_ctrl:1
	s_nop 1
	v_add_f32_dpp v34, v35, v35 quad_perm:[2,3,0,1] row_mask:0xf bank_mask:0xf bound_ctrl:1
	s_nop 1
	v_add_f32_dpp v35, v34, v34 row_half_mirror row_mask:0xf bank_mask:0xf bound_ctrl:1
	s_nop 1
	v_add_f32_dpp v90, v35, v35 row_mirror row_mask:0xf bank_mask:0xf bound_ctrl:1
	ds_read_b128 v[16:19], v91 offset:2944
	ds_read_b128 v[32:35], v91 offset:3712
	ds_read_b32 v36, v92 offset:3968
	s_waitcnt lgkmcnt(10)
	v_pk_fma_f32 v[20:21], v[90:91], v[24:25], v[12:13] op_sel_hi:[0,1,1] neg_lo:[1,0,0] neg_hi:[1,0,0]
	v_pk_fma_f32 v[22:23], v[90:91], v[26:27], v[14:15] op_sel_hi:[0,1,1] neg_lo:[1,0,0] neg_hi:[1,0,0]
	ds_read_b128 v[12:15], v91 offset:2688
	ds_read_b128 v[24:27], v91 offset:3200
	s_waitcnt lgkmcnt(7)
	v_pk_mul_f32 v[94:95], v[20:21], v[94:95]
	v_pk_mul_f32 v[28:29], v[20:21], v[28:29]
	v_pk_fma_f32 v[94:95], v[22:23], v[96:97], v[94:95]
	v_pk_fma_f32 v[28:29], v[22:23], v[30:31], v[28:29]
	v_add_f32_e32 v96, v94, v95
	v_add_f32_e32 v30, v28, v29
	v_pk_fma_f32 v[40:41], v[20:21], v[40:41], v[20:21] neg_lo:[1,0,0] neg_hi:[1,0,0]
	v_add_f32_dpp v97, v96, v96 quad_perm:[1,0,3,2] row_mask:0xf bank_mask:0xf bound_ctrl:1
	v_add_f32_dpp v31, v30, v30 quad_perm:[1,0,3,2] row_mask:0xf bank_mask:0xf bound_ctrl:1
	v_pk_fma_f32 v[42:43], v[22:23], v[42:43], v[22:23] neg_lo:[1,0,0] neg_hi:[1,0,0]
	v_add_f32_dpp v96, v97, v97 quad_perm:[2,3,0,1] row_mask:0xf bank_mask:0xf bound_ctrl:1
	v_add_f32_dpp v30, v31, v31 quad_perm:[2,3,0,1] row_mask:0xf bank_mask:0xf bound_ctrl:1
	s_waitcnt lgkmcnt(6)
	v_pk_fma_f32 v[40:41], v[38:39], v[44:45], v[40:41] op_sel_hi:[0,1,1]
	v_add_f32_dpp v97, v96, v96 row_half_mirror row_mask:0xf bank_mask:0xf bound_ctrl:1
	v_add_f32_dpp v31, v30, v30 row_half_mirror row_mask:0xf bank_mask:0xf bound_ctrl:1
	v_pk_fma_f32 v[42:43], v[38:39], v[46:47], v[42:43] op_sel_hi:[0,1,1]
	v_add_f32_dpp v90, v97, v97 row_mirror row_mask:0xf bank_mask:0xf bound_ctrl:1
	v_add_f32_dpp v30, v31, v31 row_mirror row_mask:0xf bank_mask:0xf bound_ctrl:1
	ds_write_b32 v37, v30 offset:43008
	ds_read_b128 v[28:31], v91 offset:3456
	v_pk_fma_f32 v[20:21], v[90:91], v[60:61], v[40:41] op_sel_hi:[0,1,1] neg_lo:[1,0,0] neg_hi:[1,0,0]
	v_pk_fma_f32 v[22:23], v[90:91], v[62:63], v[42:43] op_sel_hi:[0,1,1] neg_lo:[1,0,0] neg_hi:[1,0,0]
	ds_read_b128 v[40:43], v91 offset:4032
	ds_read_b128 v[60:63], v91 offset:4544
	ds_read_b128 v[44:47], v91 offset:4288
	ds_read_b128 v[94:97], v91 offset:5056
	ds_read_b32 v38, v92 offset:5312
	s_waitcnt lgkmcnt(8)
	v_pk_mul_f32 v[32:33], v[20:21], v[32:33]
	v_pk_mul_f32 v[64:65], v[20:21], v[64:65]
	v_pk_fma_f32 v[32:33], v[22:23], v[34:35], v[32:33]
	v_pk_fma_f32 v[64:65], v[22:23], v[66:67], v[64:65]
	v_add_f32_e32 v34, v32, v33
	v_add_f32_e32 v66, v64, v65
	v_pk_fma_f32 v[12:13], v[20:21], v[12:13], v[20:21] neg_lo:[1,0,0] neg_hi:[1,0,0]
	v_add_f32_dpp v35, v34, v34 quad_perm:[1,0,3,2] row_mask:0xf bank_mask:0xf bound_ctrl:1
	v_add_f32_dpp v67, v66, v66 quad_perm:[1,0,3,2] row_mask:0xf bank_mask:0xf bound_ctrl:1
	v_pk_fma_f32 v[14:15], v[22:23], v[14:15], v[22:23] neg_lo:[1,0,0] neg_hi:[1,0,0]
	v_add_f32_dpp v34, v35, v35 quad_perm:[2,3,0,1] row_mask:0xf bank_mask:0xf bound_ctrl:1
	v_add_f32_dpp v66, v67, v67 quad_perm:[2,3,0,1] row_mask:0xf bank_mask:0xf bound_ctrl:1
	v_pk_fma_f32 v[12:13], v[36:37], v[16:17], v[12:13] op_sel_hi:[0,1,1]
	v_add_f32_dpp v35, v34, v34 row_half_mirror row_mask:0xf bank_mask:0xf bound_ctrl:1
	v_add_f32_dpp v67, v66, v66 row_half_mirror row_mask:0xf bank_mask:0xf bound_ctrl:1
	v_pk_fma_f32 v[14:15], v[36:37], v[18:19], v[14:15] op_sel_hi:[0,1,1]
	v_add_f32_dpp v90, v35, v35 row_mirror row_mask:0xf bank_mask:0xf bound_ctrl:1
	v_add_f32_dpp v66, v67, v67 row_mirror row_mask:0xf bank_mask:0xf bound_ctrl:1
	ds_write_b32 v37, v66 offset:43072
	ds_read_b128 v[64:67], v91 offset:4800
	s_waitcnt lgkmcnt(9)
	v_pk_fma_f32 v[20:21], v[90:91], v[24:25], v[12:13] op_sel_hi:[0,1,1] neg_lo:[1,0,0] neg_hi:[1,0,0]
	v_pk_fma_f32 v[22:23], v[90:91], v[26:27], v[14:15] op_sel_hi:[0,1,1] neg_lo:[1,0,0] neg_hi:[1,0,0]
	ds_read_b128 v[12:15], v91 offset:5376
	ds_read_b128 v[24:27], v91 offset:5888
	ds_read_b128 v[16:19], v91 offset:5632
	ds_read_b128 v[32:35], v91 offset:6400
	ds_read_b32 v36, v92 offset:6656
	s_waitcnt lgkmcnt(7)
; #define DPP_ADD(v, ctrl) ((v) + __builtin_bit_cast(float, __builtin_amdgcn_update_dpp(0, __builtin_bit_cast(int, (v)), (ctrl), 0xf, 0xf, true)))
; __device__ __forceinline__ void rwkv_scan_unit(const Params& p, int unit, char* smem) {
;     ...
;         for (int u = 0; u < SCH; ++u) {
;             f32x4 ne = e4, nkd = kd4, nka = ka4, nr = r4, nkk = kk4; float nv = vv;
;             if (u + 1 < SCH) { const char* q = lb + (u + 1) * STEPB;
;                 ne = *(const f32x4*)(q); nkd = *(const f32x4*)(q + 256); nka = *(const f32x4*)(q + 512); nr = *(const f32x4*)(q + 768); nkk = *(const f32x4*)(q + 1024);
;                 nv = *(const float*)(vb + (u + 1) * STEPB); }
;             const f32x2 v2 = {vv, vv}, c2 = {c, c};
;             const f32x2 tA = __builtin_elementwise_fma(v2, (f32x2){kd4[0], kd4[1]}, __builtin_elementwise_fma(-sA, (f32x2){e4[0], e4[1]}, sA));
;             const f32x2 tB = __builtin_elementwise_fma(v2, (f32x2){kd4[2], kd4[3]}, __builtin_elementwise_fma(-sB, (f32x2){e4[2], e4[3]}, sB));
;             sA = __builtin_elementwise_fma(-c2, (f32x2){ka4[0], ka4[1]}, tA);
;             sB = __builtin_elementwise_fma(-c2, (f32x2){ka4[2], ka4[3]}, tB);
;             const f32x2 yv = __builtin_elementwise_fma(sB, (f32x2){r4[2], r4[3]}, sA * (f32x2){r4[0], r4[1]});
;             float y = yv[0] + yv[1];
;             if (u + 1 < SCH) {
;                 const f32x2 cv = __builtin_elementwise_fma(sB, (f32x2){nkk[2], nkk[3]}, sA * (f32x2){nkk[0], nkk[1]});
;                 float cn = cv[0] + cv[1];
;                 cn = DPP_ADD(cn, 0xB1);  y = DPP_ADD(y, 0xB1);
;                 cn = DPP_ADD(cn, 0x4E);  y = DPP_ADD(y, 0x4E);
;                 cn = DPP_ADD(cn, 0x141); y = DPP_ADD(y, 0x141);
;                 cn = DPP_ADD(cn, 0x140); y = DPP_ADD(y, 0x140);
;                 c = cn;
;             } else y = red16(y);
;             if (ks == 0) yl[u * 16] = y;
;             e4 = ne; kd4 = nkd; ka4 = nka; r4 = nr; kk4 = nkk; vv = nv;
;         }
	v_pk_mul_f32 v[94:95], v[20:21], v[94:95]
	v_pk_mul_f32 v[28:29], v[20:21], v[28:29]
	v_pk_fma_f32 v[94:95], v[22:23], v[96:97], v[94:95]
	v_pk_fma_f32 v[28:29], v[22:23], v[30:31], v[28:29]
	v_add_f32_e32 v96, v94, v95
	v_add_f32_e32 v30, v28, v29
	v_pk_fma_f32 v[40:41], v[20:21], v[40:41], v[20:21] neg_lo:[1,0,0] neg_hi:[1,0,0]
	v_add_f32_dpp v97, v96, v96 quad_perm:[1,0,3,2] row_mask:0xf bank_mask:0xf bound_ctrl:1
	v_add_f32_dpp v31, v30, v30 quad_perm:[1,0,3,2] row_mask:0xf bank_mask:0xf bound_ctrl:1
	v_pk_fma_f32 v[42:43], v[22:23], v[42:43], v[22:23] neg_lo:[1,0,0] neg_hi:[1,0,0]
	v_add_f32_dpp v96, v97, v97 quad_perm:[2,3,0,1] row_mask:0xf bank_mask:0xf bound_ctrl:1
	v_add_f32_dpp v30, v31, v31 quad_perm:[2,3,0,1] row_mask:0xf bank_mask:0xf bound_ctrl:1
	v_pk_fma_f32 v[40:41], v[38:39], v[44:45], v[40:41] op_sel_hi:[0,1,1]
	v_add_f32_dpp v97, v96, v96 row_half_mirror row_mask:0xf bank_mask:0xf bound_ctrl:1
	v_add_f32_dpp v31, v30, v30 row_half_mirror row_mask:0xf bank_mask:0xf bound_ctrl:1
	v_pk_fma_f32 v[42:43], v[38:39], v[46:47], v[42:43] op_sel_hi:[0,1,1]
	v_add_f32_dpp v90, v97, v97 row_mirror row_mask:0xf bank_mask:0xf bound_ctrl:1
	v_add_f32_dpp v30, v31, v31 row_mirror row_mask:0xf bank_mask:0xf bound_ctrl:1
	ds_write_b32 v37, v30 offset:43136
	ds_read_b128 v[28:31], v91 offset:6144
	v_pk_fma_f32 v[20:21], v[90:91], v[60:61], v[40:41] op_sel_hi:[0,1,1] neg_lo:[1,0,0] neg_hi:[1,0,0]
	v_pk_fma_f32 v[22:23], v[90:91], v[62:63], v[42:43] op_sel_hi:[0,1,1] neg_lo:[1,0,0] neg_hi:[1,0,0]
	ds_read_b128 v[40:43], v91 offset:6720
	ds_read_b128 v[60:63], v91 offset:7232
	ds_read_b128 v[44:47], v91 offset:6976
	ds_read_b128 v[94:97], v91 offset:7744
	ds_read_b32 v38, v92 offset:8000
	s_waitcnt lgkmcnt(7)
	v_pk_mul_f32 v[32:33], v[20:21], v[32:33]
	v_pk_mul_f32 v[64:65], v[20:21], v[64:65]
	v_pk_fma_f32 v[32:33], v[22:23], v[34:35], v[32:33]
	v_pk_fma_f32 v[64:65], v[22:23], v[66:67], v[64:65]
	v_add_f32_e32 v34, v32, v33
	v_add_f32_e32 v66, v64, v65
	v_pk_fma_f32 v[12:13], v[20:21], v[12:13], v[20:21] neg_lo:[1,0,0] neg_hi:[1,0,0]
	v_add_f32_dpp v35, v34, v34 quad_perm:[1,0,3,2] row_mask:0xf bank_mask:0xf bound_ctrl:1
	v_add_f32_dpp v67, v66, v66 quad_perm:[1,0,3,2] row_mask:0xf bank_mask:0xf bound_ctrl:1
	v_pk_fma_f32 v[14:15], v[22:23], v[14:15], v[22:23] neg_lo:[1,0,0] neg_hi:[1,0,0]
	v_add_f32_dpp v34, v35, v35 quad_perm:[2,3,0,1] row_mask:0xf bank_mask:0xf bound_ctrl:1
	v_add_f32_dpp v66, v67, v67 quad_perm:[2,3,0,1] row_mask:0xf bank_mask:0xf bound_ctrl:1
	v_pk_fma_f32 v[12:13], v[36:37], v[16:17], v[12:13] op_sel_hi:[0,1,1]
	v_add_f32_dpp v35, v34, v34 row_half_mirror row_mask:0xf bank_mask:0xf bound_ctrl:1
	v_add_f32_dpp v67, v66, v66 row_half_mirror row_mask:0xf bank_mask:0xf bound_ctrl:1
	v_pk_fma_f32 v[14:15], v[36:37], v[18:19], v[14:15] op_sel_hi:[0,1,1]
	v_add_f32_dpp v90, v35, v35 row_mirror row_mask:0xf bank_mask:0xf bound_ctrl:1
	v_add_f32_dpp v66, v67, v67 row_mirror row_mask:0xf bank_mask:0xf bound_ctrl:1
	ds_write_b32 v37, v66 offset:43200
	ds_read_b128 v[64:67], v91 offset:7488
	v_pk_fma_f32 v[20:21], v[90:91], v[24:25], v[12:13] op_sel_hi:[0,1,1] neg_lo:[1,0,0] neg_hi:[1,0,0]
	v_pk_fma_f32 v[22:23], v[90:91], v[26:27], v[14:15] op_sel_hi:[0,1,1] neg_lo:[1,0,0] neg_hi:[1,0,0]
	ds_read_b128 v[12:15], v91 offset:8064
	ds_read_b128 v[24:27], v91 offset:8576
	ds_read_b128 v[16:19], v91 offset:8320
	ds_read_b128 v[32:35], v91 offset:9088
	ds_read_b32 v36, v92 offset:9344
	s_waitcnt lgkmcnt(7)
	v_pk_mul_f32 v[94:95], v[20:21], v[94:95]
	v_pk_mul_f32 v[28:29], v[20:21], v[28:29]
	v_pk_fma_f32 v[94:95], v[22:23], v[96:97], v[94:95]
	v_pk_fma_f32 v[28:29], v[22:23], v[30:31], v[28:29]
	v_add_f32_e32 v96, v94, v95
	v_add_f32_e32 v30, v28, v29
	v_pk_fma_f32 v[40:41], v[20:21], v[40:41], v[20:21] neg_lo:[1,0,0] neg_hi:[1,0,0]
	v_add_f32_dpp v97, v96, v96 quad_perm:[1,0,3,2] row_mask:0xf bank_mask:0xf bound_ctrl:1
	v_add_f32_dpp v31, v30, v30 quad_perm:[1,0,3,2] row_mask:0xf bank_mask:0xf bound_ctrl:1
	v_pk_fma_f32 v[42:43], v[22:23], v[42:43], v[22:23] neg_lo:[1,0,0] neg_hi:[1,0,0]
	v_add_f32_dpp v96, v97, v97 quad_perm:[2,3,0,1] row_mask:0xf bank_mask:0xf bound_ctrl:1
	v_add_f32_dpp v30, v31, v31 quad_perm:[2,3,0,1] row_mask:0xf bank_mask:0xf bound_ctrl:1
	v_pk_fma_f32 v[40:41], v[38:39], v[44:45], v[40:41] op_sel_hi:[0,1,1]
	v_add_f32_dpp v97, v96, v96 row_half_mirror row_mask:0xf bank_mask:0xf bound_ctrl:1
	v_add_f32_dpp v31, v30, v30 row_half_mirror row_mask:0xf bank_mask:0xf bound_ctrl:1
	v_pk_fma_f32 v[42:43], v[38:39], v[46:47], v[42:43] op_sel_hi:[0,1,1]
	v_add_f32_dpp v90, v97, v97 row_mirror row_mask:0xf bank_mask:0xf bound_ctrl:1
	v_add_f32_dpp v30, v31, v31 row_mirror row_mask:0xf bank_mask:0xf bound_ctrl:1
	ds_write_b32 v37, v30 offset:43264
	ds_read_b128 v[28:31], v91 offset:8832
	v_pk_fma_f32 v[20:21], v[90:91], v[60:61], v[40:41] op_sel_hi:[0,1,1] neg_lo:[1,0,0] neg_hi:[1,0,0]
	v_pk_fma_f32 v[22:23], v[90:91], v[62:63], v[42:43] op_sel_hi:[0,1,1] neg_lo:[1,0,0] neg_hi:[1,0,0]
	ds_read_b128 v[40:43], v91 offset:9408
	ds_read_b128 v[60:63], v91 offset:9920
	ds_read_b128 v[44:47], v91 offset:9664
	ds_read_b128 v[94:97], v91 offset:10432
	ds_read_b32 v38, v92 offset:10688
	s_waitcnt lgkmcnt(7)
; #define DPP_ADD(v, ctrl) ((v) + __builtin_bit_cast(float, __builtin_amdgcn_update_dpp(0, __builtin_bit_cast(int, (v)), (ctrl), 0xf, 0xf, true)))
; __device__ __forceinline__ void rwkv_scan_unit(const Params& p, int unit, char* smem) {
;     ...
;         for (int u = 0; u < SCH; ++u) {
;             f32x4 ne = e4, nkd = kd4, nka = ka4, nr = r4, nkk = kk4; float nv = vv;
;             if (u + 1 < SCH) { const char* q = lb + (u + 1) * STEPB;
;                 ne = *(const f32x4*)(q); nkd = *(const f32x4*)(q + 256); nka = *(const f32x4*)(q + 512); nr = *(const f32x4*)(q + 768); nkk = *(const f32x4*)(q + 1024);
;                 nv = *(const float*)(vb + (u + 1) * STEPB); }
;             const f32x2 v2 = {vv, vv}, c2 = {c, c};
;             const f32x2 tA = __builtin_elementwise_fma(v2, (f32x2){kd4[0], kd4[1]}, __builtin_elementwise_fma(-sA, (f32x2){e4[0], e4[1]}, sA));
;             const f32x2 tB = __builtin_elementwise_fma(v2, (f32x2){kd4[2], kd4[3]}, __builtin_elementwise_fma(-sB, (f32x2){e4[2], e4[3]}, sB));
;             sA = __builtin_elementwise_fma(-c2, (f32x2){ka4[0], ka4[1]}, tA);
;             sB = __builtin_elementwise_fma(-c2, (f32x2){ka4[2], ka4[3]}, tB);
;             const f32x2 yv = __builtin_elementwise_fma(sB, (f32x2){r4[2], r4[3]}, sA * (f32x2){r4[0], r4[1]});
;             float y = yv[0] + yv[1];
;             if (u + 1 < SCH) {
;                 const f32x2 cv = __builtin_elementwise_fma(sB, (f32x2){nkk[2], nkk[3]}, sA * (f32x2){nkk[0], nkk[1]});
;                 float cn = cv[0] + cv[1];
;                 cn = DPP_ADD(cn, 0xB1);  y = DPP_ADD(y, 0xB1);
;                 cn = DPP_ADD(cn, 0x4E);  y = DPP_ADD(y, 0x4E);
;                 cn = DPP_ADD(cn, 0x141); y = DPP_ADD(y, 0x141);
;                 cn = DPP_ADD(cn, 0x140); y = DPP_ADD(y, 0x140);
;                 c = cn;
;             } else y = red16(y);
;             if (ks == 0) yl[u * 16] = y;
;             e4 = ne; kd4 = nkd; ka4 = nka; r4 = nr; kk4 = nkk; vv = nv;
;         }
	v_pk_mul_f32 v[32:33], v[20:21], v[32:33]
	v_pk_mul_f32 v[64:65], v[20:21], v[64:65]
	v_pk_fma_f32 v[32:33], v[22:23], v[34:35], v[32:33]
	v_pk_fma_f32 v[64:65], v[22:23], v[66:67], v[64:65]
	v_add_f32_e32 v34, v32, v33
	v_add_f32_e32 v66, v64, v65
	v_pk_fma_f32 v[12:13], v[20:21], v[12:13], v[20:21] neg_lo:[1,0,0] neg_hi:[1,0,0]
	v_add_f32_dpp v35, v34, v34 quad_perm:[1,0,3,2] row_mask:0xf bank_mask:0xf bound_ctrl:1
	v_add_f32_dpp v67, v66, v66 quad_perm:[1,0,3,2] row_mask:0xf bank_mask:0xf bound_ctrl:1
	v_pk_fma_f32 v[14:15], v[22:23], v[14:15], v[22:23] neg_lo:[1,0,0] neg_hi:[1,0,0]
	v_add_f32_dpp v34, v35, v35 quad_perm:[2,3,0,1] row_mask:0xf bank_mask:0xf bound_ctrl:1
	v_add_f32_dpp v66, v67, v67 quad_perm:[2,3,0,1] row_mask:0xf bank_mask:0xf bound_ctrl:1
	v_pk_fma_f32 v[12:13], v[36:37], v[16:17], v[12:13] op_sel_hi:[0,1,1]
	v_add_f32_dpp v35, v34, v34 row_half_mirror row_mask:0xf bank_mask:0xf bound_ctrl:1
	v_add_f32_dpp v67, v66, v66 row_half_mirror row_mask:0xf bank_mask:0xf bound_ctrl:1
	v_pk_fma_f32 v[14:15], v[36:37], v[18:19], v[14:15] op_sel_hi:[0,1,1]
	v_add_f32_dpp v90, v35, v35 row_mirror row_mask:0xf bank_mask:0xf bound_ctrl:1
	v_add_f32_dpp v66, v67, v67 row_mirror row_mask:0xf bank_mask:0xf bound_ctrl:1
	ds_write_b32 v37, v66 offset:43328
	ds_read_b128 v[64:67], v91 offset:10176
	v_pk_fma_f32 v[20:21], v[90:91], v[24:25], v[12:13] op_sel_hi:[0,1,1] neg_lo:[1,0,0] neg_hi:[1,0,0]
	v_pk_fma_f32 v[22:23], v[90:91], v[26:27], v[14:15] op_sel_hi:[0,1,1] neg_lo:[1,0,0] neg_hi:[1,0,0]
	ds_read_b128 v[12:15], v91 offset:10752
	ds_read_b128 v[24:27], v91 offset:11264
	ds_read_b128 v[16:19], v91 offset:11008
	ds_read_b128 v[32:35], v91 offset:11776
	ds_read_b32 v36, v92 offset:12032
	s_waitcnt lgkmcnt(7)
	v_pk_mul_f32 v[94:95], v[20:21], v[94:95]
	v_pk_mul_f32 v[28:29], v[20:21], v[28:29]
	v_pk_fma_f32 v[94:95], v[22:23], v[96:97], v[94:95]
	v_pk_fma_f32 v[28:29], v[22:23], v[30:31], v[28:29]
	v_add_f32_e32 v96, v94, v95
	v_add_f32_e32 v30, v28, v29
	v_pk_fma_f32 v[40:41], v[20:21], v[40:41], v[20:21] neg_lo:[1,0,0] neg_hi:[1,0,0]
	v_add_f32_dpp v97, v96, v96 quad_perm:[1,0,3,2] row_mask:0xf bank_mask:0xf bound_ctrl:1
	v_add_f32_dpp v31, v30, v30 quad_perm:[1,0,3,2] row_mask:0xf bank_mask:0xf bound_ctrl:1
	v_pk_fma_f32 v[42:43], v[22:23], v[42:43], v[22:23] neg_lo:[1,0,0] neg_hi:[1,0,0]
	v_add_f32_dpp v96, v97, v97 quad_perm:[2,3,0,1] row_mask:0xf bank_mask:0xf bound_ctrl:1
	v_add_f32_dpp v30, v31, v31 quad_perm:[2,3,0,1] row_mask:0xf bank_mask:0xf bound_ctrl:1
	v_pk_fma_f32 v[40:41], v[38:39], v[44:45], v[40:41] op_sel_hi:[0,1,1]
	v_add_f32_dpp v97, v96, v96 row_half_mirror row_mask:0xf bank_mask:0xf bound_ctrl:1
	v_add_f32_dpp v31, v30, v30 row_half_mirror row_mask:0xf bank_mask:0xf bound_ctrl:1
	v_pk_fma_f32 v[42:43], v[38:39], v[46:47], v[42:43] op_sel_hi:[0,1,1]
	v_add_f32_dpp v90, v97, v97 row_mirror row_mask:0xf bank_mask:0xf bound_ctrl:1
	v_add_f32_dpp v30, v31, v31 row_mirror row_mask:0xf bank_mask:0xf bound_ctrl:1
	ds_write_b32 v37, v30 offset:43392
	ds_read_b128 v[28:31], v91 offset:11520
	v_pk_fma_f32 v[20:21], v[90:91], v[60:61], v[40:41] op_sel_hi:[0,1,1] neg_lo:[1,0,0] neg_hi:[1,0,0]
	v_pk_fma_f32 v[22:23], v[90:91], v[62:63], v[42:43] op_sel_hi:[0,1,1] neg_lo:[1,0,0] neg_hi:[1,0,0]
	ds_read_b128 v[40:43], v91 offset:12096
	ds_read_b128 v[60:63], v91 offset:12608
	ds_read_b128 v[44:47], v91 offset:12352
	ds_read_b128 v[94:97], v91 offset:13120
	ds_read_b32 v38, v92 offset:13376
	s_waitcnt lgkmcnt(7)
	v_pk_mul_f32 v[32:33], v[20:21], v[32:33]
	v_pk_mul_f32 v[64:65], v[20:21], v[64:65]
	v_pk_fma_f32 v[32:33], v[22:23], v[34:35], v[32:33]
	v_pk_fma_f32 v[64:65], v[22:23], v[66:67], v[64:65]
	v_add_f32_e32 v34, v32, v33
	v_add_f32_e32 v66, v64, v65
	v_pk_fma_f32 v[12:13], v[20:21], v[12:13], v[20:21] neg_lo:[1,0,0] neg_hi:[1,0,0]
	v_add_f32_dpp v35, v34, v34 quad_perm:[1,0,3,2] row_mask:0xf bank_mask:0xf bound_ctrl:1
	v_add_f32_dpp v67, v66, v66 quad_perm:[1,0,3,2] row_mask:0xf bank_mask:0xf bound_ctrl:1
	v_pk_fma_f32 v[14:15], v[22:23], v[14:15], v[22:23] neg_lo:[1,0,0] neg_hi:[1,0,0]
	v_add_f32_dpp v34, v35, v35 quad_perm:[2,3,0,1] row_mask:0xf bank_mask:0xf bound_ctrl:1
	v_add_f32_dpp v66, v67, v67 quad_perm:[2,3,0,1] row_mask:0xf bank_mask:0xf bound_ctrl:1
	v_pk_fma_f32 v[12:13], v[36:37], v[16:17], v[12:13] op_sel_hi:[0,1,1]
	v_add_f32_dpp v35, v34, v34 row_half_mirror row_mask:0xf bank_mask:0xf bound_ctrl:1
	v_add_f32_dpp v67, v66, v66 row_half_mirror row_mask:0xf bank_mask:0xf bound_ctrl:1
	v_pk_fma_f32 v[14:15], v[36:37], v[18:19], v[14:15] op_sel_hi:[0,1,1]
	v_add_f32_dpp v90, v35, v35 row_mirror row_mask:0xf bank_mask:0xf bound_ctrl:1
	v_add_f32_dpp v66, v67, v67 row_mirror row_mask:0xf bank_mask:0xf bound_ctrl:1
	ds_write_b32 v37, v66 offset:43456
	ds_read_b128 v[64:67], v91 offset:12864
	v_pk_fma_f32 v[20:21], v[90:91], v[24:25], v[12:13] op_sel_hi:[0,1,1] neg_lo:[1,0,0] neg_hi:[1,0,0]
	v_pk_fma_f32 v[22:23], v[90:91], v[26:27], v[14:15] op_sel_hi:[0,1,1] neg_lo:[1,0,0] neg_hi:[1,0,0]
	ds_read_b128 v[12:15], v91 offset:13440
	ds_read_b128 v[24:27], v91 offset:13952
	ds_read_b128 v[16:19], v91 offset:13696
	ds_read_b128 v[32:35], v91 offset:14464
	ds_read_b32 v36, v92 offset:14720
	s_waitcnt lgkmcnt(7)
; #define DPP_ADD(v, ctrl) ((v) + __builtin_bit_cast(float, __builtin_amdgcn_update_dpp(0, __builtin_bit_cast(int, (v)), (ctrl), 0xf, 0xf, true)))
; __device__ __forceinline__ void rwkv_scan_unit(const Params& p, int unit, char* smem) {
;     ...
;         for (int u = 0; u < SCH; ++u) {
;             f32x4 ne = e4, nkd = kd4, nka = ka4, nr = r4, nkk = kk4; float nv = vv;
;             if (u + 1 < SCH) { const char* q = lb + (u + 1) * STEPB;
;                 ne = *(const f32x4*)(q); nkd = *(const f32x4*)(q + 256); nka = *(const f32x4*)(q + 512); nr = *(const f32x4*)(q + 768); nkk = *(const f32x4*)(q + 1024);
;                 nv = *(const float*)(vb + (u + 1) * STEPB); }
;             const f32x2 v2 = {vv, vv}, c2 = {c, c};
;             const f32x2 tA = __builtin_elementwise_fma(v2, (f32x2){kd4[0], kd4[1]}, __builtin_elementwise_fma(-sA, (f32x2){e4[0], e4[1]}, sA));
;             const f32x2 tB = __builtin_elementwise_fma(v2, (f32x2){kd4[2], kd4[3]}, __builtin_elementwise_fma(-sB, (f32x2){e4[2], e4[3]}, sB));
;             sA = __builtin_elementwise_fma(-c2, (f32x2){ka4[0], ka4[1]}, tA);
;             sB = __builtin_elementwise_fma(-c2, (f32x2){ka4[2], ka4[3]}, tB);
;             const f32x2 yv = __builtin_elementwise_fma(sB, (f32x2){r4[2], r4[3]}, sA * (f32x2){r4[0], r4[1]});
;             float y = yv[0] + yv[1];
;             if (u + 1 < SCH) {
;                 const f32x2 cv = __builtin_elementwise_fma(sB, (f32x2){nkk[2], nkk[3]}, sA * (f32x2){nkk[0], nkk[1]});
;                 float cn = cv[0] + cv[1];
;                 cn = DPP_ADD(cn, 0xB1);  y = DPP_ADD(y, 0xB1);
;                 cn = DPP_ADD(cn, 0x4E);  y = DPP_ADD(y, 0x4E);
;                 cn = DPP_ADD(cn, 0x141); y = DPP_ADD(y, 0x141);
;                 cn = DPP_ADD(cn, 0x140); y = DPP_ADD(y, 0x140);
;                 c = cn;
;             } else y = red16(y);
;             if (ks == 0) yl[u * 16] = y;
;             e4 = ne; kd4 = nkd; ka4 = nka; r4 = nr; kk4 = nkk; vv = nv;
;         }
	v_pk_mul_f32 v[94:95], v[20:21], v[94:95]
	v_pk_mul_f32 v[28:29], v[20:21], v[28:29]
	v_pk_fma_f32 v[94:95], v[22:23], v[96:97], v[94:95]
	v_pk_fma_f32 v[28:29], v[22:23], v[30:31], v[28:29]
	v_add_f32_e32 v96, v94, v95
	v_add_f32_e32 v30, v28, v29
	v_pk_fma_f32 v[40:41], v[20:21], v[40:41], v[20:21] neg_lo:[1,0,0] neg_hi:[1,0,0]
	v_add_f32_dpp v97, v96, v96 quad_perm:[1,0,3,2] row_mask:0xf bank_mask:0xf bound_ctrl:1
	v_add_f32_dpp v31, v30, v30 quad_perm:[1,0,3,2] row_mask:0xf bank_mask:0xf bound_ctrl:1
	v_pk_fma_f32 v[42:43], v[22:23], v[42:43], v[22:23] neg_lo:[1,0,0] neg_hi:[1,0,0]
	v_add_f32_dpp v96, v97, v97 quad_perm:[2,3,0,1] row_mask:0xf bank_mask:0xf bound_ctrl:1
	v_add_f32_dpp v30, v31, v31 quad_perm:[2,3,0,1] row_mask:0xf bank_mask:0xf bound_ctrl:1
	v_pk_fma_f32 v[40:41], v[38:39], v[44:45], v[40:41] op_sel_hi:[0,1,1]
	v_add_f32_dpp v97, v96, v96 row_half_mirror row_mask:0xf bank_mask:0xf bound_ctrl:1
	v_add_f32_dpp v31, v30, v30 row_half_mirror row_mask:0xf bank_mask:0xf bound_ctrl:1
	v_pk_fma_f32 v[42:43], v[38:39], v[46:47], v[42:43] op_sel_hi:[0,1,1]
	v_add_f32_dpp v90, v97, v97 row_mirror row_mask:0xf bank_mask:0xf bound_ctrl:1
	v_add_f32_dpp v30, v31, v31 row_mirror row_mask:0xf bank_mask:0xf bound_ctrl:1
	ds_write_b32 v37, v30 offset:43520
	ds_read_b128 v[28:31], v91 offset:14208
	v_pk_fma_f32 v[20:21], v[90:91], v[60:61], v[40:41] op_sel_hi:[0,1,1] neg_lo:[1,0,0] neg_hi:[1,0,0]
	v_pk_fma_f32 v[22:23], v[90:91], v[62:63], v[42:43] op_sel_hi:[0,1,1] neg_lo:[1,0,0] neg_hi:[1,0,0]
	ds_read_b128 v[40:43], v91 offset:14784
	ds_read_b128 v[60:63], v91 offset:15296
	ds_read_b128 v[44:47], v91 offset:15040
	ds_read_b128 v[94:97], v91 offset:15808
	ds_read_b32 v38, v92 offset:16064
	s_waitcnt lgkmcnt(7)
	v_pk_mul_f32 v[32:33], v[20:21], v[32:33]
	v_pk_mul_f32 v[64:65], v[20:21], v[64:65]
	v_pk_fma_f32 v[32:33], v[22:23], v[34:35], v[32:33]
	v_pk_fma_f32 v[64:65], v[22:23], v[66:67], v[64:65]
	v_add_f32_e32 v34, v32, v33
	v_add_f32_e32 v66, v64, v65
	v_pk_fma_f32 v[12:13], v[20:21], v[12:13], v[20:21] neg_lo:[1,0,0] neg_hi:[1,0,0]
	v_add_f32_dpp v35, v34, v34 quad_perm:[1,0,3,2] row_mask:0xf bank_mask:0xf bound_ctrl:1
	v_add_f32_dpp v67, v66, v66 quad_perm:[1,0,3,2] row_mask:0xf bank_mask:0xf bound_ctrl:1
	v_pk_fma_f32 v[14:15], v[22:23], v[14:15], v[22:23] neg_lo:[1,0,0] neg_hi:[1,0,0]
	v_add_f32_dpp v34, v35, v35 quad_perm:[2,3,0,1] row_mask:0xf bank_mask:0xf bound_ctrl:1
	v_add_f32_dpp v66, v67, v67 quad_perm:[2,3,0,1] row_mask:0xf bank_mask:0xf bound_ctrl:1
	v_pk_fma_f32 v[12:13], v[36:37], v[16:17], v[12:13] op_sel_hi:[0,1,1]
	v_add_f32_dpp v35, v34, v34 row_half_mirror row_mask:0xf bank_mask:0xf bound_ctrl:1
	v_add_f32_dpp v67, v66, v66 row_half_mirror row_mask:0xf bank_mask:0xf bound_ctrl:1
	v_pk_fma_f32 v[14:15], v[36:37], v[18:19], v[14:15] op_sel_hi:[0,1,1]
	v_add_f32_dpp v90, v35, v35 row_mirror row_mask:0xf bank_mask:0xf bound_ctrl:1
	v_add_f32_dpp v66, v67, v67 row_mirror row_mask:0xf bank_mask:0xf bound_ctrl:1
	ds_write_b32 v37, v66 offset:43584
	ds_read_b128 v[64:67], v91 offset:15552
	v_pk_fma_f32 v[20:21], v[90:91], v[24:25], v[12:13] op_sel_hi:[0,1,1] neg_lo:[1,0,0] neg_hi:[1,0,0]
	v_pk_fma_f32 v[22:23], v[90:91], v[26:27], v[14:15] op_sel_hi:[0,1,1] neg_lo:[1,0,0] neg_hi:[1,0,0]
	ds_read_b128 v[12:15], v91 offset:16128
	ds_read_b128 v[24:27], v91 offset:16640
	ds_read_b128 v[16:19], v91 offset:16384
	ds_read_b128 v[32:35], v91 offset:17152
	ds_read_b32 v36, v92 offset:17408
	s_waitcnt lgkmcnt(7)
	v_pk_mul_f32 v[94:95], v[20:21], v[94:95]
	v_pk_mul_f32 v[28:29], v[20:21], v[28:29]
	v_pk_fma_f32 v[94:95], v[22:23], v[96:97], v[94:95]
	v_pk_fma_f32 v[28:29], v[22:23], v[30:31], v[28:29]
	v_add_f32_e32 v96, v94, v95
	v_add_f32_e32 v30, v28, v29
	v_pk_fma_f32 v[40:41], v[20:21], v[40:41], v[20:21] neg_lo:[1,0,0] neg_hi:[1,0,0]
	v_add_f32_dpp v97, v96, v96 quad_perm:[1,0,3,2] row_mask:0xf bank_mask:0xf bound_ctrl:1
	v_add_f32_dpp v31, v30, v30 quad_perm:[1,0,3,2] row_mask:0xf bank_mask:0xf bound_ctrl:1
	v_pk_fma_f32 v[42:43], v[22:23], v[42:43], v[22:23] neg_lo:[1,0,0] neg_hi:[1,0,0]
	v_add_f32_dpp v96, v97, v97 quad_perm:[2,3,0,1] row_mask:0xf bank_mask:0xf bound_ctrl:1
	v_add_f32_dpp v30, v31, v31 quad_perm:[2,3,0,1] row_mask:0xf bank_mask:0xf bound_ctrl:1
	v_pk_fma_f32 v[40:41], v[38:39], v[44:45], v[40:41] op_sel_hi:[0,1,1]
	v_add_f32_dpp v97, v96, v96 row_half_mirror row_mask:0xf bank_mask:0xf bound_ctrl:1
	v_add_f32_dpp v31, v30, v30 row_half_mirror row_mask:0xf bank_mask:0xf bound_ctrl:1
	v_pk_fma_f32 v[42:43], v[38:39], v[46:47], v[42:43] op_sel_hi:[0,1,1]
	v_add_f32_dpp v90, v97, v97 row_mirror row_mask:0xf bank_mask:0xf bound_ctrl:1
	v_add_f32_dpp v30, v31, v31 row_mirror row_mask:0xf bank_mask:0xf bound_ctrl:1
	ds_write_b32 v37, v30 offset:43648
	ds_read_b128 v[28:31], v91 offset:16896
	v_pk_fma_f32 v[20:21], v[90:91], v[60:61], v[40:41] op_sel_hi:[0,1,1] neg_lo:[1,0,0] neg_hi:[1,0,0]
	v_pk_fma_f32 v[22:23], v[90:91], v[62:63], v[42:43] op_sel_hi:[0,1,1] neg_lo:[1,0,0] neg_hi:[1,0,0]
	ds_read_b128 v[40:43], v91 offset:17472
	ds_read_b128 v[60:63], v91 offset:17984
	ds_read_b128 v[44:47], v91 offset:17728
	ds_read_b128 v[94:97], v91 offset:18496
	ds_read_b32 v38, v92 offset:18752
	s_waitcnt lgkmcnt(7)
; #define DPP_ADD(v, ctrl) ((v) + __builtin_bit_cast(float, __builtin_amdgcn_update_dpp(0, __builtin_bit_cast(int, (v)), (ctrl), 0xf, 0xf, true)))
; __device__ __forceinline__ void rwkv_scan_unit(const Params& p, int unit, char* smem) {
;     ...
;         for (int u = 0; u < SCH; ++u) {
;             f32x4 ne = e4, nkd = kd4, nka = ka4, nr = r4, nkk = kk4; float nv = vv;
;             if (u + 1 < SCH) { const char* q = lb + (u + 1) * STEPB;
;                 ne = *(const f32x4*)(q); nkd = *(const f32x4*)(q + 256); nka = *(const f32x4*)(q + 512); nr = *(const f32x4*)(q + 768); nkk = *(const f32x4*)(q + 1024);
;                 nv = *(const float*)(vb + (u + 1) * STEPB); }
;             const f32x2 v2 = {vv, vv}, c2 = {c, c};
;             const f32x2 tA = __builtin_elementwise_fma(v2, (f32x2){kd4[0], kd4[1]}, __builtin_elementwise_fma(-sA, (f32x2){e4[0], e4[1]}, sA));
;             const f32x2 tB = __builtin_elementwise_fma(v2, (f32x2){kd4[2], kd4[3]}, __builtin_elementwise_fma(-sB, (f32x2){e4[2], e4[3]}, sB));
;             sA = __builtin_elementwise_fma(-c2, (f32x2){ka4[0], ka4[1]}, tA);
;             sB = __builtin_elementwise_fma(-c2, (f32x2){ka4[2], ka4[3]}, tB);
;             const f32x2 yv = __builtin_elementwise_fma(sB, (f32x2){r4[2], r4[3]}, sA * (f32x2){r4[0], r4[1]});
;             float y = yv[0] + yv[1];
;             if (u + 1 < SCH) {
;                 const f32x2 cv = __builtin_elementwise_fma(sB, (f32x2){nkk[2], nkk[3]}, sA * (f32x2){nkk[0], nkk[1]});
;                 float cn = cv[0] + cv[1];
;                 cn = DPP_ADD(cn, 0xB1);  y = DPP_ADD(y, 0xB1);
;                 cn = DPP_ADD(cn, 0x4E);  y = DPP_ADD(y, 0x4E);
;                 cn = DPP_ADD(cn, 0x141); y = DPP_ADD(y, 0x141);
;                 cn = DPP_ADD(cn, 0x140); y = DPP_ADD(y, 0x140);
;                 c = cn;
;             } else y = red16(y);
;             if (ks == 0) yl[u * 16] = y;
;             e4 = ne; kd4 = nkd; ka4 = nka; r4 = nr; kk4 = nkk; vv = nv;
;         }
	v_pk_mul_f32 v[32:33], v[20:21], v[32:33]
	v_pk_mul_f32 v[64:65], v[20:21], v[64:65]
	v_pk_fma_f32 v[32:33], v[22:23], v[34:35], v[32:33]
	v_pk_fma_f32 v[64:65], v[22:23], v[66:67], v[64:65]
	v_add_f32_e32 v34, v32, v33
	v_add_f32_e32 v66, v64, v65
	v_pk_fma_f32 v[12:13], v[20:21], v[12:13], v[20:21] neg_lo:[1,0,0] neg_hi:[1,0,0]
	v_add_f32_dpp v35, v34, v34 quad_perm:[1,0,3,2] row_mask:0xf bank_mask:0xf bound_ctrl:1
	v_add_f32_dpp v67, v66, v66 quad_perm:[1,0,3,2] row_mask:0xf bank_mask:0xf bound_ctrl:1
	v_pk_fma_f32 v[14:15], v[22:23], v[14:15], v[22:23] neg_lo:[1,0,0] neg_hi:[1,0,0]
	v_add_f32_dpp v34, v35, v35 quad_perm:[2,3,0,1] row_mask:0xf bank_mask:0xf bound_ctrl:1
	v_add_f32_dpp v66, v67, v67 quad_perm:[2,3,0,1] row_mask:0xf bank_mask:0xf bound_ctrl:1
	v_pk_fma_f32 v[12:13], v[36:37], v[16:17], v[12:13] op_sel_hi:[0,1,1]
	v_add_f32_dpp v35, v34, v34 row_half_mirror row_mask:0xf bank_mask:0xf bound_ctrl:1
	v_add_f32_dpp v67, v66, v66 row_half_mirror row_mask:0xf bank_mask:0xf bound_ctrl:1
	v_pk_fma_f32 v[14:15], v[36:37], v[18:19], v[14:15] op_sel_hi:[0,1,1]
	v_add_f32_dpp v90, v35, v35 row_mirror row_mask:0xf bank_mask:0xf bound_ctrl:1
	v_add_f32_dpp v66, v67, v67 row_mirror row_mask:0xf bank_mask:0xf bound_ctrl:1
	ds_write_b32 v37, v66 offset:43712
	ds_read_b128 v[64:67], v91 offset:18240
	v_pk_fma_f32 v[20:21], v[90:91], v[24:25], v[12:13] op_sel_hi:[0,1,1] neg_lo:[1,0,0] neg_hi:[1,0,0]
	v_pk_fma_f32 v[22:23], v[90:91], v[26:27], v[14:15] op_sel_hi:[0,1,1] neg_lo:[1,0,0] neg_hi:[1,0,0]
	ds_read_b128 v[12:15], v91 offset:18816
	ds_read_b128 v[24:27], v91 offset:19328
	ds_read_b128 v[16:19], v91 offset:19072
	ds_read_b128 v[32:35], v91 offset:19840
	ds_read_b32 v36, v92 offset:20096
	s_waitcnt lgkmcnt(7)
	v_pk_mul_f32 v[94:95], v[20:21], v[94:95]
	v_pk_mul_f32 v[28:29], v[20:21], v[28:29]
	v_pk_fma_f32 v[94:95], v[22:23], v[96:97], v[94:95]
	v_pk_fma_f32 v[28:29], v[22:23], v[30:31], v[28:29]
	v_add_f32_e32 v96, v94, v95
	v_add_f32_e32 v30, v28, v29
	v_pk_fma_f32 v[40:41], v[20:21], v[40:41], v[20:21] neg_lo:[1,0,0] neg_hi:[1,0,0]
	v_add_f32_dpp v97, v96, v96 quad_perm:[1,0,3,2] row_mask:0xf bank_mask:0xf bound_ctrl:1
	v_add_f32_dpp v31, v30, v30 quad_perm:[1,0,3,2] row_mask:0xf bank_mask:0xf bound_ctrl:1
	v_pk_fma_f32 v[42:43], v[22:23], v[42:43], v[22:23] neg_lo:[1,0,0] neg_hi:[1,0,0]
	v_add_f32_dpp v96, v97, v97 quad_perm:[2,3,0,1] row_mask:0xf bank_mask:0xf bound_ctrl:1
	v_add_f32_dpp v30, v31, v31 quad_perm:[2,3,0,1] row_mask:0xf bank_mask:0xf bound_ctrl:1
	v_pk_fma_f32 v[40:41], v[38:39], v[44:45], v[40:41] op_sel_hi:[0,1,1]
	v_add_f32_dpp v97, v96, v96 row_half_mirror row_mask:0xf bank_mask:0xf bound_ctrl:1
	v_add_f32_dpp v31, v30, v30 row_half_mirror row_mask:0xf bank_mask:0xf bound_ctrl:1
	v_pk_fma_f32 v[42:43], v[38:39], v[46:47], v[42:43] op_sel_hi:[0,1,1]
	v_add_f32_dpp v90, v97, v97 row_mirror row_mask:0xf bank_mask:0xf bound_ctrl:1
	v_add_f32_dpp v30, v31, v31 row_mirror row_mask:0xf bank_mask:0xf bound_ctrl:1
	ds_write_b32 v37, v30 offset:43776
	ds_read_b128 v[28:31], v91 offset:19584
	v_pk_fma_f32 v[20:21], v[90:91], v[60:61], v[40:41] op_sel_hi:[0,1,1] neg_lo:[1,0,0] neg_hi:[1,0,0]
	v_pk_fma_f32 v[22:23], v[90:91], v[62:63], v[42:43] op_sel_hi:[0,1,1] neg_lo:[1,0,0] neg_hi:[1,0,0]
	ds_read_b128 v[40:43], v91 offset:20160
	ds_read_b128 v[60:63], v91 offset:20672
	ds_read_b128 v[44:47], v91 offset:20416
	ds_read_b128 v[94:97], v91 offset:21184
	ds_read_b32 v38, v92 offset:21440
	s_waitcnt lgkmcnt(7)
	v_pk_mul_f32 v[32:33], v[20:21], v[32:33]
	v_pk_mul_f32 v[64:65], v[20:21], v[64:65]
	v_pk_fma_f32 v[32:33], v[22:23], v[34:35], v[32:33]
	v_pk_fma_f32 v[64:65], v[22:23], v[66:67], v[64:65]
	v_add_f32_e32 v34, v32, v33
	v_add_f32_e32 v66, v64, v65
	v_pk_fma_f32 v[12:13], v[20:21], v[12:13], v[20:21] neg_lo:[1,0,0] neg_hi:[1,0,0]
	v_add_f32_dpp v35, v34, v34 quad_perm:[1,0,3,2] row_mask:0xf bank_mask:0xf bound_ctrl:1
	v_add_f32_dpp v67, v66, v66 quad_perm:[1,0,3,2] row_mask:0xf bank_mask:0xf bound_ctrl:1
	v_pk_fma_f32 v[14:15], v[22:23], v[14:15], v[22:23] neg_lo:[1,0,0] neg_hi:[1,0,0]
	v_add_f32_dpp v34, v35, v35 quad_perm:[2,3,0,1] row_mask:0xf bank_mask:0xf bound_ctrl:1
	v_add_f32_dpp v66, v67, v67 quad_perm:[2,3,0,1] row_mask:0xf bank_mask:0xf bound_ctrl:1
	v_pk_fma_f32 v[12:13], v[36:37], v[16:17], v[12:13] op_sel_hi:[0,1,1]
	v_add_f32_dpp v35, v34, v34 row_half_mirror row_mask:0xf bank_mask:0xf bound_ctrl:1
	v_add_f32_dpp v67, v66, v66 row_half_mirror row_mask:0xf bank_mask:0xf bound_ctrl:1
	v_pk_fma_f32 v[14:15], v[36:37], v[18:19], v[14:15] op_sel_hi:[0,1,1]
	v_add_f32_dpp v90, v35, v35 row_mirror row_mask:0xf bank_mask:0xf bound_ctrl:1
	v_add_f32_dpp v66, v67, v67 row_mirror row_mask:0xf bank_mask:0xf bound_ctrl:1
	ds_write_b32 v37, v66 offset:43840
	ds_read_b128 v[64:67], v91 offset:20928
	v_pk_fma_f32 v[20:21], v[90:91], v[24:25], v[12:13] op_sel_hi:[0,1,1] neg_lo:[1,0,0] neg_hi:[1,0,0]
	v_pk_fma_f32 v[22:23], v[90:91], v[26:27], v[14:15] op_sel_hi:[0,1,1] neg_lo:[1,0,0] neg_hi:[1,0,0]
	s_waitcnt lgkmcnt(2)
; #define DPP_ADD(v, ctrl) ((v) + __builtin_bit_cast(float, __builtin_amdgcn_update_dpp(0, __builtin_bit_cast(int, (v)), (ctrl), 0xf, 0xf, true)))
; __device__ __forceinline__ void rwkv_scan_unit(const Params& p, int unit, char* smem) {
;     ...
;         for (int u = 0; u < SCH; ++u) {
;             f32x4 ne = e4, nkd = kd4, nka = ka4, nr = r4, nkk = kk4; float nv = vv;
;             if (u + 1 < SCH) { const char* q = lb + (u + 1) * STEPB;
;                 ne = *(const f32x4*)(q); nkd = *(const f32x4*)(q + 256); nka = *(const f32x4*)(q + 512); nr = *(const f32x4*)(q + 768); nkk = *(const f32x4*)(q + 1024);
;                 nv = *(const float*)(vb + (u + 1) * STEPB); }
;             const f32x2 v2 = {vv, vv}, c2 = {c, c};
;             const f32x2 tA = __builtin_elementwise_fma(v2, (f32x2){kd4[0], kd4[1]}, __builtin_elementwise_fma(-sA, (f32x2){e4[0], e4[1]}, sA));
;             const f32x2 tB = __builtin_elementwise_fma(v2, (f32x2){kd4[2], kd4[3]}, __builtin_elementwise_fma(-sB, (f32x2){e4[2], e4[3]}, sB));
;             sA = __builtin_elementwise_fma(-c2, (f32x2){ka4[0], ka4[1]}, tA);
;             sB = __builtin_elementwise_fma(-c2, (f32x2){ka4[2], ka4[3]}, tB);
;             const f32x2 yv = __builtin_elementwise_fma(sB, (f32x2){r4[2], r4[3]}, sA * (f32x2){r4[0], r4[1]});
;             float y = yv[0] + yv[1];
;             if (u + 1 < SCH) {
;                 const f32x2 cv = __builtin_elementwise_fma(sB, (f32x2){nkk[2], nkk[3]}, sA * (f32x2){nkk[0], nkk[1]});
;                 float cn = cv[0] + cv[1];
;                 cn = DPP_ADD(cn, 0xB1);  y = DPP_ADD(y, 0xB1);
;                 cn = DPP_ADD(cn, 0x4E);  y = DPP_ADD(y, 0x4E);
;                 cn = DPP_ADD(cn, 0x141); y = DPP_ADD(y, 0x141);
;                 cn = DPP_ADD(cn, 0x140); y = DPP_ADD(y, 0x140);
;                 c = cn;
;             } else y = red16(y);
;             if (ks == 0) yl[u * 16] = y;
;             e4 = ne; kd4 = nkd; ka4 = nka; r4 = nr; kk4 = nkk; vv = nv;
;         }
;         s0 = sA[0]; s1 = sA[1]; s2 = sB[0]; s3 = sB[1];
;         __builtin_amdgcn_sched_barrier(0);
;         if (ci + 1 < NCH) { SC_LSTORE(((ci + 1) & 1) * STG) }
;         __syncthreads();
;         {
;             const int u = tid >> 4, r = tid & 15;
;             Yb[((size_t)b * TT + step_tok(ci * SCH + u, d)) * 1024 + r] = f2bf(*((const float*)(smem + YOFF + (ci & 1) * 1024) + u * 16 + r));
	v_pk_mul_f32 v[94:95], v[20:21], v[94:95]
	v_pk_mul_f32 v[28:29], v[20:21], v[28:29]
	v_pk_fma_f32 v[94:95], v[22:23], v[96:97], v[94:95]
	v_pk_fma_f32 v[28:29], v[22:23], v[30:31], v[28:29]
	v_add_f32_e32 v96, v94, v95
	v_add_f32_e32 v30, v28, v29
	v_pk_fma_f32 v[40:41], v[20:21], v[40:41], v[20:21] neg_lo:[1,0,0] neg_hi:[1,0,0]
	v_add_f32_dpp v97, v96, v96 quad_perm:[1,0,3,2] row_mask:0xf bank_mask:0xf bound_ctrl:1
	v_add_f32_dpp v31, v30, v30 quad_perm:[1,0,3,2] row_mask:0xf bank_mask:0xf bound_ctrl:1
	v_pk_fma_f32 v[42:43], v[22:23], v[42:43], v[22:23] neg_lo:[1,0,0] neg_hi:[1,0,0]
	v_add_f32_dpp v96, v97, v97 quad_perm:[2,3,0,1] row_mask:0xf bank_mask:0xf bound_ctrl:1
	v_add_f32_dpp v30, v31, v31 quad_perm:[2,3,0,1] row_mask:0xf bank_mask:0xf bound_ctrl:1
	v_pk_fma_f32 v[40:41], v[38:39], v[44:45], v[40:41] op_sel_hi:[0,1,1]
	v_add_f32_dpp v97, v96, v96 row_half_mirror row_mask:0xf bank_mask:0xf bound_ctrl:1
	v_add_f32_dpp v31, v30, v30 row_half_mirror row_mask:0xf bank_mask:0xf bound_ctrl:1
	v_pk_fma_f32 v[42:43], v[38:39], v[46:47], v[42:43] op_sel_hi:[0,1,1]
	v_add_f32_dpp v90, v97, v97 row_mirror row_mask:0xf bank_mask:0xf bound_ctrl:1
	v_add_f32_dpp v30, v31, v31 row_mirror row_mask:0xf bank_mask:0xf bound_ctrl:1
	ds_write_b32 v37, v30 offset:43904
	v_pk_fma_f32 v[20:21], v[90:91], v[60:61], v[40:41] op_sel_hi:[0,1,1] neg_lo:[1,0,0] neg_hi:[1,0,0]
	v_pk_fma_f32 v[22:23], v[90:91], v[62:63], v[42:43] op_sel_hi:[0,1,1] neg_lo:[1,0,0] neg_hi:[1,0,0]
	s_waitcnt lgkmcnt(1)
	v_pk_mul_f32 v[64:65], v[20:21], v[64:65]
	v_pk_fma_f32 v[64:65], v[22:23], v[66:67], v[64:65]
	s_nop 0
	v_add_f32_e32 v66, v64, v65
	s_nop 1
	v_add_f32_dpp v67, v66, v66 quad_perm:[1,0,3,2] row_mask:0xf bank_mask:0xf bound_ctrl:1
	s_nop 1
	v_add_f32_dpp v66, v67, v67 quad_perm:[2,3,0,1] row_mask:0xf bank_mask:0xf bound_ctrl:1
	s_nop 1
	v_add_f32_dpp v67, v66, v66 row_half_mirror row_mask:0xf bank_mask:0xf bound_ctrl:1
	s_nop 1
	v_add_f32_dpp v66, v67, v67 row_mirror row_mask:0xf bank_mask:0xf bound_ctrl:1
	ds_write_b32 v37, v66 offset:43968
	s_cmpk_eq_i32 s55, 0x10f0
	s_cbranch_scc1 .Lsc_p3_flush
	s_bitcmp1_b32 s64, 0
	s_cselect_b32 s0, 0x5400, 0
	s_waitcnt vmcnt(13)
	v_add3_u32 v16, s0, v74, v75
	v_cvt_f32_f16_sdwa v13, v160 dst_sel:DWORD dst_unused:UNUSED_PAD src0_sel:WORD_1
	v_cvt_f32_f16_e32 v12, v160
	v_cvt_f32_f16_sdwa v15, v161 dst_sel:DWORD dst_unused:UNUSED_PAD src0_sel:WORD_1
	v_cvt_f32_f16_e32 v14, v161
	ds_write_b128 v16, v[12:15]
	v_cvt_f32_f16_sdwa v13, v162 dst_sel:DWORD dst_unused:UNUSED_PAD src0_sel:WORD_1
	v_cvt_f32_f16_e32 v12, v162
	v_cvt_f32_f16_sdwa v15, v163 dst_sel:DWORD dst_unused:UNUSED_PAD src0_sel:WORD_1
	v_cvt_f32_f16_e32 v14, v163
	ds_write_b128 v16, v[12:15] offset:16
	v_add3_u32 v16, s0, v76, v77
	v_cvt_f32_f16_sdwa v13, v164 dst_sel:DWORD dst_unused:UNUSED_PAD src0_sel:WORD_1
	v_cvt_f32_f16_e32 v12, v164
	v_cvt_f32_f16_sdwa v15, v165 dst_sel:DWORD dst_unused:UNUSED_PAD src0_sel:WORD_1
	v_cvt_f32_f16_e32 v14, v165
	ds_write_b128 v16, v[12:15]
	v_cvt_f32_f16_sdwa v13, v166 dst_sel:DWORD dst_unused:UNUSED_PAD src0_sel:WORD_1
	v_cvt_f32_f16_e32 v12, v166
	v_cvt_f32_f16_sdwa v15, v167 dst_sel:DWORD dst_unused:UNUSED_PAD src0_sel:WORD_1
	v_cvt_f32_f16_e32 v14, v167
	ds_write_b128 v16, v[12:15] offset:16
	v_add3_u32 v16, s0, v78, v79
	v_cvt_f32_f16_sdwa v13, v168 dst_sel:DWORD dst_unused:UNUSED_PAD src0_sel:WORD_1
	v_cvt_f32_f16_e32 v12, v168
	v_cvt_f32_f16_sdwa v15, v169 dst_sel:DWORD dst_unused:UNUSED_PAD src0_sel:WORD_1
	v_cvt_f32_f16_e32 v14, v169
	ds_write_b128 v16, v[12:15]
	v_cvt_f32_f16_sdwa v13, v170 dst_sel:DWORD dst_unused:UNUSED_PAD src0_sel:WORD_1
	v_cvt_f32_f16_e32 v12, v170
	v_cvt_f32_f16_sdwa v15, v171 dst_sel:DWORD dst_unused:UNUSED_PAD src0_sel:WORD_1
	v_cvt_f32_f16_e32 v14, v171
	ds_write_b128 v16, v[12:15] offset:16
.Lsc_p3_flush:
	v_lshlrev_b32_e32 v246, 2, v73
	v_add3_u32 v246, s52, v89, v246
	s_waitcnt lgkmcnt(0)
	s_barrier
	ds_read_b32 v246, v246 offset:43008
	v_add_u32_e32 v245, s55, v71
	v_cmp_lt_i32_e32 vcc, s2, v245
	s_add_i32 s55, s55, 16
	v_cndmask_b32_e32 v244, v196, v197, vcc
	v_add_u32_e32 v244, v244, v82
	v_cndmask_b32_e64 v244, v244, v245, s[44:45]
	v_ashrrev_i32_e32 v245, 31, v244
	v_lshl_add_u64 v[244:245], v[244:245], 0, s[88:89]
	v_lshlrev_b64 v[244:245], 11, v[244:245]
	s_add_i32 s64, s64, 1
	v_lshl_add_u64 v[244:245], v[48:49], 0, v[244:245]
	v_add_u32_e32 v82, -16, v82
	s_mov_b32 s100, 1
	s_cmpk_lg_i32 s55, 0x1100
	s_cbranch_scc1 .Lsc_p0
	s_waitcnt lgkmcnt(0)
	v_bfe_u32 v247, v246, 16, 1
	s_movk_i32 s0, 0x7fff
	v_add3_u32 v247, v246, v247, s0
	global_store_short_d16_hi v[244:245], v247, off
	s_branch .LBB0_420
